# v32 + s_setprio 1 hoisted before the MFMA-segment opening s_barrier (one fewer issue slot between barrier release and first MFMA); bit-identical
# speedup vs baseline: 1.0276x; 1.0028x over previous
; #define PG8_WAIT_V(n) asm volatile("s_waitcnt vmcnt(" #n ")" ::: "memory")
; #define PG8_WAIT_L(n) asm volatile("s_waitcnt lgkmcnt(" #n ")" ::: "memory")
; #define PG8_BAR __builtin_amdgcn_s_barrier()
; #define PG8_SCHED __builtin_amdgcn_sched_barrier(0)
; template <class Epi, class AddrA, class AddrB>
; __device__ __forceinline__ void gemm_phase(const Sched S, const int lda, const int ldb, const int K, const AddrA addrA,
;                                            const AddrB addrB, const Epi E) {
;     ...
;     const bool has_next = S.next(ui + 1, nxt);
;     const char* nA = has_next ? addrA(nxt) : cA;
;     const char* nB = has_next ? addrB(nxt) : cB;
;     for (int t = 0; t < nt; t += 2) {
;       const bool last = (t == nt - 2);
;       const char* a1 = cA + (size_t)(t + 1) * kstep;
;       const char* a2 = last ? nA : cA + (size_t)(t + 2) * kstep;
;       const char* b2 = last ? nB : cB + (size_t)(t + 2) * kstep;
;       const char* a3 = a2 + kstep;
;       const char* b3 = b2 + kstep;
;       PG8_LDB(B0, 0, 0); PG8_SCHED; PG8_LDA(At, 0, 0); PG8_STAGE(PG8_SA(1, 1), a1 + hstepA, voffA);
;       PG8_WAIT_L(8); PG8_BAR; PG8_WAIT_L(0); PG8_MMA(0, 0, At, B0); PG8_BAR; PG8_SCHED;
;       PG8_LDB(B1, 0, 1); PG8_STAGE(PG8_SB(0, 0), b2, voffB);
;       PG8_BAR; PG8_WAIT_L(0); PG8_MMA(0, 1, At, B1); PG8_BAR;
;       PG8_LDA(At, 0, 1); PG8_STAGE(PG8_SA(0, 0), a2, voffA);
;       PG8_BAR; PG8_WAIT_L(0); PG8_MMA(1, 0, At, B0); PG8_BAR; PG8_SCHED;
;       PG8_STAGE(PG8_SB(0, 1), b2 + hstepB, voffB);
;       PG8_WAIT_V(6); PG8_BAR; PG8_MMA(1, 1, At, B1); PG8_BAR;
.LBB0_108:
	s_ashr_i32 s1, s0, 31
	s_lshl_b64 s[6:7], s[0:1], 20
	s_add_u32 s6, s20, s6
	s_addc_u32 s7, s21, s7
	s_and_b64 s[8:9], s[16:17], exec
	s_cselect_b32 s1, s7, s15
	s_cselect_b32 s11, s6, s14
	s_ashr_i32 s3, s2, 31
	s_lshl_b64 s[8:9], s[2:3], 20
	s_add_u32 s8, s22, s8
	s_addc_u32 s9, s23, s9
	s_and_b64 s[16:17], s[16:17], exec
	s_cselect_b32 s3, s9, s13
	s_cselect_b32 s36, s8, s12
	s_add_u32 s37, s12, 0x100
	s_addc_u32 s38, s13, 0
	s_add_u32 s12, s14, 0x80080
	s_addc_u32 s13, s15, 0
	s_mov_b32 s39, -2
	s_add_u32 s14, s12, 0xfff80080
	s_addc_u32 s15, s13, -1
	s_add_i32 s40, 0, 0x10000
	v_add_u32_e32 v142, s40, v145
	ds_read_b128 v[148:151], v142
	ds_read_b128 v[152:155], v142 offset:1024
	ds_read_b128 v[156:159], v142 offset:2048
	ds_read_b128 v[160:163], v142 offset:3072
	s_cmp_eq_u32 s39, 28
	s_cselect_b32 s17, s1, s15
	s_cselect_b32 s16, s11, s14
	s_cselect_b32 s15, s3, s38
	s_cselect_b32 s14, s36, s37
	v_lshl_add_u64 v[142:143], s[12:13], 0, v[140:141]
	s_add_i32 m0, s24, 0xc000
	ds_read_b128 v[168:171], v146
	ds_read_b128 v[172:175], v146 offset:1024
	ds_read_b128 v[176:179], v146 offset:2048
	ds_read_b128 v[180:183], v146 offset:3072
	ds_read_b128 v[184:187], v146 offset:4096
	ds_read_b128 v[188:191], v146 offset:5120
	ds_read_b128 v[192:195], v146 offset:6144
	ds_read_b128 v[212:215], v146 offset:7168
	global_load_lds_dwordx4 v[142:143], off
	v_lshl_add_u64 v[142:143], s[12:13], 0, v[138:139]
	s_add_i32 m0, s24, 0xe000
	s_nop 0
	global_load_lds_dwordx4 v[142:143], off
	s_waitcnt lgkmcnt(8)
	s_setprio 1
	s_barrier
	s_waitcnt lgkmcnt(0)
	v_mfma_f32_16x16x32_bf16 v[128:131], v[148:151], v[168:171], 0
	v_mfma_f32_16x16x32_bf16 v[128:131], v[152:155], v[172:175], v[128:131]
	v_mfma_f32_16x16x32_bf16 v[120:123], v[148:151], v[176:179], 0
	v_mfma_f32_16x16x32_bf16 v[120:123], v[152:155], v[180:183], v[120:123]
	v_mfma_f32_16x16x32_bf16 v[104:107], v[148:151], v[184:187], 0
	v_mfma_f32_16x16x32_bf16 v[104:107], v[152:155], v[188:191], v[104:107]
	v_mfma_f32_16x16x32_bf16 v[88:91], v[148:151], v[192:195], 0
	v_mfma_f32_16x16x32_bf16 v[88:91], v[152:155], v[212:215], v[88:91]
	v_mfma_f32_16x16x32_bf16 v[124:127], v[156:159], v[168:171], 0
	v_mfma_f32_16x16x32_bf16 v[124:127], v[160:163], v[172:175], v[124:127]
	v_mfma_f32_16x16x32_bf16 v[112:115], v[156:159], v[176:179], 0
	v_mfma_f32_16x16x32_bf16 v[112:115], v[160:163], v[180:183], v[112:115]
	v_mfma_f32_16x16x32_bf16 v[96:99], v[156:159], v[184:187], 0
	v_mfma_f32_16x16x32_bf16 v[96:99], v[160:163], v[188:191], v[96:99]
	v_mfma_f32_16x16x32_bf16 v[80:83], v[156:159], v[192:195], 0
	v_mfma_f32_16x16x32_bf16 v[80:83], v[160:163], v[212:215], v[80:83]
	s_barrier
	s_setprio 0
	s_add_i32 s42, 0, 0x14000
	v_add_u32_e32 v142, s42, v145
	s_add_i32 s40, s40, s19
	ds_read_b128 v[216:219], v142
	ds_read_b128 v[220:223], v142 offset:1024
	ds_read_b128 v[224:227], v142 offset:2048
	ds_read_b128 v[228:231], v142 offset:3072
	v_lshl_add_u64 v[142:143], s[14:15], 0, v[134:135]
	s_mov_b32 m0, s40
	v_lshl_add_u64 v[196:197], s[14:15], 0, v[0:1]
	global_load_lds_dwordx4 v[142:143], off
	s_add_i32 m0, s40, 0x2000
	s_nop 0
	global_load_lds_dwordx4 v[196:197], off
	s_setprio 1
	s_barrier
	s_waitcnt lgkmcnt(0)
	v_mfma_f32_16x16x32_bf16 v[116:119], v[216:219], v[168:171], 0
	v_mfma_f32_16x16x32_bf16 v[116:119], v[220:223], v[172:175], v[116:119]
	v_mfma_f32_16x16x32_bf16 v[100:103], v[216:219], v[176:179], 0
	v_mfma_f32_16x16x32_bf16 v[100:103], v[220:223], v[180:183], v[100:103]
	v_mfma_f32_16x16x32_bf16 v[84:87], v[216:219], v[184:187], 0
	v_mfma_f32_16x16x32_bf16 v[84:87], v[220:223], v[188:191], v[84:87]
	v_mfma_f32_16x16x32_bf16 v[72:75], v[216:219], v[192:195], 0
	v_mfma_f32_16x16x32_bf16 v[72:75], v[220:223], v[212:215], v[72:75]
	v_mfma_f32_16x16x32_bf16 v[108:111], v[224:227], v[168:171], 0
	v_mfma_f32_16x16x32_bf16 v[108:111], v[228:231], v[172:175], v[108:111]
	v_mfma_f32_16x16x32_bf16 v[92:95], v[224:227], v[176:179], 0
	v_mfma_f32_16x16x32_bf16 v[92:95], v[228:231], v[180:183], v[92:95]
	v_mfma_f32_16x16x32_bf16 v[76:79], v[224:227], v[184:187], 0
	v_mfma_f32_16x16x32_bf16 v[76:79], v[228:231], v[188:191], v[76:79]
	v_mfma_f32_16x16x32_bf16 v[68:71], v[224:227], v[192:195], 0
	v_mfma_f32_16x16x32_bf16 v[68:71], v[228:231], v[212:215], v[68:71]
	s_mov_b32 m0, s24
	v_lshl_add_u64 v[232:233], s[16:17], 0, v[136:137]
	s_barrier
	s_setprio 0
	ds_read_b128 v[168:171], v146 offset:16384
	ds_read_b128 v[172:175], v146 offset:17408
	ds_read_b128 v[176:179], v146 offset:18432
	ds_read_b128 v[180:183], v146 offset:19456
	ds_read_b128 v[184:187], v146 offset:20480
	ds_read_b128 v[188:191], v146 offset:21504
	ds_read_b128 v[192:195], v146 offset:22528
	ds_read_b128 v[212:215], v146 offset:23552
	global_load_lds_dwordx4 v[232:233], off
	v_lshl_add_u64 v[234:235], s[16:17], 0, v[132:133]
	s_mov_b32 m0, s25
	s_nop 0
	global_load_lds_dwordx4 v[234:235], off
	s_setprio 1
	s_barrier
	s_waitcnt lgkmcnt(0)
	v_mfma_f32_16x16x32_bf16 v[64:67], v[148:151], v[168:171], 0
	v_mfma_f32_16x16x32_bf16 v[64:67], v[152:155], v[172:175], v[64:67]
	v_mfma_f32_16x16x32_bf16 v[56:59], v[148:151], v[176:179], 0
	v_mfma_f32_16x16x32_bf16 v[56:59], v[152:155], v[180:183], v[56:59]
	v_mfma_f32_16x16x32_bf16 v[40:43], v[148:151], v[184:187], 0
	v_mfma_f32_16x16x32_bf16 v[40:43], v[152:155], v[188:191], v[40:43]
	v_mfma_f32_16x16x32_bf16 v[24:27], v[148:151], v[192:195], 0
	v_mfma_f32_16x16x32_bf16 v[24:27], v[152:155], v[212:215], v[24:27]
	v_mfma_f32_16x16x32_bf16 v[60:63], v[156:159], v[168:171], 0
	v_mfma_f32_16x16x32_bf16 v[60:63], v[160:163], v[172:175], v[60:63]
	v_mfma_f32_16x16x32_bf16 v[48:51], v[156:159], v[176:179], 0
	v_mfma_f32_16x16x32_bf16 v[48:51], v[160:163], v[180:183], v[48:51]
	v_mfma_f32_16x16x32_bf16 v[32:35], v[156:159], v[184:187], 0
	v_mfma_f32_16x16x32_bf16 v[32:35], v[160:163], v[188:191], v[32:35]
	v_mfma_f32_16x16x32_bf16 v[16:19], v[156:159], v[192:195], 0
	v_mfma_f32_16x16x32_bf16 v[16:19], v[160:163], v[212:215], v[16:19]
	s_barrier
; #define PG8_WAIT_V(n) asm volatile("s_waitcnt vmcnt(" #n ")" ::: "memory")
; #define PG8_WAIT_L(n) asm volatile("s_waitcnt lgkmcnt(" #n ")" ::: "memory")
; #define PG8_BAR __builtin_amdgcn_s_barrier()
; #define PG8_SCHED __builtin_amdgcn_sched_barrier(0)
; template <class Epi, class AddrA, class AddrB>
; __device__ __forceinline__ void gemm_phase(const Sched S, const int lda, const int ldb, const int K, const AddrA addrA,
;                                            const AddrB addrB, const Epi E) {
;     ...
;       PG8_BAR; PG8_WAIT_L(0); PG8_MMA(1, 0, At, B0); PG8_BAR; PG8_SCHED;
;       PG8_STAGE(PG8_SB(0, 1), b2 + hstepB, voffB);
;       PG8_WAIT_V(6); PG8_BAR; PG8_MMA(1, 1, At, B1); PG8_BAR;
;       PG8_LDB(B0, 1, 0); PG8_SCHED; PG8_LDA(At, 1, 0); PG8_STAGE(PG8_SA(0, 1), a2 + hstepA, voffA);
;       PG8_WAIT_L(8); PG8_BAR; PG8_WAIT_L(0); PG8_MMA(0, 0, At, B0); PG8_BAR; PG8_SCHED;
;       PG8_LDB(B1, 1, 1); PG8_STAGE(PG8_SB(1, 0), b3, voffB);
;       PG8_BAR; PG8_WAIT_L(0); PG8_MMA(0, 1, At, B1); PG8_BAR;
;       PG8_LDA(At, 1, 1); PG8_STAGE(PG8_SA(1, 0), a3, voffA);
;       PG8_BAR; PG8_WAIT_L(0); PG8_MMA(1, 0, At, B0); PG8_BAR; PG8_SCHED;
	s_setprio 0
	s_add_u32 s40, s14, 0x80000
	s_addc_u32 s41, s15, 0
	s_add_i32 s42, s42, s19
	v_lshl_add_u64 v[148:149], s[40:41], 0, v[134:135]
	s_mov_b32 m0, s42
	s_nop 0
	global_load_lds_dwordx4 v[148:149], off
	v_lshl_add_u64 v[148:149], s[40:41], 0, v[0:1]
	s_add_i32 m0, s42, 0x2000
	s_nop 0
	global_load_lds_dwordx4 v[148:149], off
	s_waitcnt vmcnt(6)
	s_setprio 1
	s_barrier
	v_mfma_f32_16x16x32_bf16 v[52:55], v[216:219], v[168:171], 0
	v_mfma_f32_16x16x32_bf16 v[52:55], v[220:223], v[172:175], v[52:55]
	v_mfma_f32_16x16x32_bf16 v[36:39], v[216:219], v[176:179], 0
	v_mfma_f32_16x16x32_bf16 v[36:39], v[220:223], v[180:183], v[36:39]
	v_mfma_f32_16x16x32_bf16 v[20:23], v[216:219], v[184:187], 0
	v_mfma_f32_16x16x32_bf16 v[20:23], v[220:223], v[188:191], v[20:23]
	v_mfma_f32_16x16x32_bf16 v[8:11], v[216:219], v[192:195], 0
	v_mfma_f32_16x16x32_bf16 v[8:11], v[220:223], v[212:215], v[8:11]
	v_mfma_f32_16x16x32_bf16 v[44:47], v[224:227], v[168:171], 0
	v_mfma_f32_16x16x32_bf16 v[44:47], v[228:231], v[172:175], v[44:47]
	v_mfma_f32_16x16x32_bf16 v[28:31], v[224:227], v[176:179], 0
	v_mfma_f32_16x16x32_bf16 v[28:31], v[228:231], v[180:183], v[28:31]
	v_mfma_f32_16x16x32_bf16 v[12:15], v[224:227], v[184:187], 0
	v_mfma_f32_16x16x32_bf16 v[12:15], v[228:231], v[188:191], v[12:15]
	v_mfma_f32_16x16x32_bf16 v[4:7], v[224:227], v[192:195], 0
	v_mfma_f32_16x16x32_bf16 v[4:7], v[228:231], v[212:215], v[4:7]
	s_add_i32 s40, 0, 0x18000
	v_add_u32_e32 v147, s40, v145
	s_barrier
	s_setprio 0
	ds_read_b128 v[148:151], v147
	ds_read_b128 v[152:155], v147 offset:1024
	ds_read_b128 v[156:159], v147 offset:2048
	ds_read_b128 v[160:163], v147 offset:3072
	s_add_u32 s16, s16, 0x80000
	s_addc_u32 s17, s17, 0
	s_mov_b32 m0, s26
	v_lshl_add_u64 v[216:217], s[16:17], 0, v[136:137]
	ds_read_b128 v[168:171], v146 offset:32768
	ds_read_b128 v[172:175], v146 offset:33792
	ds_read_b128 v[176:179], v146 offset:34816
	ds_read_b128 v[180:183], v146 offset:35840
	ds_read_b128 v[184:187], v146 offset:36864
	ds_read_b128 v[188:191], v146 offset:37888
	ds_read_b128 v[192:195], v146 offset:38912
	ds_read_b128 v[212:215], v146 offset:39936
	global_load_lds_dwordx4 v[216:217], off
	v_lshl_add_u64 v[216:217], s[16:17], 0, v[132:133]
	s_mov_b32 m0, s27
	s_nop 0
	global_load_lds_dwordx4 v[216:217], off
	s_waitcnt lgkmcnt(8)
	s_setprio 1
	s_barrier
	s_waitcnt lgkmcnt(0)
	v_mfma_f32_16x16x32_bf16 v[128:131], v[148:151], v[168:171], v[128:131]
	v_mfma_f32_16x16x32_bf16 v[128:131], v[152:155], v[172:175], v[128:131]
	v_mfma_f32_16x16x32_bf16 v[120:123], v[148:151], v[176:179], v[120:123]
	v_mfma_f32_16x16x32_bf16 v[120:123], v[152:155], v[180:183], v[120:123]
	v_mfma_f32_16x16x32_bf16 v[104:107], v[148:151], v[184:187], v[104:107]
	v_mfma_f32_16x16x32_bf16 v[104:107], v[152:155], v[188:191], v[104:107]
	v_mfma_f32_16x16x32_bf16 v[88:91], v[148:151], v[192:195], v[88:91]
	v_mfma_f32_16x16x32_bf16 v[88:91], v[152:155], v[212:215], v[88:91]
	v_mfma_f32_16x16x32_bf16 v[124:127], v[156:159], v[168:171], v[124:127]
	v_mfma_f32_16x16x32_bf16 v[124:127], v[160:163], v[172:175], v[124:127]
	v_mfma_f32_16x16x32_bf16 v[112:115], v[156:159], v[176:179], v[112:115]
	v_mfma_f32_16x16x32_bf16 v[112:115], v[160:163], v[180:183], v[112:115]
	v_mfma_f32_16x16x32_bf16 v[96:99], v[156:159], v[184:187], v[96:99]
	v_mfma_f32_16x16x32_bf16 v[96:99], v[160:163], v[188:191], v[96:99]
	v_mfma_f32_16x16x32_bf16 v[80:83], v[156:159], v[192:195], v[80:83]
	v_mfma_f32_16x16x32_bf16 v[80:83], v[160:163], v[212:215], v[80:83]
	s_barrier
	s_setprio 0
	s_add_i32 s16, 0, 0x1c000
	s_add_i32 s17, s40, s19
	v_add_u32_e32 v147, s16, v145
	v_lshl_add_u64 v[142:143], v[142:143], 0, s[52:53]
	s_mov_b32 m0, s17
	ds_read_b128 v[216:219], v147
	ds_read_b128 v[220:223], v147 offset:1024
	ds_read_b128 v[224:227], v147 offset:2048
	ds_read_b128 v[228:231], v147 offset:3072
	global_load_lds_dwordx4 v[142:143], off
	v_lshl_add_u64 v[142:143], v[196:197], 0, s[52:53]
	s_add_i32 m0, s17, 0x2000
	s_nop 0
	global_load_lds_dwordx4 v[142:143], off
	s_setprio 1
	s_barrier
	s_waitcnt lgkmcnt(0)
	v_mfma_f32_16x16x32_bf16 v[116:119], v[216:219], v[168:171], v[116:119]
	v_mfma_f32_16x16x32_bf16 v[116:119], v[220:223], v[172:175], v[116:119]
	v_mfma_f32_16x16x32_bf16 v[100:103], v[216:219], v[176:179], v[100:103]
	v_mfma_f32_16x16x32_bf16 v[100:103], v[220:223], v[180:183], v[100:103]
	v_mfma_f32_16x16x32_bf16 v[84:87], v[216:219], v[184:187], v[84:87]
	v_mfma_f32_16x16x32_bf16 v[84:87], v[220:223], v[188:191], v[84:87]
	v_mfma_f32_16x16x32_bf16 v[72:75], v[216:219], v[192:195], v[72:75]
	v_mfma_f32_16x16x32_bf16 v[72:75], v[220:223], v[212:215], v[72:75]
	v_mfma_f32_16x16x32_bf16 v[108:111], v[224:227], v[168:171], v[108:111]
	v_mfma_f32_16x16x32_bf16 v[108:111], v[228:231], v[172:175], v[108:111]
	v_mfma_f32_16x16x32_bf16 v[92:95], v[224:227], v[176:179], v[92:95]
	v_mfma_f32_16x16x32_bf16 v[92:95], v[228:231], v[180:183], v[92:95]
	v_mfma_f32_16x16x32_bf16 v[76:79], v[224:227], v[184:187], v[76:79]
	v_mfma_f32_16x16x32_bf16 v[76:79], v[228:231], v[188:191], v[76:79]
	v_mfma_f32_16x16x32_bf16 v[68:71], v[224:227], v[192:195], v[68:71]
	v_mfma_f32_16x16x32_bf16 v[68:71], v[228:231], v[212:215], v[68:71]
	s_mov_b32 m0, s30
	v_lshl_add_u64 v[142:143], v[232:233], 0, s[52:53]
	s_barrier
	s_setprio 0
	ds_read_b128 v[168:171], v146 offset:49152
	ds_read_b128 v[172:175], v146 offset:50176
	ds_read_b128 v[176:179], v146 offset:51200
	ds_read_b128 v[180:183], v146 offset:52224
	ds_read_b128 v[184:187], v146 offset:53248
	ds_read_b128 v[188:191], v146 offset:54272
	ds_read_b128 v[192:195], v146 offset:55296
	ds_read_b128 v[212:215], v146 offset:56320
	global_load_lds_dwordx4 v[142:143], off
	v_lshl_add_u64 v[142:143], v[234:235], 0, s[52:53]
	s_mov_b32 m0, s31
	s_nop 0
	global_load_lds_dwordx4 v[142:143], off
	s_setprio 1
	s_barrier
; #define PG8_WAIT_V(n) asm volatile("s_waitcnt vmcnt(" #n ")" ::: "memory")
; #define PG8_WAIT_L(n) asm volatile("s_waitcnt lgkmcnt(" #n ")" ::: "memory")
; #define PG8_BAR __builtin_amdgcn_s_barrier()
; #define PG8_SCHED __builtin_amdgcn_sched_barrier(0)
; template <class Epi, class AddrA, class AddrB>
; __device__ __forceinline__ void gemm_phase(const Sched S, const int lda, const int ldb, const int K, const AddrA addrA,
;                                            const AddrB addrB, const Epi E) {
;     ...
;     for (int t = 0; t < nt; t += 2) {
;       const bool last = (t == nt - 2);
;       const char* a1 = cA + (size_t)(t + 1) * kstep;
;       const char* a2 = last ? nA : cA + (size_t)(t + 2) * kstep;
;       const char* b2 = last ? nB : cB + (size_t)(t + 2) * kstep;
;       const char* a3 = a2 + kstep;
;       const char* b3 = b2 + kstep;
;       PG8_LDB(B0, 0, 0); PG8_SCHED; PG8_LDA(At, 0, 0); PG8_STAGE(PG8_SA(1, 1), a1 + hstepA, voffA);
;       PG8_WAIT_L(8); PG8_BAR; PG8_WAIT_L(0); PG8_MMA(0, 0, At, B0); PG8_BAR; PG8_SCHED;
;       PG8_LDB(B1, 0, 1); PG8_STAGE(PG8_SB(0, 0), b2, voffB);
;       PG8_BAR; PG8_WAIT_L(0); PG8_MMA(0, 1, At, B1); PG8_BAR;
;     ...
;       PG8_BAR; PG8_WAIT_L(0); PG8_MMA(1, 0, At, B0); PG8_BAR; PG8_SCHED;
;       PG8_STAGE(PG8_SB(1, 1), b3 + hstepB, voffB);
;       PG8_WAIT_V(6); PG8_BAR; PG8_MMA(1, 1, At, B1); PG8_BAR;
	s_waitcnt lgkmcnt(0)
	v_mfma_f32_16x16x32_bf16 v[64:67], v[148:151], v[168:171], v[64:67]
	v_mfma_f32_16x16x32_bf16 v[64:67], v[152:155], v[172:175], v[64:67]
	v_mfma_f32_16x16x32_bf16 v[56:59], v[148:151], v[176:179], v[56:59]
	v_mfma_f32_16x16x32_bf16 v[56:59], v[152:155], v[180:183], v[56:59]
	v_mfma_f32_16x16x32_bf16 v[40:43], v[148:151], v[184:187], v[40:43]
	v_mfma_f32_16x16x32_bf16 v[40:43], v[152:155], v[188:191], v[40:43]
	v_mfma_f32_16x16x32_bf16 v[24:27], v[148:151], v[192:195], v[24:27]
	v_mfma_f32_16x16x32_bf16 v[24:27], v[152:155], v[212:215], v[24:27]
	v_mfma_f32_16x16x32_bf16 v[60:63], v[156:159], v[168:171], v[60:63]
	v_mfma_f32_16x16x32_bf16 v[60:63], v[160:163], v[172:175], v[60:63]
	v_mfma_f32_16x16x32_bf16 v[48:51], v[156:159], v[176:179], v[48:51]
	v_mfma_f32_16x16x32_bf16 v[48:51], v[160:163], v[180:183], v[48:51]
	v_mfma_f32_16x16x32_bf16 v[32:35], v[156:159], v[184:187], v[32:35]
	v_mfma_f32_16x16x32_bf16 v[32:35], v[160:163], v[188:191], v[32:35]
	v_mfma_f32_16x16x32_bf16 v[16:19], v[156:159], v[192:195], v[16:19]
	v_mfma_f32_16x16x32_bf16 v[16:19], v[160:163], v[212:215], v[16:19]
	s_barrier
	s_setprio 0
	s_add_u32 s14, s14, 0x80080
	s_addc_u32 s15, s15, 0
	s_add_i32 s16, s16, s19
	v_lshl_add_u64 v[142:143], s[14:15], 0, v[134:135]
	s_mov_b32 m0, s16
	s_nop 0
	global_load_lds_dwordx4 v[142:143], off
	v_lshl_add_u64 v[142:143], s[14:15], 0, v[0:1]
	s_add_i32 m0, s16, 0x2000
	s_nop 0
	global_load_lds_dwordx4 v[142:143], off
	s_waitcnt vmcnt(6)
	s_setprio 1
	s_barrier
	v_mfma_f32_16x16x32_bf16 v[52:55], v[216:219], v[168:171], v[52:55]
	v_mfma_f32_16x16x32_bf16 v[52:55], v[220:223], v[172:175], v[52:55]
	v_mfma_f32_16x16x32_bf16 v[36:39], v[216:219], v[176:179], v[36:39]
	v_mfma_f32_16x16x32_bf16 v[36:39], v[220:223], v[180:183], v[36:39]
	v_mfma_f32_16x16x32_bf16 v[20:23], v[216:219], v[184:187], v[20:23]
	v_mfma_f32_16x16x32_bf16 v[20:23], v[220:223], v[188:191], v[20:23]
	v_mfma_f32_16x16x32_bf16 v[8:11], v[216:219], v[192:195], v[8:11]
	v_mfma_f32_16x16x32_bf16 v[8:11], v[220:223], v[212:215], v[8:11]
	v_mfma_f32_16x16x32_bf16 v[44:47], v[224:227], v[168:171], v[44:47]
	v_mfma_f32_16x16x32_bf16 v[44:47], v[228:231], v[172:175], v[44:47]
	v_mfma_f32_16x16x32_bf16 v[28:31], v[224:227], v[176:179], v[28:31]
	v_mfma_f32_16x16x32_bf16 v[28:31], v[228:231], v[180:183], v[28:31]
	v_mfma_f32_16x16x32_bf16 v[12:15], v[224:227], v[184:187], v[12:15]
	v_mfma_f32_16x16x32_bf16 v[12:15], v[228:231], v[188:191], v[12:15]
	v_mfma_f32_16x16x32_bf16 v[4:7], v[224:227], v[192:195], v[4:7]
	v_mfma_f32_16x16x32_bf16 v[4:7], v[228:231], v[212:215], v[4:7]
	s_add_i32 s39, s39, 2
	s_add_u32 s37, s37, 0x100
	s_addc_u32 s38, s38, 0
	s_add_u32 s12, s12, 0x100
	s_addc_u32 s13, s13, 0
	s_cmp_gt_u32 s39, 29
	s_barrier
	s_setprio 0
.LBB0_109:
	s_add_u32 s14, s12, 0xfff80080
	s_addc_u32 s15, s13, -1
	s_add_i32 s40, 0, 0x10000
	v_add_u32_e32 v142, s40, v145
	ds_read_b128 v[148:151], v142
	ds_read_b128 v[152:155], v142 offset:1024
	ds_read_b128 v[156:159], v142 offset:2048
	ds_read_b128 v[160:163], v142 offset:3072
	s_cmp_eq_u32 s39, 28
	s_cselect_b32 s17, s1, s15
	s_cselect_b32 s16, s11, s14
	s_cselect_b32 s15, s3, s38
	s_cselect_b32 s14, s36, s37
	v_lshl_add_u64 v[142:143], s[12:13], 0, v[140:141]
	s_add_i32 m0, s24, 0xc000
	ds_read_b128 v[168:171], v146
	ds_read_b128 v[172:175], v146 offset:1024
	ds_read_b128 v[176:179], v146 offset:2048
	ds_read_b128 v[180:183], v146 offset:3072
	ds_read_b128 v[184:187], v146 offset:4096
	ds_read_b128 v[188:191], v146 offset:5120
	ds_read_b128 v[192:195], v146 offset:6144
	ds_read_b128 v[212:215], v146 offset:7168
	global_load_lds_dwordx4 v[142:143], off
	v_lshl_add_u64 v[142:143], s[12:13], 0, v[138:139]
	s_add_i32 m0, s24, 0xe000
	s_nop 0
	global_load_lds_dwordx4 v[142:143], off
	s_waitcnt lgkmcnt(8)
	s_setprio 1
	s_barrier
	s_waitcnt lgkmcnt(0)
	v_mfma_f32_16x16x32_bf16 v[128:131], v[148:151], v[168:171], v[128:131]
	v_mfma_f32_16x16x32_bf16 v[128:131], v[152:155], v[172:175], v[128:131]
	v_mfma_f32_16x16x32_bf16 v[120:123], v[148:151], v[176:179], v[120:123]
	v_mfma_f32_16x16x32_bf16 v[120:123], v[152:155], v[180:183], v[120:123]
	v_mfma_f32_16x16x32_bf16 v[104:107], v[148:151], v[184:187], v[104:107]
	v_mfma_f32_16x16x32_bf16 v[104:107], v[152:155], v[188:191], v[104:107]
	v_mfma_f32_16x16x32_bf16 v[88:91], v[148:151], v[192:195], v[88:91]
	v_mfma_f32_16x16x32_bf16 v[88:91], v[152:155], v[212:215], v[88:91]
	v_mfma_f32_16x16x32_bf16 v[124:127], v[156:159], v[168:171], v[124:127]
	v_mfma_f32_16x16x32_bf16 v[124:127], v[160:163], v[172:175], v[124:127]
	v_mfma_f32_16x16x32_bf16 v[112:115], v[156:159], v[176:179], v[112:115]
	v_mfma_f32_16x16x32_bf16 v[112:115], v[160:163], v[180:183], v[112:115]
	v_mfma_f32_16x16x32_bf16 v[96:99], v[156:159], v[184:187], v[96:99]
	v_mfma_f32_16x16x32_bf16 v[96:99], v[160:163], v[188:191], v[96:99]
	v_mfma_f32_16x16x32_bf16 v[80:83], v[156:159], v[192:195], v[80:83]
	v_mfma_f32_16x16x32_bf16 v[80:83], v[160:163], v[212:215], v[80:83]
	s_barrier
	s_setprio 0
	s_add_i32 s42, 0, 0x14000
	v_add_u32_e32 v142, s42, v145
	s_add_i32 s40, s40, s19
	ds_read_b128 v[216:219], v142
	ds_read_b128 v[220:223], v142 offset:1024
	ds_read_b128 v[224:227], v142 offset:2048
	ds_read_b128 v[228:231], v142 offset:3072
	v_lshl_add_u64 v[142:143], s[14:15], 0, v[134:135]
	s_mov_b32 m0, s40
	v_lshl_add_u64 v[196:197], s[14:15], 0, v[0:1]
	global_load_lds_dwordx4 v[142:143], off
	s_add_i32 m0, s40, 0x2000
	s_nop 0
	global_load_lds_dwordx4 v[196:197], off
	s_setprio 1
	s_barrier
; #define PG8_WAIT_V(n) asm volatile("s_waitcnt vmcnt(" #n ")" ::: "memory")
; #define PG8_WAIT_L(n) asm volatile("s_waitcnt lgkmcnt(" #n ")" ::: "memory")
; #define PG8_BAR __builtin_amdgcn_s_barrier()
; #define PG8_SCHED __builtin_amdgcn_sched_barrier(0)
; template <class Epi, class AddrA, class AddrB>
; __device__ __forceinline__ void gemm_phase(const Sched S, const int lda, const int ldb, const int K, const AddrA addrA,
;                                            const AddrB addrB, const Epi E) {
;     ...
;       PG8_WAIT_L(8); PG8_BAR; PG8_WAIT_L(0); PG8_MMA(0, 0, At, B0); PG8_BAR; PG8_SCHED;
;       PG8_LDB(B1, 0, 1); PG8_STAGE(PG8_SB(0, 0), b2, voffB);
;       PG8_BAR; PG8_WAIT_L(0); PG8_MMA(0, 1, At, B1); PG8_BAR;
;       PG8_LDA(At, 0, 1); PG8_STAGE(PG8_SA(0, 0), a2, voffA);
;       PG8_BAR; PG8_WAIT_L(0); PG8_MMA(1, 0, At, B0); PG8_BAR; PG8_SCHED;
;       PG8_STAGE(PG8_SB(0, 1), b2 + hstepB, voffB);
;       PG8_WAIT_V(6); PG8_BAR; PG8_MMA(1, 1, At, B1); PG8_BAR;
;       PG8_LDB(B0, 1, 0); PG8_SCHED; PG8_LDA(At, 1, 0); PG8_STAGE(PG8_SA(0, 1), a2 + hstepA, voffA);
;       PG8_WAIT_L(8); PG8_BAR; PG8_WAIT_L(0); PG8_MMA(0, 0, At, B0); PG8_BAR; PG8_SCHED;
;       PG8_LDB(B1, 1, 1); PG8_STAGE(PG8_SB(1, 0), b3, voffB);
;       PG8_BAR; PG8_WAIT_L(0); PG8_MMA(0, 1, At, B1); PG8_BAR;
	s_waitcnt lgkmcnt(0)
	v_mfma_f32_16x16x32_bf16 v[116:119], v[216:219], v[168:171], v[116:119]
	v_mfma_f32_16x16x32_bf16 v[116:119], v[220:223], v[172:175], v[116:119]
	v_mfma_f32_16x16x32_bf16 v[100:103], v[216:219], v[176:179], v[100:103]
	v_mfma_f32_16x16x32_bf16 v[100:103], v[220:223], v[180:183], v[100:103]
	v_mfma_f32_16x16x32_bf16 v[84:87], v[216:219], v[184:187], v[84:87]
	v_mfma_f32_16x16x32_bf16 v[84:87], v[220:223], v[188:191], v[84:87]
	v_mfma_f32_16x16x32_bf16 v[72:75], v[216:219], v[192:195], v[72:75]
	v_mfma_f32_16x16x32_bf16 v[72:75], v[220:223], v[212:215], v[72:75]
	v_mfma_f32_16x16x32_bf16 v[108:111], v[224:227], v[168:171], v[108:111]
	v_mfma_f32_16x16x32_bf16 v[108:111], v[228:231], v[172:175], v[108:111]
	v_mfma_f32_16x16x32_bf16 v[92:95], v[224:227], v[176:179], v[92:95]
	v_mfma_f32_16x16x32_bf16 v[92:95], v[228:231], v[180:183], v[92:95]
	v_mfma_f32_16x16x32_bf16 v[76:79], v[224:227], v[184:187], v[76:79]
	v_mfma_f32_16x16x32_bf16 v[76:79], v[228:231], v[188:191], v[76:79]
	v_mfma_f32_16x16x32_bf16 v[68:71], v[224:227], v[192:195], v[68:71]
	v_mfma_f32_16x16x32_bf16 v[68:71], v[228:231], v[212:215], v[68:71]
	s_mov_b32 m0, s24
	v_lshl_add_u64 v[232:233], s[16:17], 0, v[136:137]
	s_barrier
	s_setprio 0
	ds_read_b128 v[168:171], v146 offset:16384
	ds_read_b128 v[172:175], v146 offset:17408
	ds_read_b128 v[176:179], v146 offset:18432
	ds_read_b128 v[180:183], v146 offset:19456
	ds_read_b128 v[184:187], v146 offset:20480
	ds_read_b128 v[188:191], v146 offset:21504
	ds_read_b128 v[192:195], v146 offset:22528
	ds_read_b128 v[212:215], v146 offset:23552
	global_load_lds_dwordx4 v[232:233], off
	v_lshl_add_u64 v[234:235], s[16:17], 0, v[132:133]
	s_mov_b32 m0, s25
	s_nop 0
	global_load_lds_dwordx4 v[234:235], off
	s_setprio 1
	s_barrier
	s_waitcnt lgkmcnt(0)
	v_mfma_f32_16x16x32_bf16 v[64:67], v[148:151], v[168:171], v[64:67]
	v_mfma_f32_16x16x32_bf16 v[64:67], v[152:155], v[172:175], v[64:67]
	v_mfma_f32_16x16x32_bf16 v[56:59], v[148:151], v[176:179], v[56:59]
	v_mfma_f32_16x16x32_bf16 v[56:59], v[152:155], v[180:183], v[56:59]
	v_mfma_f32_16x16x32_bf16 v[40:43], v[148:151], v[184:187], v[40:43]
	v_mfma_f32_16x16x32_bf16 v[40:43], v[152:155], v[188:191], v[40:43]
	v_mfma_f32_16x16x32_bf16 v[24:27], v[148:151], v[192:195], v[24:27]
	v_mfma_f32_16x16x32_bf16 v[24:27], v[152:155], v[212:215], v[24:27]
	v_mfma_f32_16x16x32_bf16 v[60:63], v[156:159], v[168:171], v[60:63]
	v_mfma_f32_16x16x32_bf16 v[60:63], v[160:163], v[172:175], v[60:63]
	v_mfma_f32_16x16x32_bf16 v[48:51], v[156:159], v[176:179], v[48:51]
	v_mfma_f32_16x16x32_bf16 v[48:51], v[160:163], v[180:183], v[48:51]
	v_mfma_f32_16x16x32_bf16 v[32:35], v[156:159], v[184:187], v[32:35]
	v_mfma_f32_16x16x32_bf16 v[32:35], v[160:163], v[188:191], v[32:35]
	v_mfma_f32_16x16x32_bf16 v[16:19], v[156:159], v[192:195], v[16:19]
	v_mfma_f32_16x16x32_bf16 v[16:19], v[160:163], v[212:215], v[16:19]
	s_barrier
	s_setprio 0
	s_add_u32 s40, s14, 0x80000
	s_addc_u32 s41, s15, 0
	s_add_i32 s42, s42, s19
	v_lshl_add_u64 v[148:149], s[40:41], 0, v[134:135]
	s_mov_b32 m0, s42
	s_nop 0
	global_load_lds_dwordx4 v[148:149], off
	v_lshl_add_u64 v[148:149], s[40:41], 0, v[0:1]
	s_add_i32 m0, s42, 0x2000
	s_nop 0
	global_load_lds_dwordx4 v[148:149], off
	s_waitcnt vmcnt(6)
	s_setprio 1
	s_barrier
	v_mfma_f32_16x16x32_bf16 v[52:55], v[216:219], v[168:171], v[52:55]
	v_mfma_f32_16x16x32_bf16 v[52:55], v[220:223], v[172:175], v[52:55]
	v_mfma_f32_16x16x32_bf16 v[36:39], v[216:219], v[176:179], v[36:39]
	v_mfma_f32_16x16x32_bf16 v[36:39], v[220:223], v[180:183], v[36:39]
	v_mfma_f32_16x16x32_bf16 v[20:23], v[216:219], v[184:187], v[20:23]
	v_mfma_f32_16x16x32_bf16 v[20:23], v[220:223], v[188:191], v[20:23]
	v_mfma_f32_16x16x32_bf16 v[8:11], v[216:219], v[192:195], v[8:11]
	v_mfma_f32_16x16x32_bf16 v[8:11], v[220:223], v[212:215], v[8:11]
	v_mfma_f32_16x16x32_bf16 v[44:47], v[224:227], v[168:171], v[44:47]
	v_mfma_f32_16x16x32_bf16 v[44:47], v[228:231], v[172:175], v[44:47]
	v_mfma_f32_16x16x32_bf16 v[28:31], v[224:227], v[176:179], v[28:31]
	v_mfma_f32_16x16x32_bf16 v[28:31], v[228:231], v[180:183], v[28:31]
	v_mfma_f32_16x16x32_bf16 v[12:15], v[224:227], v[184:187], v[12:15]
	v_mfma_f32_16x16x32_bf16 v[12:15], v[228:231], v[188:191], v[12:15]
	v_mfma_f32_16x16x32_bf16 v[4:7], v[224:227], v[192:195], v[4:7]
	v_mfma_f32_16x16x32_bf16 v[4:7], v[228:231], v[212:215], v[4:7]
	s_add_i32 s40, 0, 0x18000
	v_add_u32_e32 v147, s40, v145
	s_barrier
	s_setprio 0
	ds_read_b128 v[148:151], v147
	ds_read_b128 v[152:155], v147 offset:1024
	ds_read_b128 v[156:159], v147 offset:2048
	ds_read_b128 v[160:163], v147 offset:3072
	s_add_u32 s16, s16, 0x80000
	s_addc_u32 s17, s17, 0
	s_mov_b32 m0, s26
	v_lshl_add_u64 v[216:217], s[16:17], 0, v[136:137]
	ds_read_b128 v[168:171], v146 offset:32768
	ds_read_b128 v[172:175], v146 offset:33792
	ds_read_b128 v[176:179], v146 offset:34816
	ds_read_b128 v[180:183], v146 offset:35840
	ds_read_b128 v[184:187], v146 offset:36864
	ds_read_b128 v[188:191], v146 offset:37888
	ds_read_b128 v[192:195], v146 offset:38912
	ds_read_b128 v[212:215], v146 offset:39936
	global_load_lds_dwordx4 v[216:217], off
	v_lshl_add_u64 v[216:217], s[16:17], 0, v[132:133]
	s_mov_b32 m0, s27
	s_nop 0
	global_load_lds_dwordx4 v[216:217], off
	s_waitcnt lgkmcnt(8)
	s_setprio 1
	s_barrier
; #define PG8_WAIT_V(n) asm volatile("s_waitcnt vmcnt(" #n ")" ::: "memory")
; #define PG8_WAIT_L(n) asm volatile("s_waitcnt lgkmcnt(" #n ")" ::: "memory")
; #define PG8_BAR __builtin_amdgcn_s_barrier()
; #define PG8_SCHED __builtin_amdgcn_sched_barrier(0)
; template <class Epi, class AddrA, class AddrB>
; __device__ __forceinline__ void gemm_phase(const Sched S, const int lda, const int ldb, const int K, const AddrA addrA,
;                                            const AddrB addrB, const Epi E) {
;     ...
;       PG8_WAIT_L(8); PG8_BAR; PG8_WAIT_L(0); PG8_MMA(0, 0, At, B0); PG8_BAR; PG8_SCHED;
;       PG8_LDB(B1, 1, 1); PG8_STAGE(PG8_SB(1, 0), b3, voffB);
;       PG8_BAR; PG8_WAIT_L(0); PG8_MMA(0, 1, At, B1); PG8_BAR;
;       PG8_LDA(At, 1, 1); PG8_STAGE(PG8_SA(1, 0), a3, voffA);
;       PG8_BAR; PG8_WAIT_L(0); PG8_MMA(1, 0, At, B0); PG8_BAR; PG8_SCHED;
;       PG8_STAGE(PG8_SB(1, 1), b3 + hstepB, voffB);
;       PG8_WAIT_V(6); PG8_BAR; PG8_MMA(1, 1, At, B1); PG8_BAR;
	s_waitcnt lgkmcnt(0)
	v_mfma_f32_16x16x32_bf16 v[128:131], v[148:151], v[168:171], v[128:131]
	v_mfma_f32_16x16x32_bf16 v[128:131], v[152:155], v[172:175], v[128:131]
	v_mfma_f32_16x16x32_bf16 v[120:123], v[148:151], v[176:179], v[120:123]
	v_mfma_f32_16x16x32_bf16 v[120:123], v[152:155], v[180:183], v[120:123]
	v_mfma_f32_16x16x32_bf16 v[104:107], v[148:151], v[184:187], v[104:107]
	v_mfma_f32_16x16x32_bf16 v[104:107], v[152:155], v[188:191], v[104:107]
	v_mfma_f32_16x16x32_bf16 v[88:91], v[148:151], v[192:195], v[88:91]
	v_mfma_f32_16x16x32_bf16 v[88:91], v[152:155], v[212:215], v[88:91]
	v_mfma_f32_16x16x32_bf16 v[124:127], v[156:159], v[168:171], v[124:127]
	v_mfma_f32_16x16x32_bf16 v[124:127], v[160:163], v[172:175], v[124:127]
	v_mfma_f32_16x16x32_bf16 v[112:115], v[156:159], v[176:179], v[112:115]
	v_mfma_f32_16x16x32_bf16 v[112:115], v[160:163], v[180:183], v[112:115]
	v_mfma_f32_16x16x32_bf16 v[96:99], v[156:159], v[184:187], v[96:99]
	v_mfma_f32_16x16x32_bf16 v[96:99], v[160:163], v[188:191], v[96:99]
	v_mfma_f32_16x16x32_bf16 v[80:83], v[156:159], v[192:195], v[80:83]
	v_mfma_f32_16x16x32_bf16 v[80:83], v[160:163], v[212:215], v[80:83]
	s_barrier
	s_setprio 0
	s_add_i32 s16, 0, 0x1c000
	s_add_i32 s17, s40, s19
	v_add_u32_e32 v147, s16, v145
	v_lshl_add_u64 v[142:143], v[142:143], 0, s[52:53]
	s_mov_b32 m0, s17
	ds_read_b128 v[216:219], v147
	ds_read_b128 v[220:223], v147 offset:1024
	ds_read_b128 v[224:227], v147 offset:2048
	ds_read_b128 v[228:231], v147 offset:3072
	global_load_lds_dwordx4 v[142:143], off
	v_lshl_add_u64 v[142:143], v[196:197], 0, s[52:53]
	s_add_i32 m0, s17, 0x2000
	s_nop 0
	global_load_lds_dwordx4 v[142:143], off
	s_setprio 1
	s_barrier
	s_waitcnt lgkmcnt(0)
	v_mfma_f32_16x16x32_bf16 v[116:119], v[216:219], v[168:171], v[116:119]
	v_mfma_f32_16x16x32_bf16 v[116:119], v[220:223], v[172:175], v[116:119]
	v_mfma_f32_16x16x32_bf16 v[100:103], v[216:219], v[176:179], v[100:103]
	v_mfma_f32_16x16x32_bf16 v[100:103], v[220:223], v[180:183], v[100:103]
	v_mfma_f32_16x16x32_bf16 v[84:87], v[216:219], v[184:187], v[84:87]
	v_mfma_f32_16x16x32_bf16 v[84:87], v[220:223], v[188:191], v[84:87]
	v_mfma_f32_16x16x32_bf16 v[72:75], v[216:219], v[192:195], v[72:75]
	v_mfma_f32_16x16x32_bf16 v[72:75], v[220:223], v[212:215], v[72:75]
	v_mfma_f32_16x16x32_bf16 v[108:111], v[224:227], v[168:171], v[108:111]
	v_mfma_f32_16x16x32_bf16 v[108:111], v[228:231], v[172:175], v[108:111]
	v_mfma_f32_16x16x32_bf16 v[92:95], v[224:227], v[176:179], v[92:95]
	v_mfma_f32_16x16x32_bf16 v[92:95], v[228:231], v[180:183], v[92:95]
	v_mfma_f32_16x16x32_bf16 v[76:79], v[224:227], v[184:187], v[76:79]
	v_mfma_f32_16x16x32_bf16 v[76:79], v[228:231], v[188:191], v[76:79]
	v_mfma_f32_16x16x32_bf16 v[68:71], v[224:227], v[192:195], v[68:71]
	v_mfma_f32_16x16x32_bf16 v[68:71], v[228:231], v[212:215], v[68:71]
	s_mov_b32 m0, s30
	v_lshl_add_u64 v[142:143], v[232:233], 0, s[52:53]
	s_barrier
	s_setprio 0
	ds_read_b128 v[168:171], v146 offset:49152
	ds_read_b128 v[172:175], v146 offset:50176
	ds_read_b128 v[176:179], v146 offset:51200
	ds_read_b128 v[180:183], v146 offset:52224
	ds_read_b128 v[184:187], v146 offset:53248
	ds_read_b128 v[188:191], v146 offset:54272
	ds_read_b128 v[192:195], v146 offset:55296
	ds_read_b128 v[212:215], v146 offset:56320
	global_load_lds_dwordx4 v[142:143], off
	v_lshl_add_u64 v[142:143], v[234:235], 0, s[52:53]
	s_mov_b32 m0, s31
	s_nop 0
	global_load_lds_dwordx4 v[142:143], off
	s_setprio 1
	s_barrier
	s_waitcnt lgkmcnt(0)
	v_mfma_f32_16x16x32_bf16 v[64:67], v[148:151], v[168:171], v[64:67]
	v_mfma_f32_16x16x32_bf16 v[64:67], v[152:155], v[172:175], v[64:67]
	v_mfma_f32_16x16x32_bf16 v[56:59], v[148:151], v[176:179], v[56:59]
	v_mfma_f32_16x16x32_bf16 v[56:59], v[152:155], v[180:183], v[56:59]
	v_mfma_f32_16x16x32_bf16 v[40:43], v[148:151], v[184:187], v[40:43]
	v_mfma_f32_16x16x32_bf16 v[40:43], v[152:155], v[188:191], v[40:43]
	v_mfma_f32_16x16x32_bf16 v[24:27], v[148:151], v[192:195], v[24:27]
	v_mfma_f32_16x16x32_bf16 v[24:27], v[152:155], v[212:215], v[24:27]
	v_mfma_f32_16x16x32_bf16 v[60:63], v[156:159], v[168:171], v[60:63]
	v_mfma_f32_16x16x32_bf16 v[60:63], v[160:163], v[172:175], v[60:63]
	v_mfma_f32_16x16x32_bf16 v[48:51], v[156:159], v[176:179], v[48:51]
	v_mfma_f32_16x16x32_bf16 v[48:51], v[160:163], v[180:183], v[48:51]
	v_mfma_f32_16x16x32_bf16 v[32:35], v[156:159], v[184:187], v[32:35]
	v_mfma_f32_16x16x32_bf16 v[32:35], v[160:163], v[188:191], v[32:35]
	v_mfma_f32_16x16x32_bf16 v[16:19], v[156:159], v[192:195], v[16:19]
	v_mfma_f32_16x16x32_bf16 v[16:19], v[160:163], v[212:215], v[16:19]
	s_barrier
	s_setprio 0
	s_add_u32 s14, s14, 0x80080
	s_addc_u32 s15, s15, 0
	s_add_i32 s16, s16, s19
	v_lshl_add_u64 v[142:143], s[14:15], 0, v[134:135]
	s_mov_b32 m0, s16
	s_nop 0
	global_load_lds_dwordx4 v[142:143], off
	v_lshl_add_u64 v[142:143], s[14:15], 0, v[0:1]
	s_add_i32 m0, s16, 0x2000
	s_nop 0
	global_load_lds_dwordx4 v[142:143], off
	s_waitcnt vmcnt(6)
	s_setprio 1
	s_barrier
; #define PG8_WAIT_V(n) asm volatile("s_waitcnt vmcnt(" #n ")" ::: "memory")
; #define PG8_BAR __builtin_amdgcn_s_barrier()
; template <class Epi, class AddrA, class AddrB>
; __device__ __forceinline__ void gemm_phase(const Sched S, const int lda, const int ldb, const int K, const AddrA addrA,
;                                            const AddrB addrB, const Epi E) {
;     ...
;       PG8_WAIT_V(6); PG8_BAR; PG8_MMA(1, 1, At, B1); PG8_BAR;
;     }
;     E(acc, cur, wr, wc, fr, fq);
;     if (!has_next) break;
;   __device__ __forceinline__ void operator()(EPI_ARGS) const {
;     bf16_t* base = proj + ((size_t)u.pn * MTOK + (size_t)(u.pm * 256 + wr * 64 + fr)) * PLD + wc * 32 + 8 * fq;
; #pragma unroll
;     for (int ai = 0; ai < 2; ++ai)
; #pragma unroll
;       for (int m = 0; m < 4; ++m) {
;         bf16_t* rowp = base + (size_t)(ai * HALF + m * 16) * PLD;
; #pragma unroll
;         for (int bj = 0; bj < 2; ++bj) {
;           const f32x4 v0 = acc[ai][bj][m][0], v1 = acc[ai][bj][m][1];
;           u32x4 o;
;           o.x = pack2(v0[0], v0[1]); o.y = pack2(v0[2], v0[3]); o.z = pack2(v1[0], v1[1]); o.w = pack2(v1[2], v1[3]);
;           *(u32x4*)(rowp + bj * HALF) = o;
;         }
;       }
	v_mfma_f32_16x16x32_bf16 v[52:55], v[216:219], v[168:171], v[52:55]
	v_mfma_f32_16x16x32_bf16 v[52:55], v[220:223], v[172:175], v[52:55]
	v_mfma_f32_16x16x32_bf16 v[36:39], v[216:219], v[176:179], v[36:39]
	v_mfma_f32_16x16x32_bf16 v[36:39], v[220:223], v[180:183], v[36:39]
	v_mfma_f32_16x16x32_bf16 v[20:23], v[216:219], v[184:187], v[20:23]
	v_mfma_f32_16x16x32_bf16 v[20:23], v[220:223], v[188:191], v[20:23]
	v_mfma_f32_16x16x32_bf16 v[8:11], v[216:219], v[192:195], v[8:11]
	v_mfma_f32_16x16x32_bf16 v[8:11], v[220:223], v[212:215], v[8:11]
	v_mfma_f32_16x16x32_bf16 v[44:47], v[224:227], v[168:171], v[44:47]
	v_mfma_f32_16x16x32_bf16 v[44:47], v[228:231], v[172:175], v[44:47]
	v_mfma_f32_16x16x32_bf16 v[28:31], v[224:227], v[176:179], v[28:31]
	v_mfma_f32_16x16x32_bf16 v[28:31], v[228:231], v[180:183], v[28:31]
	v_mfma_f32_16x16x32_bf16 v[12:15], v[224:227], v[184:187], v[12:15]
	v_mfma_f32_16x16x32_bf16 v[12:15], v[228:231], v[188:191], v[12:15]
	v_mfma_f32_16x16x32_bf16 v[4:7], v[224:227], v[192:195], v[4:7]
	v_mfma_f32_16x16x32_bf16 v[4:7], v[228:231], v[212:215], v[4:7]
	s_add_i32 s39, s39, 2
	s_add_u32 s37, s37, 0x100
	s_addc_u32 s38, s38, 0
	s_add_u32 s12, s12, 0x100
	s_addc_u32 s13, s13, 0
	s_cmp_gt_u32 s39, 29
	s_barrier
	s_setprio 0
	s_cbranch_scc0 .LBB0_109
	s_ashr_i32 s11, s10, 31
	v_lshl_add_u32 v142, s35, 8, v144
	s_lshl_b64 s[10:11], s[10:11], 23
	v_ashrrev_i32_e32 v143, 31, v142
	s_add_u32 s10, s28, s10
	s_addc_u32 s11, s29, s11
	v_lshlrev_b64 v[142:143], 9, v[142:143]
	v_lshl_add_u64 v[142:143], s[10:11], 0, v[142:143]
	v_lshl_add_u64 v[142:143], v[142:143], 0, s[72:73]
	v_lshl_add_u64 v[142:143], v[142:143], 0, v[2:3]
	v_cvt_pk_bf16_f32 v116, v116, v117
	v_cvt_pk_bf16_f32 v117, v118, v119
	v_cvt_pk_bf16_f32 v119, v110, v111
	v_cvt_pk_bf16_f32 v110, v112, v113
	v_add_co_u32_e32 v112, vcc, s96, v142
	s_movk_i32 s1, 0x4000
	s_nop 0
	v_addc_co_u32_e32 v113, vcc, 0, v143, vcc
	v_cvt_pk_bf16_f32 v100, v100, v101
	v_cvt_pk_bf16_f32 v101, v102, v103
	v_cvt_pk_bf16_f32 v103, v94, v95
	v_cvt_pk_bf16_f32 v94, v96, v97
	v_add_co_u32_e32 v96, vcc, s1, v142
	s_movk_i32 s1, 0x6000
	s_nop 0
	v_addc_co_u32_e32 v97, vcc, 0, v143, vcc
	v_cvt_pk_bf16_f32 v84, v84, v85
	v_cvt_pk_bf16_f32 v85, v86, v87
	v_cvt_pk_bf16_f32 v87, v78, v79
	v_cvt_pk_bf16_f32 v78, v80, v81
	v_add_co_u32_e32 v80, vcc, s1, v142
	v_cvt_pk_bf16_f32 v64, v64, v65
	v_cvt_pk_bf16_f32 v65, v66, v67
	v_cvt_pk_bf16_f32 v66, v60, v61
	s_mov_b32 s1, 0x12000
	s_nop 0
	v_addc_co_u32_e32 v81, vcc, 0, v143, vcc
	v_add_co_u32_e32 v60, vcc, s67, v142
	v_cvt_pk_bf16_f32 v52, v52, v53
	v_cvt_pk_bf16_f32 v53, v54, v55
	v_cvt_pk_bf16_f32 v55, v46, v47
	v_cvt_pk_bf16_f32 v46, v48, v49
	s_nop 1
	v_addc_co_u32_e32 v61, vcc, 0, v143, vcc
	v_add_co_u32_e32 v48, vcc, s1, v142
	s_mov_b32 s1, 0x14000
	s_nop 0
	v_addc_co_u32_e32 v49, vcc, 0, v143, vcc
	v_cvt_pk_bf16_f32 v36, v36, v37
	v_cvt_pk_bf16_f32 v37, v38, v39
	v_cvt_pk_bf16_f32 v39, v30, v31
	v_cvt_pk_bf16_f32 v30, v32, v33
	v_add_co_u32_e32 v32, vcc, s1, v142
	s_mov_b32 s1, 0x16000
	s_nop 0
	v_addc_co_u32_e32 v33, vcc, 0, v143, vcc
	v_cvt_pk_bf16_f32 v20, v20, v21
	v_cvt_pk_bf16_f32 v21, v22, v23
	v_cvt_pk_bf16_f32 v23, v14, v15
	v_cvt_pk_bf16_f32 v14, v16, v17
	v_add_co_u32_e32 v16, vcc, s1, v142
	s_mov_b32 s10, s2
	s_nop 0
	v_addc_co_u32_e32 v17, vcc, 0, v143, vcc
	s_and_b64 vcc, exec, s[4:5]
	s_mov_b32 s35, s0
	s_mov_b64 s[12:13], s[8:9]
	s_mov_b64 s[14:15], s[6:7]
	v_cvt_pk_bf16_f32 v128, v128, v129
	v_cvt_pk_bf16_f32 v129, v130, v131
	v_cvt_pk_bf16_f32 v130, v124, v125
	v_cvt_pk_bf16_f32 v131, v126, v127
	flat_store_dwordx4 v[142:143], v[128:131]
	v_cvt_pk_bf16_f32 v118, v108, v109
	flat_store_dwordx4 v[142:143], v[116:119] offset:256
	v_cvt_pk_bf16_f32 v108, v120, v121
	v_cvt_pk_bf16_f32 v109, v122, v123
	v_cvt_pk_bf16_f32 v111, v114, v115
	flat_store_dwordx4 v[112:113], v[108:111]
	v_cvt_pk_bf16_f32 v102, v92, v93
	flat_store_dwordx4 v[112:113], v[100:103] offset:256
	v_cvt_pk_bf16_f32 v92, v104, v105
	v_cvt_pk_bf16_f32 v93, v106, v107
	v_cvt_pk_bf16_f32 v95, v98, v99
	flat_store_dwordx4 v[96:97], v[92:95]
	v_cvt_pk_bf16_f32 v86, v76, v77
	flat_store_dwordx4 v[96:97], v[84:87] offset:256
	v_cvt_pk_bf16_f32 v76, v88, v89
	v_cvt_pk_bf16_f32 v77, v90, v91
	v_cvt_pk_bf16_f32 v79, v82, v83
	flat_store_dwordx4 v[80:81], v[76:79]
	v_cvt_pk_bf16_f32 v72, v72, v73
	v_cvt_pk_bf16_f32 v73, v74, v75
	v_cvt_pk_bf16_f32 v74, v68, v69
	v_cvt_pk_bf16_f32 v75, v70, v71
	flat_store_dwordx4 v[80:81], v[72:75] offset:256
	v_cvt_pk_bf16_f32 v67, v62, v63
	flat_store_dwordx4 v[60:61], v[64:67]
	v_cvt_pk_bf16_f32 v54, v44, v45
	flat_store_dwordx4 v[60:61], v[52:55] offset:256
	v_cvt_pk_bf16_f32 v44, v56, v57
	v_cvt_pk_bf16_f32 v45, v58, v59
	v_cvt_pk_bf16_f32 v47, v50, v51
	flat_store_dwordx4 v[48:49], v[44:47]
	v_cvt_pk_bf16_f32 v38, v28, v29
	flat_store_dwordx4 v[48:49], v[36:39] offset:256
	v_cvt_pk_bf16_f32 v28, v40, v41
	v_cvt_pk_bf16_f32 v29, v42, v43
	v_cvt_pk_bf16_f32 v31, v34, v35
	flat_store_dwordx4 v[32:33], v[28:31]
	v_cvt_pk_bf16_f32 v22, v12, v13
	flat_store_dwordx4 v[32:33], v[20:23] offset:256
	v_cvt_pk_bf16_f32 v12, v24, v25
	v_cvt_pk_bf16_f32 v13, v26, v27
	v_cvt_pk_bf16_f32 v15, v18, v19
	flat_store_dwordx4 v[16:17], v[12:15]
	v_cvt_pk_bf16_f32 v8, v8, v9
	v_cvt_pk_bf16_f32 v9, v10, v11
	v_cvt_pk_bf16_f32 v10, v4, v5
	v_cvt_pk_bf16_f32 v11, v6, v7
	flat_store_dwordx4 v[16:17], v[8:11] offset:256
	s_cbranch_vccz .LBB0_106
	s_waitcnt vmcnt(0)
	s_cmpk_gt_u32 s18, 0xff
	s_cbranch_scc1 .LBB0_113
	s_barrier

; #define PG8_WAIT_V(n) asm volatile("s_waitcnt vmcnt(" #n ")" ::: "memory")
; #define PG8_WAIT_L(n) asm volatile("s_waitcnt lgkmcnt(" #n ")" ::: "memory")
; #define PG8_BAR __builtin_amdgcn_s_barrier()
; #define PG8_SCHED __builtin_amdgcn_sched_barrier(0)
; template <class Epi, class AddrA, class AddrB>
; __device__ __forceinline__ void gemm_phase(const Sched S, const int lda, const int ldb, const int K, const AddrA addrA,
;                                            const AddrB addrB, const Epi E) {
;     ...
;     const bool has_next = S.next(ui + 1, nxt);
;     const char* nA = has_next ? addrA(nxt) : cA;
;     const char* nB = has_next ? addrB(nxt) : cB;
;     for (int t = 0; t < nt; t += 2) {
;       const bool last = (t == nt - 2);
;       const char* a1 = cA + (size_t)(t + 1) * kstep;
;       const char* a2 = last ? nA : cA + (size_t)(t + 2) * kstep;
;       const char* b2 = last ? nB : cB + (size_t)(t + 2) * kstep;
;       const char* a3 = a2 + kstep;
;       const char* b3 = b2 + kstep;
;       PG8_LDB(B0, 0, 0); PG8_SCHED; PG8_LDA(At, 0, 0); PG8_STAGE(PG8_SA(1, 1), a1 + hstepA, voffA);
;       PG8_WAIT_L(8); PG8_BAR; PG8_WAIT_L(0); PG8_MMA(0, 0, At, B0); PG8_BAR; PG8_SCHED;
;       PG8_LDB(B1, 0, 1); PG8_STAGE(PG8_SB(0, 0), b2, voffB);
;       PG8_BAR; PG8_WAIT_L(0); PG8_MMA(0, 1, At, B1); PG8_BAR;
;       PG8_LDA(At, 0, 1); PG8_STAGE(PG8_SA(0, 0), a2, voffA);
;       PG8_BAR; PG8_WAIT_L(0); PG8_MMA(1, 0, At, B0); PG8_BAR; PG8_SCHED;
;       PG8_STAGE(PG8_SB(0, 1), b2 + hstepB, voffB);
;       PG8_WAIT_V(6); PG8_BAR; PG8_MMA(1, 1, At, B1); PG8_BAR;
.LBB0_484:
	s_ashr_i32 s15, s14, 31
	s_lshl_b64 s[20:21], s[14:15], 20
	s_add_u32 s3, s25, s20
	s_addc_u32 s15, s26, s21
	s_lshl_b32 s17, s16, 8
	s_and_b32 s20, s17, 0xfffffe00
	s_ashr_i32 s21, s20, 31
	s_lshl_b64 s[20:21], s[20:21], 1
	s_add_u32 s20, s3, s20
	s_addc_u32 s21, s15, s21
	s_and_b64 s[22:23], s[10:11], exec
	s_cselect_b32 s3, s21, s7
	s_cselect_b32 s15, s20, s6
	s_ashr_i32 s17, s16, 31
	s_lshl_b64 s[22:23], s[16:17], 18
	s_add_u32 s22, s27, s22
	s_addc_u32 s23, s28, s23
	s_and_b64 s[10:11], s[10:11], exec
	s_cselect_b32 s17, s23, s5
	s_cselect_b32 s40, s22, s4
	s_add_u32 s41, s4, 0x100
	s_addc_u32 s42, s5, 0
	s_add_u32 s4, s6, 0x80080
	s_addc_u32 s5, s7, 0
	s_mov_b32 s43, -2
	s_add_u32 s6, s4, 0xfff80080
	s_addc_u32 s7, s5, -1
	s_add_i32 s44, 0, 0x10000
	v_add_u32_e32 v2, s44, v167
	ds_read_b128 v[92:95], v2
	ds_read_b128 v[100:103], v2 offset:1024
	ds_read_b128 v[132:135], v2 offset:2048
	ds_read_b128 v[144:147], v2 offset:3072
	s_cmp_eq_u32 s43, 4
	s_cselect_b32 s11, s3, s7
	s_cselect_b32 s10, s15, s6
	s_cselect_b32 s7, s17, s42
	s_cselect_b32 s6, s40, s41
	v_lshl_add_u64 v[196:197], s[4:5], 0, v[172:173]
	s_add_i32 m0, s30, 0xc000
	ds_read_b128 v[148:151], v169
	ds_read_b128 v[152:155], v169 offset:1024
	ds_read_b128 v[176:179], v169 offset:2048
	ds_read_b128 v[180:183], v169 offset:3072
	ds_read_b128 v[184:187], v169 offset:4096
	ds_read_b128 v[188:191], v169 offset:5120
	ds_read_b128 v[192:195], v169 offset:6144
	ds_read_b128 v[212:215], v169 offset:7168
	global_load_lds_dwordx4 v[196:197], off
	v_lshl_add_u64 v[196:197], s[4:5], 0, v[170:171]
	s_add_i32 m0, s30, 0xe000
	s_nop 0
	global_load_lds_dwordx4 v[196:197], off
	s_waitcnt lgkmcnt(8)
	s_setprio 1
	s_barrier
	s_waitcnt lgkmcnt(0)
	v_mfma_f32_16x16x32_bf16 v[140:143], v[92:95], v[148:151], 0
	v_mfma_f32_16x16x32_bf16 v[140:143], v[100:103], v[152:155], v[140:143]
	v_mfma_f32_16x16x32_bf16 v[128:131], v[92:95], v[176:179], 0
	v_mfma_f32_16x16x32_bf16 v[128:131], v[100:103], v[180:183], v[128:131]
	v_mfma_f32_16x16x32_bf16 v[120:123], v[92:95], v[184:187], 0
	v_mfma_f32_16x16x32_bf16 v[120:123], v[100:103], v[188:191], v[120:123]
	v_mfma_f32_16x16x32_bf16 v[112:115], v[92:95], v[192:195], 0
	v_mfma_f32_16x16x32_bf16 v[112:115], v[100:103], v[212:215], v[112:115]
	v_mfma_f32_16x16x32_bf16 v[136:139], v[132:135], v[148:151], 0
	v_mfma_f32_16x16x32_bf16 v[136:139], v[144:147], v[152:155], v[136:139]
	v_mfma_f32_16x16x32_bf16 v[124:127], v[132:135], v[176:179], 0
	v_mfma_f32_16x16x32_bf16 v[124:127], v[144:147], v[180:183], v[124:127]
	v_mfma_f32_16x16x32_bf16 v[116:119], v[132:135], v[184:187], 0
	v_mfma_f32_16x16x32_bf16 v[116:119], v[144:147], v[188:191], v[116:119]
	v_mfma_f32_16x16x32_bf16 v[108:111], v[132:135], v[192:195], 0
	v_mfma_f32_16x16x32_bf16 v[108:111], v[144:147], v[212:215], v[108:111]
	s_barrier
	s_setprio 0
	s_add_i32 s46, 0, 0x14000
	s_add_i32 s44, s44, s29
	v_add_u32_e32 v2, s46, v167
	v_lshl_add_u64 v[196:197], s[6:7], 0, v[158:159]
	s_mov_b32 m0, s44
	ds_read_b128 v[216:219], v2
	ds_read_b128 v[220:223], v2 offset:1024
	ds_read_b128 v[224:227], v2 offset:2048
	ds_read_b128 v[228:231], v2 offset:3072
	global_load_lds_dwordx4 v[196:197], off
	v_lshl_add_u64 v[232:233], s[6:7], 0, v[0:1]
	s_add_i32 m0, s44, 0x2000
	s_nop 0
	global_load_lds_dwordx4 v[232:233], off
	s_setprio 1
	s_barrier
	s_waitcnt lgkmcnt(0)
	v_mfma_f32_16x16x32_bf16 v[64:67], v[216:219], v[148:151], 0
	v_mfma_f32_16x16x32_bf16 v[64:67], v[220:223], v[152:155], v[64:67]
	v_mfma_f32_16x16x32_bf16 v[56:59], v[216:219], v[176:179], 0
	v_mfma_f32_16x16x32_bf16 v[56:59], v[220:223], v[180:183], v[56:59]
	v_mfma_f32_16x16x32_bf16 v[48:51], v[216:219], v[184:187], 0
	v_mfma_f32_16x16x32_bf16 v[48:51], v[220:223], v[188:191], v[48:51]
	v_mfma_f32_16x16x32_bf16 v[40:43], v[216:219], v[192:195], 0
	v_mfma_f32_16x16x32_bf16 v[40:43], v[220:223], v[212:215], v[40:43]
	v_mfma_f32_16x16x32_bf16 v[60:63], v[224:227], v[148:151], 0
	v_mfma_f32_16x16x32_bf16 v[60:63], v[228:231], v[152:155], v[60:63]
	v_mfma_f32_16x16x32_bf16 v[52:55], v[224:227], v[176:179], 0
	v_mfma_f32_16x16x32_bf16 v[52:55], v[228:231], v[180:183], v[52:55]
	v_mfma_f32_16x16x32_bf16 v[44:47], v[224:227], v[184:187], 0
	v_mfma_f32_16x16x32_bf16 v[44:47], v[228:231], v[188:191], v[44:47]
	v_mfma_f32_16x16x32_bf16 v[36:39], v[224:227], v[192:195], 0
	v_mfma_f32_16x16x32_bf16 v[36:39], v[228:231], v[212:215], v[36:39]
	s_mov_b32 m0, s30
	v_lshl_add_u64 v[234:235], s[10:11], 0, v[160:161]
	s_barrier
	s_setprio 0
	ds_read_b128 v[148:151], v169 offset:16384
	ds_read_b128 v[152:155], v169 offset:17408
	ds_read_b128 v[176:179], v169 offset:18432
	ds_read_b128 v[180:183], v169 offset:19456
	ds_read_b128 v[184:187], v169 offset:20480
	ds_read_b128 v[188:191], v169 offset:21504
	ds_read_b128 v[192:195], v169 offset:22528
	ds_read_b128 v[212:215], v169 offset:23552
	global_load_lds_dwordx4 v[234:235], off
	v_lshl_add_u64 v[236:237], s[10:11], 0, v[156:157]
	s_mov_b32 m0, s31
	s_nop 0
	global_load_lds_dwordx4 v[236:237], off
	s_setprio 1
	s_barrier
	s_waitcnt lgkmcnt(0)
	v_mfma_f32_16x16x32_bf16 v[104:107], v[92:95], v[148:151], 0
	v_mfma_f32_16x16x32_bf16 v[104:107], v[100:103], v[152:155], v[104:107]
	v_mfma_f32_16x16x32_bf16 v[88:91], v[92:95], v[176:179], 0
	v_mfma_f32_16x16x32_bf16 v[88:91], v[100:103], v[180:183], v[88:91]
	v_mfma_f32_16x16x32_bf16 v[80:83], v[92:95], v[184:187], 0
	v_mfma_f32_16x16x32_bf16 v[80:83], v[100:103], v[188:191], v[80:83]
	v_mfma_f32_16x16x32_bf16 v[72:75], v[92:95], v[192:195], 0
	v_mfma_f32_16x16x32_bf16 v[72:75], v[100:103], v[212:215], v[72:75]
	v_mfma_f32_16x16x32_bf16 v[96:99], v[132:135], v[148:151], 0
	v_mfma_f32_16x16x32_bf16 v[96:99], v[144:147], v[152:155], v[96:99]
	v_mfma_f32_16x16x32_bf16 v[84:87], v[132:135], v[176:179], 0
	v_mfma_f32_16x16x32_bf16 v[84:87], v[144:147], v[180:183], v[84:87]
	v_mfma_f32_16x16x32_bf16 v[76:79], v[132:135], v[184:187], 0
	v_mfma_f32_16x16x32_bf16 v[76:79], v[144:147], v[188:191], v[76:79]
	v_mfma_f32_16x16x32_bf16 v[68:71], v[132:135], v[192:195], 0
	v_mfma_f32_16x16x32_bf16 v[68:71], v[144:147], v[212:215], v[68:71]
	s_barrier
; #define PG8_WAIT_V(n) asm volatile("s_waitcnt vmcnt(" #n ")" ::: "memory")
; #define PG8_WAIT_L(n) asm volatile("s_waitcnt lgkmcnt(" #n ")" ::: "memory")
; #define PG8_BAR __builtin_amdgcn_s_barrier()
; #define PG8_SCHED __builtin_amdgcn_sched_barrier(0)
; template <class Epi, class AddrA, class AddrB>
; __device__ __forceinline__ void gemm_phase(const Sched S, const int lda, const int ldb, const int K, const AddrA addrA,
;                                            const AddrB addrB, const Epi E) {
;     ...
;       PG8_BAR; PG8_WAIT_L(0); PG8_MMA(1, 0, At, B0); PG8_BAR; PG8_SCHED;
;       PG8_STAGE(PG8_SB(0, 1), b2 + hstepB, voffB);
;       PG8_WAIT_V(6); PG8_BAR; PG8_MMA(1, 1, At, B1); PG8_BAR;
;       PG8_LDB(B0, 1, 0); PG8_SCHED; PG8_LDA(At, 1, 0); PG8_STAGE(PG8_SA(0, 1), a2 + hstepA, voffA);
;       PG8_WAIT_L(8); PG8_BAR; PG8_WAIT_L(0); PG8_MMA(0, 0, At, B0); PG8_BAR; PG8_SCHED;
;       PG8_LDB(B1, 1, 1); PG8_STAGE(PG8_SB(1, 0), b3, voffB);
;       PG8_BAR; PG8_WAIT_L(0); PG8_MMA(0, 1, At, B1); PG8_BAR;
;       PG8_LDA(At, 1, 1); PG8_STAGE(PG8_SA(1, 0), a3, voffA);
;       PG8_BAR; PG8_WAIT_L(0); PG8_MMA(1, 0, At, B0); PG8_BAR; PG8_SCHED;
	s_setprio 0
	s_add_u32 s44, s6, 0x20000
	s_addc_u32 s45, s7, 0
	s_add_i32 s46, s46, s29
	v_lshl_add_u64 v[92:93], s[44:45], 0, v[158:159]
	s_mov_b32 m0, s46
	s_nop 0
	global_load_lds_dwordx4 v[92:93], off
	v_lshl_add_u64 v[92:93], s[44:45], 0, v[0:1]
	s_add_i32 m0, s46, 0x2000
	s_nop 0
	global_load_lds_dwordx4 v[92:93], off
	s_waitcnt vmcnt(6)
	s_setprio 1
	s_barrier
	v_mfma_f32_16x16x32_bf16 v[32:35], v[216:219], v[148:151], 0
	v_mfma_f32_16x16x32_bf16 v[32:35], v[220:223], v[152:155], v[32:35]
	v_mfma_f32_16x16x32_bf16 v[24:27], v[216:219], v[176:179], 0
	v_mfma_f32_16x16x32_bf16 v[24:27], v[220:223], v[180:183], v[24:27]
	v_mfma_f32_16x16x32_bf16 v[16:19], v[216:219], v[184:187], 0
	v_mfma_f32_16x16x32_bf16 v[16:19], v[220:223], v[188:191], v[16:19]
	v_mfma_f32_16x16x32_bf16 v[8:11], v[216:219], v[192:195], 0
	v_mfma_f32_16x16x32_bf16 v[8:11], v[220:223], v[212:215], v[8:11]
	v_mfma_f32_16x16x32_bf16 v[28:31], v[224:227], v[148:151], 0
	v_mfma_f32_16x16x32_bf16 v[28:31], v[228:231], v[152:155], v[28:31]
	v_mfma_f32_16x16x32_bf16 v[20:23], v[224:227], v[176:179], 0
	v_mfma_f32_16x16x32_bf16 v[20:23], v[228:231], v[180:183], v[20:23]
	v_mfma_f32_16x16x32_bf16 v[12:15], v[224:227], v[184:187], 0
	v_mfma_f32_16x16x32_bf16 v[12:15], v[228:231], v[188:191], v[12:15]
	v_mfma_f32_16x16x32_bf16 v[4:7], v[224:227], v[192:195], 0
	v_mfma_f32_16x16x32_bf16 v[4:7], v[228:231], v[212:215], v[4:7]
	s_add_i32 s44, 0, 0x18000
	v_add_u32_e32 v2, s44, v167
	s_barrier
	s_setprio 0
	ds_read_b128 v[92:95], v2
	ds_read_b128 v[100:103], v2 offset:1024
	ds_read_b128 v[132:135], v2 offset:2048
	ds_read_b128 v[144:147], v2 offset:3072
	s_add_u32 s10, s10, 0x80000
	s_addc_u32 s11, s11, 0
	s_mov_b32 m0, s34
	v_lshl_add_u64 v[216:217], s[10:11], 0, v[160:161]
	ds_read_b128 v[148:151], v169 offset:32768
	ds_read_b128 v[152:155], v169 offset:33792
	ds_read_b128 v[176:179], v169 offset:34816
	ds_read_b128 v[180:183], v169 offset:35840
	ds_read_b128 v[184:187], v169 offset:36864
	ds_read_b128 v[188:191], v169 offset:37888
	ds_read_b128 v[192:195], v169 offset:38912
	ds_read_b128 v[212:215], v169 offset:39936
	global_load_lds_dwordx4 v[216:217], off
	v_lshl_add_u64 v[216:217], s[10:11], 0, v[156:157]
	s_mov_b32 m0, s35
	s_nop 0
	global_load_lds_dwordx4 v[216:217], off
	s_waitcnt lgkmcnt(8)
	s_setprio 1
	s_barrier
	s_waitcnt lgkmcnt(0)
	v_mfma_f32_16x16x32_bf16 v[140:143], v[92:95], v[148:151], v[140:143]
	v_mfma_f32_16x16x32_bf16 v[140:143], v[100:103], v[152:155], v[140:143]
	v_mfma_f32_16x16x32_bf16 v[128:131], v[92:95], v[176:179], v[128:131]
	v_mfma_f32_16x16x32_bf16 v[128:131], v[100:103], v[180:183], v[128:131]
	v_mfma_f32_16x16x32_bf16 v[120:123], v[92:95], v[184:187], v[120:123]
	v_mfma_f32_16x16x32_bf16 v[120:123], v[100:103], v[188:191], v[120:123]
	v_mfma_f32_16x16x32_bf16 v[112:115], v[92:95], v[192:195], v[112:115]
	v_mfma_f32_16x16x32_bf16 v[112:115], v[100:103], v[212:215], v[112:115]
	v_mfma_f32_16x16x32_bf16 v[136:139], v[132:135], v[148:151], v[136:139]
	v_mfma_f32_16x16x32_bf16 v[136:139], v[144:147], v[152:155], v[136:139]
	v_mfma_f32_16x16x32_bf16 v[124:127], v[132:135], v[176:179], v[124:127]
	v_mfma_f32_16x16x32_bf16 v[124:127], v[144:147], v[180:183], v[124:127]
	v_mfma_f32_16x16x32_bf16 v[116:119], v[132:135], v[184:187], v[116:119]
	v_mfma_f32_16x16x32_bf16 v[116:119], v[144:147], v[188:191], v[116:119]
	v_mfma_f32_16x16x32_bf16 v[108:111], v[132:135], v[192:195], v[108:111]
	v_mfma_f32_16x16x32_bf16 v[108:111], v[144:147], v[212:215], v[108:111]
	s_barrier
	s_setprio 0
	s_add_i32 s10, 0, 0x1c000
	s_add_i32 s11, s44, s29
	v_add_u32_e32 v2, s10, v167
	v_lshl_add_u64 v[196:197], v[196:197], 0, s[52:53]
	s_mov_b32 m0, s11
	ds_read_b128 v[216:219], v2
	ds_read_b128 v[220:223], v2 offset:1024
	ds_read_b128 v[224:227], v2 offset:2048
	ds_read_b128 v[228:231], v2 offset:3072
	global_load_lds_dwordx4 v[196:197], off
	v_lshl_add_u64 v[196:197], v[232:233], 0, s[52:53]
	s_add_i32 m0, s11, 0x2000
	s_nop 0
	global_load_lds_dwordx4 v[196:197], off
	s_setprio 1
	s_barrier
	s_waitcnt lgkmcnt(0)
	v_mfma_f32_16x16x32_bf16 v[64:67], v[216:219], v[148:151], v[64:67]
	v_mfma_f32_16x16x32_bf16 v[64:67], v[220:223], v[152:155], v[64:67]
	v_mfma_f32_16x16x32_bf16 v[56:59], v[216:219], v[176:179], v[56:59]
	v_mfma_f32_16x16x32_bf16 v[56:59], v[220:223], v[180:183], v[56:59]
	v_mfma_f32_16x16x32_bf16 v[48:51], v[216:219], v[184:187], v[48:51]
	v_mfma_f32_16x16x32_bf16 v[48:51], v[220:223], v[188:191], v[48:51]
	v_mfma_f32_16x16x32_bf16 v[40:43], v[216:219], v[192:195], v[40:43]
	v_mfma_f32_16x16x32_bf16 v[40:43], v[220:223], v[212:215], v[40:43]
	v_mfma_f32_16x16x32_bf16 v[60:63], v[224:227], v[148:151], v[60:63]
	v_mfma_f32_16x16x32_bf16 v[60:63], v[228:231], v[152:155], v[60:63]
	v_mfma_f32_16x16x32_bf16 v[52:55], v[224:227], v[176:179], v[52:55]
	v_mfma_f32_16x16x32_bf16 v[52:55], v[228:231], v[180:183], v[52:55]
	v_mfma_f32_16x16x32_bf16 v[44:47], v[224:227], v[184:187], v[44:47]
	v_mfma_f32_16x16x32_bf16 v[44:47], v[228:231], v[188:191], v[44:47]
	v_mfma_f32_16x16x32_bf16 v[36:39], v[224:227], v[192:195], v[36:39]
	v_mfma_f32_16x16x32_bf16 v[36:39], v[228:231], v[212:215], v[36:39]
	s_mov_b32 m0, s37
	v_lshl_add_u64 v[196:197], v[234:235], 0, s[52:53]
	s_barrier
	s_setprio 0
	ds_read_b128 v[148:151], v169 offset:49152
	ds_read_b128 v[152:155], v169 offset:50176
	ds_read_b128 v[176:179], v169 offset:51200
	ds_read_b128 v[180:183], v169 offset:52224
	ds_read_b128 v[184:187], v169 offset:53248
	ds_read_b128 v[188:191], v169 offset:54272
	ds_read_b128 v[192:195], v169 offset:55296
	ds_read_b128 v[212:215], v169 offset:56320
	global_load_lds_dwordx4 v[196:197], off
	v_lshl_add_u64 v[196:197], v[236:237], 0, s[52:53]
	s_mov_b32 m0, s38
	s_nop 0
	global_load_lds_dwordx4 v[196:197], off
	s_setprio 1
	s_barrier
; #define PG8_WAIT_V(n) asm volatile("s_waitcnt vmcnt(" #n ")" ::: "memory")
; #define PG8_WAIT_L(n) asm volatile("s_waitcnt lgkmcnt(" #n ")" ::: "memory")
; #define PG8_BAR __builtin_amdgcn_s_barrier()
; #define PG8_SCHED __builtin_amdgcn_sched_barrier(0)
; template <class Epi, class AddrA, class AddrB>
; __device__ __forceinline__ void gemm_phase(const Sched S, const int lda, const int ldb, const int K, const AddrA addrA,
;                                            const AddrB addrB, const Epi E) {
;     ...
;     for (int t = 0; t < nt; t += 2) {
;       const bool last = (t == nt - 2);
;       const char* a1 = cA + (size_t)(t + 1) * kstep;
;       const char* a2 = last ? nA : cA + (size_t)(t + 2) * kstep;
;       const char* b2 = last ? nB : cB + (size_t)(t + 2) * kstep;
;       const char* a3 = a2 + kstep;
;       const char* b3 = b2 + kstep;
;       PG8_LDB(B0, 0, 0); PG8_SCHED; PG8_LDA(At, 0, 0); PG8_STAGE(PG8_SA(1, 1), a1 + hstepA, voffA);
;       PG8_WAIT_L(8); PG8_BAR; PG8_WAIT_L(0); PG8_MMA(0, 0, At, B0); PG8_BAR; PG8_SCHED;
;       PG8_LDB(B1, 0, 1); PG8_STAGE(PG8_SB(0, 0), b2, voffB);
;       PG8_BAR; PG8_WAIT_L(0); PG8_MMA(0, 1, At, B1); PG8_BAR;
;     ...
;       PG8_BAR; PG8_WAIT_L(0); PG8_MMA(1, 0, At, B0); PG8_BAR; PG8_SCHED;
;       PG8_STAGE(PG8_SB(1, 1), b3 + hstepB, voffB);
;       PG8_WAIT_V(6); PG8_BAR; PG8_MMA(1, 1, At, B1); PG8_BAR;
	s_waitcnt lgkmcnt(0)
	v_mfma_f32_16x16x32_bf16 v[104:107], v[92:95], v[148:151], v[104:107]
	v_mfma_f32_16x16x32_bf16 v[104:107], v[100:103], v[152:155], v[104:107]
	v_mfma_f32_16x16x32_bf16 v[88:91], v[92:95], v[176:179], v[88:91]
	v_mfma_f32_16x16x32_bf16 v[88:91], v[100:103], v[180:183], v[88:91]
	v_mfma_f32_16x16x32_bf16 v[80:83], v[92:95], v[184:187], v[80:83]
	v_mfma_f32_16x16x32_bf16 v[80:83], v[100:103], v[188:191], v[80:83]
	v_mfma_f32_16x16x32_bf16 v[72:75], v[92:95], v[192:195], v[72:75]
	v_mfma_f32_16x16x32_bf16 v[72:75], v[100:103], v[212:215], v[72:75]
	v_mfma_f32_16x16x32_bf16 v[96:99], v[132:135], v[148:151], v[96:99]
	v_mfma_f32_16x16x32_bf16 v[96:99], v[144:147], v[152:155], v[96:99]
	v_mfma_f32_16x16x32_bf16 v[84:87], v[132:135], v[176:179], v[84:87]
	v_mfma_f32_16x16x32_bf16 v[84:87], v[144:147], v[180:183], v[84:87]
	v_mfma_f32_16x16x32_bf16 v[76:79], v[132:135], v[184:187], v[76:79]
	v_mfma_f32_16x16x32_bf16 v[76:79], v[144:147], v[188:191], v[76:79]
	v_mfma_f32_16x16x32_bf16 v[68:71], v[132:135], v[192:195], v[68:71]
	v_mfma_f32_16x16x32_bf16 v[68:71], v[144:147], v[212:215], v[68:71]
	s_barrier
	s_setprio 0
	s_add_u32 s6, s6, 0x20080
	s_addc_u32 s7, s7, 0
	s_add_i32 s10, s10, s29
	v_lshl_add_u64 v[92:93], s[6:7], 0, v[158:159]
	s_mov_b32 m0, s10
	s_nop 0
	global_load_lds_dwordx4 v[92:93], off
	v_lshl_add_u64 v[92:93], s[6:7], 0, v[0:1]
	s_add_i32 m0, s10, 0x2000
	s_nop 0
	global_load_lds_dwordx4 v[92:93], off
	s_waitcnt vmcnt(6)
	s_setprio 1
	s_barrier
	v_mfma_f32_16x16x32_bf16 v[32:35], v[216:219], v[148:151], v[32:35]
	v_mfma_f32_16x16x32_bf16 v[32:35], v[220:223], v[152:155], v[32:35]
	v_mfma_f32_16x16x32_bf16 v[24:27], v[216:219], v[176:179], v[24:27]
	v_mfma_f32_16x16x32_bf16 v[24:27], v[220:223], v[180:183], v[24:27]
	v_mfma_f32_16x16x32_bf16 v[16:19], v[216:219], v[184:187], v[16:19]
	v_mfma_f32_16x16x32_bf16 v[16:19], v[220:223], v[188:191], v[16:19]
	v_mfma_f32_16x16x32_bf16 v[8:11], v[216:219], v[192:195], v[8:11]
	v_mfma_f32_16x16x32_bf16 v[8:11], v[220:223], v[212:215], v[8:11]
	v_mfma_f32_16x16x32_bf16 v[28:31], v[224:227], v[148:151], v[28:31]
	v_mfma_f32_16x16x32_bf16 v[28:31], v[228:231], v[152:155], v[28:31]
	v_mfma_f32_16x16x32_bf16 v[20:23], v[224:227], v[176:179], v[20:23]
	v_mfma_f32_16x16x32_bf16 v[20:23], v[228:231], v[180:183], v[20:23]
	v_mfma_f32_16x16x32_bf16 v[12:15], v[224:227], v[184:187], v[12:15]
	v_mfma_f32_16x16x32_bf16 v[12:15], v[228:231], v[188:191], v[12:15]
	v_mfma_f32_16x16x32_bf16 v[4:7], v[224:227], v[192:195], v[4:7]
	v_mfma_f32_16x16x32_bf16 v[4:7], v[228:231], v[212:215], v[4:7]
	s_add_i32 s43, s43, 2
	s_add_u32 s41, s41, 0x100
	s_addc_u32 s42, s42, 0
	s_add_u32 s4, s4, 0x100
	s_addc_u32 s5, s5, 0
	s_cmp_gt_u32 s43, 5
	s_barrier
	s_setprio 0
.LBB0_485:
	s_add_u32 s6, s4, 0xfff80080
	s_addc_u32 s7, s5, -1
	s_add_i32 s44, 0, 0x10000
	v_add_u32_e32 v2, s44, v167
	ds_read_b128 v[92:95], v2
	ds_read_b128 v[100:103], v2 offset:1024
	ds_read_b128 v[132:135], v2 offset:2048
	ds_read_b128 v[144:147], v2 offset:3072
	s_cmp_eq_u32 s43, 4
	s_cselect_b32 s11, s3, s7
	s_cselect_b32 s10, s15, s6
	s_cselect_b32 s7, s17, s42
	s_cselect_b32 s6, s40, s41
	v_lshl_add_u64 v[196:197], s[4:5], 0, v[172:173]
	s_add_i32 m0, s30, 0xc000
	ds_read_b128 v[148:151], v169
	ds_read_b128 v[152:155], v169 offset:1024
	ds_read_b128 v[176:179], v169 offset:2048
	ds_read_b128 v[180:183], v169 offset:3072
	ds_read_b128 v[184:187], v169 offset:4096
	ds_read_b128 v[188:191], v169 offset:5120
	ds_read_b128 v[192:195], v169 offset:6144
	ds_read_b128 v[212:215], v169 offset:7168
	global_load_lds_dwordx4 v[196:197], off
	v_lshl_add_u64 v[196:197], s[4:5], 0, v[170:171]
	s_add_i32 m0, s30, 0xe000
	s_nop 0
	global_load_lds_dwordx4 v[196:197], off
	s_waitcnt lgkmcnt(8)
	s_setprio 1
	s_barrier
	s_waitcnt lgkmcnt(0)
	v_mfma_f32_16x16x32_bf16 v[140:143], v[92:95], v[148:151], v[140:143]
	v_mfma_f32_16x16x32_bf16 v[140:143], v[100:103], v[152:155], v[140:143]
	v_mfma_f32_16x16x32_bf16 v[128:131], v[92:95], v[176:179], v[128:131]
	v_mfma_f32_16x16x32_bf16 v[128:131], v[100:103], v[180:183], v[128:131]
	v_mfma_f32_16x16x32_bf16 v[120:123], v[92:95], v[184:187], v[120:123]
	v_mfma_f32_16x16x32_bf16 v[120:123], v[100:103], v[188:191], v[120:123]
	v_mfma_f32_16x16x32_bf16 v[112:115], v[92:95], v[192:195], v[112:115]
	v_mfma_f32_16x16x32_bf16 v[112:115], v[100:103], v[212:215], v[112:115]
	v_mfma_f32_16x16x32_bf16 v[136:139], v[132:135], v[148:151], v[136:139]
	v_mfma_f32_16x16x32_bf16 v[136:139], v[144:147], v[152:155], v[136:139]
	v_mfma_f32_16x16x32_bf16 v[124:127], v[132:135], v[176:179], v[124:127]
	v_mfma_f32_16x16x32_bf16 v[124:127], v[144:147], v[180:183], v[124:127]
	v_mfma_f32_16x16x32_bf16 v[116:119], v[132:135], v[184:187], v[116:119]
	v_mfma_f32_16x16x32_bf16 v[116:119], v[144:147], v[188:191], v[116:119]
	v_mfma_f32_16x16x32_bf16 v[108:111], v[132:135], v[192:195], v[108:111]
	v_mfma_f32_16x16x32_bf16 v[108:111], v[144:147], v[212:215], v[108:111]
	s_barrier
	s_setprio 0
	s_add_i32 s46, 0, 0x14000
	s_add_i32 s44, s44, s29
	v_add_u32_e32 v2, s46, v167
	v_lshl_add_u64 v[196:197], s[6:7], 0, v[158:159]
	s_mov_b32 m0, s44
	ds_read_b128 v[216:219], v2
	ds_read_b128 v[220:223], v2 offset:1024
	ds_read_b128 v[224:227], v2 offset:2048
	ds_read_b128 v[228:231], v2 offset:3072
	global_load_lds_dwordx4 v[196:197], off
	v_lshl_add_u64 v[232:233], s[6:7], 0, v[0:1]
	s_add_i32 m0, s44, 0x2000
	s_nop 0
	global_load_lds_dwordx4 v[232:233], off
	s_setprio 1
	s_barrier
; #define PG8_WAIT_V(n) asm volatile("s_waitcnt vmcnt(" #n ")" ::: "memory")
; #define PG8_WAIT_L(n) asm volatile("s_waitcnt lgkmcnt(" #n ")" ::: "memory")
; #define PG8_BAR __builtin_amdgcn_s_barrier()
; #define PG8_SCHED __builtin_amdgcn_sched_barrier(0)
; template <class Epi, class AddrA, class AddrB>
; __device__ __forceinline__ void gemm_phase(const Sched S, const int lda, const int ldb, const int K, const AddrA addrA,
;                                            const AddrB addrB, const Epi E) {
;     ...
;       PG8_WAIT_L(8); PG8_BAR; PG8_WAIT_L(0); PG8_MMA(0, 0, At, B0); PG8_BAR; PG8_SCHED;
;       PG8_LDB(B1, 0, 1); PG8_STAGE(PG8_SB(0, 0), b2, voffB);
;       PG8_BAR; PG8_WAIT_L(0); PG8_MMA(0, 1, At, B1); PG8_BAR;
;       PG8_LDA(At, 0, 1); PG8_STAGE(PG8_SA(0, 0), a2, voffA);
;       PG8_BAR; PG8_WAIT_L(0); PG8_MMA(1, 0, At, B0); PG8_BAR; PG8_SCHED;
;       PG8_STAGE(PG8_SB(0, 1), b2 + hstepB, voffB);
;       PG8_WAIT_V(6); PG8_BAR; PG8_MMA(1, 1, At, B1); PG8_BAR;
;       PG8_LDB(B0, 1, 0); PG8_SCHED; PG8_LDA(At, 1, 0); PG8_STAGE(PG8_SA(0, 1), a2 + hstepA, voffA);
;       PG8_WAIT_L(8); PG8_BAR; PG8_WAIT_L(0); PG8_MMA(0, 0, At, B0); PG8_BAR; PG8_SCHED;
;       PG8_LDB(B1, 1, 1); PG8_STAGE(PG8_SB(1, 0), b3, voffB);
;       PG8_BAR; PG8_WAIT_L(0); PG8_MMA(0, 1, At, B1); PG8_BAR;
;       PG8_LDA(At, 1, 1); PG8_STAGE(PG8_SA(1, 0), a3, voffA);
	s_waitcnt lgkmcnt(0)
	v_mfma_f32_16x16x32_bf16 v[64:67], v[216:219], v[148:151], v[64:67]
	v_mfma_f32_16x16x32_bf16 v[64:67], v[220:223], v[152:155], v[64:67]
	v_mfma_f32_16x16x32_bf16 v[56:59], v[216:219], v[176:179], v[56:59]
	v_mfma_f32_16x16x32_bf16 v[56:59], v[220:223], v[180:183], v[56:59]
	v_mfma_f32_16x16x32_bf16 v[48:51], v[216:219], v[184:187], v[48:51]
	v_mfma_f32_16x16x32_bf16 v[48:51], v[220:223], v[188:191], v[48:51]
	v_mfma_f32_16x16x32_bf16 v[40:43], v[216:219], v[192:195], v[40:43]
	v_mfma_f32_16x16x32_bf16 v[40:43], v[220:223], v[212:215], v[40:43]
	v_mfma_f32_16x16x32_bf16 v[60:63], v[224:227], v[148:151], v[60:63]
	v_mfma_f32_16x16x32_bf16 v[60:63], v[228:231], v[152:155], v[60:63]
	v_mfma_f32_16x16x32_bf16 v[52:55], v[224:227], v[176:179], v[52:55]
	v_mfma_f32_16x16x32_bf16 v[52:55], v[228:231], v[180:183], v[52:55]
	v_mfma_f32_16x16x32_bf16 v[44:47], v[224:227], v[184:187], v[44:47]
	v_mfma_f32_16x16x32_bf16 v[44:47], v[228:231], v[188:191], v[44:47]
	v_mfma_f32_16x16x32_bf16 v[36:39], v[224:227], v[192:195], v[36:39]
	v_mfma_f32_16x16x32_bf16 v[36:39], v[228:231], v[212:215], v[36:39]
	s_mov_b32 m0, s30
	v_lshl_add_u64 v[234:235], s[10:11], 0, v[160:161]
	s_barrier
	s_setprio 0
	ds_read_b128 v[148:151], v169 offset:16384
	ds_read_b128 v[152:155], v169 offset:17408
	ds_read_b128 v[176:179], v169 offset:18432
	ds_read_b128 v[180:183], v169 offset:19456
	ds_read_b128 v[184:187], v169 offset:20480
	ds_read_b128 v[188:191], v169 offset:21504
	ds_read_b128 v[192:195], v169 offset:22528
	ds_read_b128 v[212:215], v169 offset:23552
	global_load_lds_dwordx4 v[234:235], off
	v_lshl_add_u64 v[236:237], s[10:11], 0, v[156:157]
	s_mov_b32 m0, s31
	s_nop 0
	global_load_lds_dwordx4 v[236:237], off
	s_setprio 1
	s_barrier
	s_waitcnt lgkmcnt(0)
	v_mfma_f32_16x16x32_bf16 v[104:107], v[92:95], v[148:151], v[104:107]
	v_mfma_f32_16x16x32_bf16 v[104:107], v[100:103], v[152:155], v[104:107]
	v_mfma_f32_16x16x32_bf16 v[88:91], v[92:95], v[176:179], v[88:91]
	v_mfma_f32_16x16x32_bf16 v[88:91], v[100:103], v[180:183], v[88:91]
	v_mfma_f32_16x16x32_bf16 v[80:83], v[92:95], v[184:187], v[80:83]
	v_mfma_f32_16x16x32_bf16 v[80:83], v[100:103], v[188:191], v[80:83]
	v_mfma_f32_16x16x32_bf16 v[72:75], v[92:95], v[192:195], v[72:75]
	v_mfma_f32_16x16x32_bf16 v[72:75], v[100:103], v[212:215], v[72:75]
	v_mfma_f32_16x16x32_bf16 v[96:99], v[132:135], v[148:151], v[96:99]
	v_mfma_f32_16x16x32_bf16 v[96:99], v[144:147], v[152:155], v[96:99]
	v_mfma_f32_16x16x32_bf16 v[84:87], v[132:135], v[176:179], v[84:87]
	v_mfma_f32_16x16x32_bf16 v[84:87], v[144:147], v[180:183], v[84:87]
	v_mfma_f32_16x16x32_bf16 v[76:79], v[132:135], v[184:187], v[76:79]
	v_mfma_f32_16x16x32_bf16 v[76:79], v[144:147], v[188:191], v[76:79]
	v_mfma_f32_16x16x32_bf16 v[68:71], v[132:135], v[192:195], v[68:71]
	v_mfma_f32_16x16x32_bf16 v[68:71], v[144:147], v[212:215], v[68:71]
	s_barrier
	s_setprio 0
	s_add_u32 s44, s6, 0x20000
	s_addc_u32 s45, s7, 0
	s_add_i32 s46, s46, s29
	v_lshl_add_u64 v[92:93], s[44:45], 0, v[158:159]
	s_mov_b32 m0, s46
	s_nop 0
	global_load_lds_dwordx4 v[92:93], off
	v_lshl_add_u64 v[92:93], s[44:45], 0, v[0:1]
	s_add_i32 m0, s46, 0x2000
	s_nop 0
	global_load_lds_dwordx4 v[92:93], off
	s_waitcnt vmcnt(6)
	s_setprio 1
	s_barrier
	v_mfma_f32_16x16x32_bf16 v[32:35], v[216:219], v[148:151], v[32:35]
	v_mfma_f32_16x16x32_bf16 v[32:35], v[220:223], v[152:155], v[32:35]
	v_mfma_f32_16x16x32_bf16 v[24:27], v[216:219], v[176:179], v[24:27]
	v_mfma_f32_16x16x32_bf16 v[24:27], v[220:223], v[180:183], v[24:27]
	v_mfma_f32_16x16x32_bf16 v[16:19], v[216:219], v[184:187], v[16:19]
	v_mfma_f32_16x16x32_bf16 v[16:19], v[220:223], v[188:191], v[16:19]
	v_mfma_f32_16x16x32_bf16 v[8:11], v[216:219], v[192:195], v[8:11]
	v_mfma_f32_16x16x32_bf16 v[8:11], v[220:223], v[212:215], v[8:11]
	v_mfma_f32_16x16x32_bf16 v[28:31], v[224:227], v[148:151], v[28:31]
	v_mfma_f32_16x16x32_bf16 v[28:31], v[228:231], v[152:155], v[28:31]
	v_mfma_f32_16x16x32_bf16 v[20:23], v[224:227], v[176:179], v[20:23]
	v_mfma_f32_16x16x32_bf16 v[20:23], v[228:231], v[180:183], v[20:23]
	v_mfma_f32_16x16x32_bf16 v[12:15], v[224:227], v[184:187], v[12:15]
	v_mfma_f32_16x16x32_bf16 v[12:15], v[228:231], v[188:191], v[12:15]
	v_mfma_f32_16x16x32_bf16 v[4:7], v[224:227], v[192:195], v[4:7]
	v_mfma_f32_16x16x32_bf16 v[4:7], v[228:231], v[212:215], v[4:7]
	s_add_i32 s44, 0, 0x18000
	v_add_u32_e32 v2, s44, v167
	s_barrier
	s_setprio 0
	ds_read_b128 v[92:95], v2
	ds_read_b128 v[100:103], v2 offset:1024
	ds_read_b128 v[132:135], v2 offset:2048
	ds_read_b128 v[144:147], v2 offset:3072
	s_add_u32 s10, s10, 0x80000
	s_addc_u32 s11, s11, 0
	s_mov_b32 m0, s34
	v_lshl_add_u64 v[216:217], s[10:11], 0, v[160:161]
	ds_read_b128 v[148:151], v169 offset:32768
	ds_read_b128 v[152:155], v169 offset:33792
	ds_read_b128 v[176:179], v169 offset:34816
	ds_read_b128 v[180:183], v169 offset:35840
	ds_read_b128 v[184:187], v169 offset:36864
	ds_read_b128 v[188:191], v169 offset:37888
	ds_read_b128 v[192:195], v169 offset:38912
	ds_read_b128 v[212:215], v169 offset:39936
	global_load_lds_dwordx4 v[216:217], off
	v_lshl_add_u64 v[216:217], s[10:11], 0, v[156:157]
	s_mov_b32 m0, s35
	s_nop 0
	global_load_lds_dwordx4 v[216:217], off
	s_waitcnt lgkmcnt(8)
	s_setprio 1
	s_barrier
; #define PG8_WAIT_V(n) asm volatile("s_waitcnt vmcnt(" #n ")" ::: "memory")
; #define PG8_WAIT_L(n) asm volatile("s_waitcnt lgkmcnt(" #n ")" ::: "memory")
; #define PG8_BAR __builtin_amdgcn_s_barrier()
; #define PG8_SCHED __builtin_amdgcn_sched_barrier(0)
; template <class Epi, class AddrA, class AddrB>
; __device__ __forceinline__ void gemm_phase(const Sched S, const int lda, const int ldb, const int K, const AddrA addrA,
;                                            const AddrB addrB, const Epi E) {
;     ...
;       PG8_WAIT_L(8); PG8_BAR; PG8_WAIT_L(0); PG8_MMA(0, 0, At, B0); PG8_BAR; PG8_SCHED;
;       PG8_LDB(B1, 1, 1); PG8_STAGE(PG8_SB(1, 0), b3, voffB);
;       PG8_BAR; PG8_WAIT_L(0); PG8_MMA(0, 1, At, B1); PG8_BAR;
;       PG8_LDA(At, 1, 1); PG8_STAGE(PG8_SA(1, 0), a3, voffA);
;       PG8_BAR; PG8_WAIT_L(0); PG8_MMA(1, 0, At, B0); PG8_BAR; PG8_SCHED;
;       PG8_STAGE(PG8_SB(1, 1), b3 + hstepB, voffB);
;       PG8_WAIT_V(6); PG8_BAR; PG8_MMA(1, 1, At, B1); PG8_BAR;
	s_waitcnt lgkmcnt(0)
	v_mfma_f32_16x16x32_bf16 v[140:143], v[92:95], v[148:151], v[140:143]
	v_mfma_f32_16x16x32_bf16 v[140:143], v[100:103], v[152:155], v[140:143]
	v_mfma_f32_16x16x32_bf16 v[128:131], v[92:95], v[176:179], v[128:131]
	v_mfma_f32_16x16x32_bf16 v[128:131], v[100:103], v[180:183], v[128:131]
	v_mfma_f32_16x16x32_bf16 v[120:123], v[92:95], v[184:187], v[120:123]
	v_mfma_f32_16x16x32_bf16 v[120:123], v[100:103], v[188:191], v[120:123]
	v_mfma_f32_16x16x32_bf16 v[112:115], v[92:95], v[192:195], v[112:115]
	v_mfma_f32_16x16x32_bf16 v[112:115], v[100:103], v[212:215], v[112:115]
	v_mfma_f32_16x16x32_bf16 v[136:139], v[132:135], v[148:151], v[136:139]
	v_mfma_f32_16x16x32_bf16 v[136:139], v[144:147], v[152:155], v[136:139]
	v_mfma_f32_16x16x32_bf16 v[124:127], v[132:135], v[176:179], v[124:127]
	v_mfma_f32_16x16x32_bf16 v[124:127], v[144:147], v[180:183], v[124:127]
	v_mfma_f32_16x16x32_bf16 v[116:119], v[132:135], v[184:187], v[116:119]
	v_mfma_f32_16x16x32_bf16 v[116:119], v[144:147], v[188:191], v[116:119]
	v_mfma_f32_16x16x32_bf16 v[108:111], v[132:135], v[192:195], v[108:111]
	v_mfma_f32_16x16x32_bf16 v[108:111], v[144:147], v[212:215], v[108:111]
	s_barrier
	s_setprio 0
	s_add_i32 s10, 0, 0x1c000
	s_add_i32 s11, s44, s29
	v_add_u32_e32 v2, s10, v167
	v_lshl_add_u64 v[196:197], v[196:197], 0, s[52:53]
	s_mov_b32 m0, s11
	ds_read_b128 v[216:219], v2
	ds_read_b128 v[220:223], v2 offset:1024
	ds_read_b128 v[224:227], v2 offset:2048
	ds_read_b128 v[228:231], v2 offset:3072
	global_load_lds_dwordx4 v[196:197], off
	v_lshl_add_u64 v[196:197], v[232:233], 0, s[52:53]
	s_add_i32 m0, s11, 0x2000
	s_nop 0
	global_load_lds_dwordx4 v[196:197], off
	s_setprio 1
	s_barrier
	s_waitcnt lgkmcnt(0)
	v_mfma_f32_16x16x32_bf16 v[64:67], v[216:219], v[148:151], v[64:67]
	v_mfma_f32_16x16x32_bf16 v[64:67], v[220:223], v[152:155], v[64:67]
	v_mfma_f32_16x16x32_bf16 v[56:59], v[216:219], v[176:179], v[56:59]
	v_mfma_f32_16x16x32_bf16 v[56:59], v[220:223], v[180:183], v[56:59]
	v_mfma_f32_16x16x32_bf16 v[48:51], v[216:219], v[184:187], v[48:51]
	v_mfma_f32_16x16x32_bf16 v[48:51], v[220:223], v[188:191], v[48:51]
	v_mfma_f32_16x16x32_bf16 v[40:43], v[216:219], v[192:195], v[40:43]
	v_mfma_f32_16x16x32_bf16 v[40:43], v[220:223], v[212:215], v[40:43]
	v_mfma_f32_16x16x32_bf16 v[60:63], v[224:227], v[148:151], v[60:63]
	v_mfma_f32_16x16x32_bf16 v[60:63], v[228:231], v[152:155], v[60:63]
	v_mfma_f32_16x16x32_bf16 v[52:55], v[224:227], v[176:179], v[52:55]
	v_mfma_f32_16x16x32_bf16 v[52:55], v[228:231], v[180:183], v[52:55]
	v_mfma_f32_16x16x32_bf16 v[44:47], v[224:227], v[184:187], v[44:47]
	v_mfma_f32_16x16x32_bf16 v[44:47], v[228:231], v[188:191], v[44:47]
	v_mfma_f32_16x16x32_bf16 v[36:39], v[224:227], v[192:195], v[36:39]
	v_mfma_f32_16x16x32_bf16 v[36:39], v[228:231], v[212:215], v[36:39]
	s_mov_b32 m0, s37
	v_lshl_add_u64 v[196:197], v[234:235], 0, s[52:53]
	s_barrier
	s_setprio 0
	ds_read_b128 v[148:151], v169 offset:49152
	ds_read_b128 v[152:155], v169 offset:50176
	ds_read_b128 v[176:179], v169 offset:51200
	ds_read_b128 v[180:183], v169 offset:52224
	ds_read_b128 v[184:187], v169 offset:53248
	ds_read_b128 v[188:191], v169 offset:54272
	ds_read_b128 v[192:195], v169 offset:55296
	ds_read_b128 v[212:215], v169 offset:56320
	global_load_lds_dwordx4 v[196:197], off
	v_lshl_add_u64 v[196:197], v[236:237], 0, s[52:53]
	s_mov_b32 m0, s38
	s_nop 0
	global_load_lds_dwordx4 v[196:197], off
	s_setprio 1
	s_barrier
	s_waitcnt lgkmcnt(0)
	v_mfma_f32_16x16x32_bf16 v[104:107], v[92:95], v[148:151], v[104:107]
	v_mfma_f32_16x16x32_bf16 v[104:107], v[100:103], v[152:155], v[104:107]
	v_mfma_f32_16x16x32_bf16 v[88:91], v[92:95], v[176:179], v[88:91]
	v_mfma_f32_16x16x32_bf16 v[88:91], v[100:103], v[180:183], v[88:91]
	v_mfma_f32_16x16x32_bf16 v[80:83], v[92:95], v[184:187], v[80:83]
	v_mfma_f32_16x16x32_bf16 v[80:83], v[100:103], v[188:191], v[80:83]
	v_mfma_f32_16x16x32_bf16 v[72:75], v[92:95], v[192:195], v[72:75]
	v_mfma_f32_16x16x32_bf16 v[72:75], v[100:103], v[212:215], v[72:75]
	v_mfma_f32_16x16x32_bf16 v[96:99], v[132:135], v[148:151], v[96:99]
	v_mfma_f32_16x16x32_bf16 v[96:99], v[144:147], v[152:155], v[96:99]
	v_mfma_f32_16x16x32_bf16 v[84:87], v[132:135], v[176:179], v[84:87]
	v_mfma_f32_16x16x32_bf16 v[84:87], v[144:147], v[180:183], v[84:87]
	v_mfma_f32_16x16x32_bf16 v[76:79], v[132:135], v[184:187], v[76:79]
	v_mfma_f32_16x16x32_bf16 v[76:79], v[144:147], v[188:191], v[76:79]
	v_mfma_f32_16x16x32_bf16 v[68:71], v[132:135], v[192:195], v[68:71]
	v_mfma_f32_16x16x32_bf16 v[68:71], v[144:147], v[212:215], v[68:71]
	s_barrier
	s_setprio 0
	s_add_u32 s6, s6, 0x20080
	s_addc_u32 s7, s7, 0
	s_add_i32 s10, s10, s29
	v_lshl_add_u64 v[92:93], s[6:7], 0, v[158:159]
	s_mov_b32 m0, s10
	s_nop 0
	global_load_lds_dwordx4 v[92:93], off
	v_lshl_add_u64 v[92:93], s[6:7], 0, v[0:1]
	s_add_i32 m0, s10, 0x2000
	s_nop 0
	global_load_lds_dwordx4 v[92:93], off
	s_waitcnt vmcnt(6)
	s_setprio 1
	s_barrier
	v_mfma_f32_16x16x32_bf16 v[32:35], v[216:219], v[148:151], v[32:35]
	v_mfma_f32_16x16x32_bf16 v[32:35], v[220:223], v[152:155], v[32:35]
	v_mfma_f32_16x16x32_bf16 v[24:27], v[216:219], v[176:179], v[24:27]
	v_mfma_f32_16x16x32_bf16 v[24:27], v[220:223], v[180:183], v[24:27]
	v_mfma_f32_16x16x32_bf16 v[16:19], v[216:219], v[184:187], v[16:19]
	v_mfma_f32_16x16x32_bf16 v[16:19], v[220:223], v[188:191], v[16:19]
	v_mfma_f32_16x16x32_bf16 v[8:11], v[216:219], v[192:195], v[8:11]
	v_mfma_f32_16x16x32_bf16 v[8:11], v[220:223], v[212:215], v[8:11]
	v_mfma_f32_16x16x32_bf16 v[28:31], v[224:227], v[148:151], v[28:31]
	v_mfma_f32_16x16x32_bf16 v[28:31], v[228:231], v[152:155], v[28:31]
	v_mfma_f32_16x16x32_bf16 v[20:23], v[224:227], v[176:179], v[20:23]
	v_mfma_f32_16x16x32_bf16 v[20:23], v[228:231], v[180:183], v[20:23]
	v_mfma_f32_16x16x32_bf16 v[12:15], v[224:227], v[184:187], v[12:15]
	v_mfma_f32_16x16x32_bf16 v[12:15], v[228:231], v[188:191], v[12:15]
	v_mfma_f32_16x16x32_bf16 v[4:7], v[224:227], v[192:195], v[4:7]
	v_mfma_f32_16x16x32_bf16 v[4:7], v[228:231], v[212:215], v[4:7]
	s_add_i32 s43, s43, 2
	s_add_u32 s41, s41, 0x100
	s_addc_u32 s42, s42, 0
	s_add_u32 s4, s4, 0x100
	s_addc_u32 s5, s5, 0
	s_cmp_gt_u32 s43, 5
	s_barrier
; __device__ __forceinline__ size_t pidx(size_t row, int col) { return ((size_t)(col >> 8) * MTOK + row) * PLD + (col & 255); }
; __device__ __forceinline__ float bflo(unsigned v) { return __uint_as_float(v << 16); }
; __device__ __forceinline__ float bfhi(unsigned v) { return __uint_as_float(v & 0xffff0000u); }
; __device__ __forceinline__ float siluf_(float x) { return x * __builtin_amdgcn_rcpf(1.0f + __expf(-x)); }
;   __device__ __forceinline__ void operator()(EPI_ARGS) const {
;     const size_t row0 = (size_t)u.pm * 256 + wr * 64 + fr;
;     const int col0 = u.pn * 256 + wc * 32 + 8 * fq;
; #pragma unroll
;     for (int bj = 0; bj < 2; ++bj) {
;       const int c = col0 + bj * HALF;
;       const f32x4 s0 = *(const f32x4*)(psc + c), s1 = *(const f32x4*)(psc + c + 4);
; #pragma unroll
;       for (int ai = 0; ai < 2; ++ai) {
;         u32x4 z[4];
; #pragma unroll
;         for (int m = 0; m < 4; ++m) z[m] = *(const u32x4*)(proj + pidx(row0 + ai * HALF + m * 16, PZ + c));
;         __builtin_amdgcn_sched_barrier(0);
; #pragma unroll
;         for (int m = 0; m < 4; ++m) {
;           const size_t row = row0 + ai * HALF + m * 16;
;           const f32x4 v0 = acc[ai][bj][m][0], v1 = acc[ai][bj][m][1];
;           u32x4 o;
;           o.x = pack2(v0[0] * s0[0] * siluf_(bflo(z[m].x)), v0[1] * s0[1] * siluf_(bfhi(z[m].x)));
;           o.y = pack2(v0[2] * s0[2] * siluf_(bflo(z[m].y)), v0[3] * s0[3] * siluf_(bfhi(z[m].y)));
;           o.z = pack2(v1[0] * s1[0] * siluf_(bflo(z[m].z)), v1[1] * s1[1] * siluf_(bfhi(z[m].z)));
;           o.w = pack2(v1[2] * s1[2] * siluf_(bflo(z[m].w)), v1[3] * s1[3] * siluf_(bfhi(z[m].w)));
;           *(u32x4*)(y0 + row * DM + c) = o;
;         }
	s_setprio 0
	s_cbranch_scc0 .LBB0_485
	s_ashr_i32 s3, s2, 31
	s_lshl_b64 s[2:3], s[2:3], 8
	v_lshl_add_u64 v[186:187], s[2:3], 0, v[162:163]
	s_lshl_b32 s2, s33, 8
	v_or_b32_e32 v196, s2, v168
	s_addk_i32 s2, 0x800
	s_ashr_i32 s2, s2, 8
	s_ashr_i32 s3, s2, 31
	s_lshl_b64 s[2:3], s[2:3], 23
	s_add_u32 s2, s0, s2
	s_addc_u32 s3, s1, s3
	v_lshlrev_b32_e32 v2, 1, v168
	v_or_b32_e32 v194, 16, v186
	v_mov_b32_e32 v195, v187
	v_ashrrev_i32_e32 v197, 31, v196
	v_lshl_add_u64 v[188:189], s[2:3], 0, v[2:3]
	v_lshlrev_b64 v[178:179], 9, v[186:187]
	v_lshlrev_b64 v[180:181], 9, v[194:195]
	v_or_b32_e32 v192, 32, v186
	v_mov_b32_e32 v193, v187
	v_or_b32_e32 v190, 48, v186
	v_mov_b32_e32 v191, v187
	v_lshl_add_u64 v[176:177], v[196:197], 2, s[12:13]
	v_lshl_add_u64 v[132:133], v[188:189], 0, v[178:179]
	v_lshl_add_u64 v[134:135], v[188:189], 0, v[180:181]
	v_lshlrev_b64 v[182:183], 9, v[192:193]
	v_lshlrev_b64 v[184:185], 9, v[190:191]
	global_load_dwordx4 v[92:95], v[176:177], off offset:16
	global_load_dwordx4 v[100:103], v[176:177], off
	flat_load_dwordx4 v[152:155], v[132:133]
	flat_load_dwordx4 v[148:151], v[134:135]
	v_lshl_add_u64 v[132:133], v[188:189], 0, v[182:183]
	v_lshl_add_u64 v[134:135], v[188:189], 0, v[184:185]
	flat_load_dwordx4 v[144:147], v[132:133]
	s_nop 0
	flat_load_dwordx4 v[132:135], v[134:135]
	s_waitcnt vmcnt(0) lgkmcnt(0)
	v_lshlrev_b32_e32 v213, 16, v152
	v_mul_f32_e32 v2, 0xbfb8aa3b, v213
	v_exp_f32_e32 v2, v2
	v_mov_b32_e32 v214, v140
	v_mov_b32_e32 v212, v100
	s_mov_b64 s[4:5], 0x90
	v_add_f32_e32 v2, 1.0, v2
	v_rcp_f32_e32 v215, v2
	s_nop 0
	v_pk_mul_f32 v[212:213], v[214:215], v[212:213]
	s_nop 0
	v_mul_f32_e32 v2, v212, v213
	v_and_b32_e32 v213, 0xffff0000, v152
	v_mul_f32_e32 v140, 0xbfb8aa3b, v213
	v_exp_f32_e32 v140, v140
	v_mov_b32_e32 v214, v141
	v_mov_b32_e32 v212, v101
	v_add_f32_e32 v140, 1.0, v140
	v_rcp_f32_e32 v215, v140
	s_nop 0
	v_pk_mul_f32 v[140:141], v[214:215], v[212:213]
	s_nop 0
	v_mul_f32_e32 v140, v140, v141
	v_lshlrev_b32_e32 v141, 16, v153
	v_cvt_pk_bf16_f32 v152, v2, v140
	v_mul_f32_e32 v2, 0xbfb8aa3b, v141
	v_exp_f32_e32 v2, v2
	v_mov_b32_e32 v212, v142
	v_mov_b32_e32 v140, v102
	v_mov_b32_e32 v142, v136
	v_add_f32_e32 v2, 1.0, v2
	v_rcp_f32_e32 v213, v2
	s_nop 0
	v_pk_mul_f32 v[140:141], v[212:213], v[140:141]
	s_nop 0
	v_mul_f32_e32 v2, v140, v141
	v_and_b32_e32 v141, 0xffff0000, v153
	v_mul_f32_e32 v140, 0xbfb8aa3b, v141
	v_exp_f32_e32 v140, v140
	v_mov_b32_e32 v212, v143
	v_add_f32_e32 v140, 1.0, v140
	v_rcp_f32_e32 v213, v140
	v_mov_b32_e32 v140, v103
	v_pk_mul_f32 v[140:141], v[212:213], v[140:141]
	s_nop 0
	v_mul_f32_e32 v140, v140, v141
	v_lshlrev_b32_e32 v141, 16, v154
	v_cvt_pk_bf16_f32 v153, v2, v140
	v_mul_f32_e32 v2, 0xbfb8aa3b, v141
	v_exp_f32_e32 v2, v2
	v_mov_b32_e32 v140, v92
	v_add_f32_e32 v2, 1.0, v2
	v_rcp_f32_e32 v143, v2
	s_nop 0
	v_pk_mul_f32 v[140:141], v[142:143], v[140:141]
	s_nop 0
	v_mul_f32_e32 v2, v140, v141
	v_and_b32_e32 v141, 0xffff0000, v154
	v_mul_f32_e32 v136, 0xbfb8aa3b, v141
	v_exp_f32_e32 v136, v136
	v_mov_b32_e32 v142, v137
	v_mov_b32_e32 v140, v93
	v_add_f32_e32 v136, 1.0, v136
	v_rcp_f32_e32 v143, v136
	s_nop 0
	v_pk_mul_f32 v[136:137], v[142:143], v[140:141]
	s_nop 0
	v_mul_f32_e32 v136, v136, v137
	v_lshlrev_b32_e32 v137, 16, v155
	v_cvt_pk_bf16_f32 v154, v2, v136
	v_mul_f32_e32 v2, 0xbfb8aa3b, v137
	v_exp_f32_e32 v2, v2
	v_mov_b32_e32 v140, v138
	v_mov_b32_e32 v136, v94
	v_mov_b32_e32 v142, v128
	v_add_f32_e32 v2, 1.0, v2
	v_rcp_f32_e32 v141, v2
	v_mov_b32_e32 v138, v100
	v_pk_mul_f32 v[136:137], v[140:141], v[136:137]
	s_nop 0
	v_mul_f32_e32 v2, v136, v137
	v_and_b32_e32 v137, 0xffff0000, v155
	v_mul_f32_e32 v136, 0xbfb8aa3b, v137
	v_exp_f32_e32 v136, v136
	v_mov_b32_e32 v140, v139
	v_lshlrev_b32_e32 v139, 16, v148
	v_add_f32_e32 v136, 1.0, v136
	v_rcp_f32_e32 v141, v136
	v_mov_b32_e32 v136, v95
	v_pk_mul_f32 v[136:137], v[140:141], v[136:137]
	s_nop 0
	v_mul_f32_e32 v136, v136, v137
	v_cvt_pk_bf16_f32 v155, v2, v136
	v_mul_f32_e32 v2, 0xbfb8aa3b, v139
	v_exp_f32_e32 v2, v2
	v_lshlrev_b64 v[140:141], 1, v[196:197]
	v_lshlrev_b64 v[136:137], 12, v[186:187]
	v_lshl_add_u64 v[136:137], s[8:9], 0, v[136:137]
	v_add_f32_e32 v2, 1.0, v2
	v_rcp_f32_e32 v143, v2
	v_lshl_add_u64 v[136:137], v[136:137], 0, v[140:141]
	flat_store_dwordx4 v[136:137], v[152:155]
	v_pk_mul_f32 v[138:139], v[142:143], v[138:139]
	s_nop 0
	v_mul_f32_e32 v2, v138, v139
	v_and_b32_e32 v139, 0xffff0000, v148
	v_mul_f32_e32 v128, 0xbfb8aa3b, v139
	v_exp_f32_e32 v128, v128
	v_mov_b32_e32 v142, v129
	v_mov_b32_e32 v138, v101
	v_add_f32_e32 v128, 1.0, v128
	v_rcp_f32_e32 v143, v128
	s_nop 0
	v_pk_mul_f32 v[128:129], v[142:143], v[138:139]
	s_nop 0
	v_mul_f32_e32 v128, v128, v129
	v_lshlrev_b32_e32 v139, 16, v149
	v_cvt_pk_bf16_f32 v128, v2, v128
	v_mul_f32_e32 v2, 0xbfb8aa3b, v139
	v_exp_f32_e32 v2, v2
	v_mov_b32_e32 v142, v130
	v_mov_b32_e32 v138, v102
	v_add_f32_e32 v2, 1.0, v2
	v_rcp_f32_e32 v143, v2
	s_nop 0
	v_pk_mul_f32 v[138:139], v[142:143], v[138:139]
	s_nop 0
	v_mul_f32_e32 v2, v138, v139
	v_and_b32_e32 v139, 0xffff0000, v149
	v_mul_f32_e32 v129, 0xbfb8aa3b, v139
	v_exp_f32_e32 v129, v129
	v_mov_b32_e32 v142, v131
	v_mov_b32_e32 v138, v103
	v_lshl_add_u64 v[148:149], v[186:187], 0, s[52:53]
	v_add_f32_e32 v129, 1.0, v129
	v_rcp_f32_e32 v143, v129
	s_nop 0
	v_pk_mul_f32 v[130:131], v[142:143], v[138:139]
	s_nop 0
	v_mul_f32_e32 v129, v130, v131
	v_lshlrev_b32_e32 v131, 16, v150
	v_cvt_pk_bf16_f32 v129, v2, v129
	v_mul_f32_e32 v2, 0xbfb8aa3b, v131
	v_exp_f32_e32 v2, v2
	v_mov_b32_e32 v138, v124
	v_mov_b32_e32 v130, v92
	v_add_f32_e32 v2, 1.0, v2
	v_rcp_f32_e32 v139, v2
	s_nop 0
; __device__ __forceinline__ float bflo(unsigned v) { return __uint_as_float(v << 16); }
; __device__ __forceinline__ float bfhi(unsigned v) { return __uint_as_float(v & 0xffff0000u); }
; __device__ __forceinline__ float siluf_(float x) { return x * __builtin_amdgcn_rcpf(1.0f + __expf(-x)); }
;   __device__ __forceinline__ void operator()(EPI_ARGS) const {
;     ...
;         for (int m = 0; m < 4; ++m) {
;           const size_t row = row0 + ai * HALF + m * 16;
;           const f32x4 v0 = acc[ai][bj][m][0], v1 = acc[ai][bj][m][1];
;           u32x4 o;
;           o.x = pack2(v0[0] * s0[0] * siluf_(bflo(z[m].x)), v0[1] * s0[1] * siluf_(bfhi(z[m].x)));
;           o.y = pack2(v0[2] * s0[2] * siluf_(bflo(z[m].y)), v0[3] * s0[3] * siluf_(bfhi(z[m].y)));
;           o.z = pack2(v1[0] * s1[0] * siluf_(bflo(z[m].z)), v1[1] * s1[1] * siluf_(bfhi(z[m].z)));
;           o.w = pack2(v1[2] * s1[2] * siluf_(bflo(z[m].w)), v1[3] * s1[3] * siluf_(bfhi(z[m].w)));
;           *(u32x4*)(y0 + row * DM + c) = o;
;         }
	v_pk_mul_f32 v[130:131], v[138:139], v[130:131]
	s_nop 0
	v_mul_f32_e32 v2, v130, v131
	v_and_b32_e32 v131, 0xffff0000, v150
	v_mul_f32_e32 v124, 0xbfb8aa3b, v131
	v_exp_f32_e32 v124, v124
	v_mov_b32_e32 v138, v125
	v_mov_b32_e32 v130, v93
	v_add_f32_e32 v124, 1.0, v124
	v_rcp_f32_e32 v139, v124
	s_nop 0
	v_pk_mul_f32 v[124:125], v[138:139], v[130:131]
	s_nop 0
	v_mul_f32_e32 v124, v124, v125
	v_lshlrev_b32_e32 v125, 16, v151
	v_cvt_pk_bf16_f32 v130, v2, v124
	v_mul_f32_e32 v2, 0xbfb8aa3b, v125
	v_exp_f32_e32 v2, v2
	v_mov_b32_e32 v138, v126
	v_mov_b32_e32 v124, v94
	v_mov_b32_e32 v126, v100
	v_add_f32_e32 v2, 1.0, v2
	v_rcp_f32_e32 v139, v2
	s_nop 0
	v_pk_mul_f32 v[124:125], v[138:139], v[124:125]
	s_nop 0
	v_mul_f32_e32 v2, v124, v125
	v_and_b32_e32 v125, 0xffff0000, v151
	v_mul_f32_e32 v124, 0xbfb8aa3b, v125
	v_exp_f32_e32 v124, v124
	v_mov_b32_e32 v138, v127
	v_lshlrev_b32_e32 v127, 16, v144
	v_add_f32_e32 v124, 1.0, v124
	v_rcp_f32_e32 v139, v124
	v_mov_b32_e32 v124, v95
	v_pk_mul_f32 v[124:125], v[138:139], v[124:125]
	s_nop 0
	v_mul_f32_e32 v124, v124, v125
	v_cvt_pk_bf16_f32 v131, v2, v124
	v_mul_f32_e32 v2, 0xbfb8aa3b, v127
	v_exp_f32_e32 v2, v2
	v_lshlrev_b64 v[124:125], 12, v[194:195]
	v_lshl_add_u64 v[124:125], s[8:9], 0, v[124:125]
	v_lshl_add_u64 v[124:125], v[124:125], 0, v[140:141]
	v_add_f32_e32 v2, 1.0, v2
	flat_store_dwordx4 v[124:125], v[128:131]
	s_nop 1
	v_rcp_f32_e32 v129, v2
	v_mov_b32_e32 v128, v120
	v_lshlrev_b64 v[130:131], 9, v[148:149]
	v_pk_mul_f32 v[126:127], v[128:129], v[126:127]
	s_nop 0
	v_mul_f32_e32 v2, v126, v127
	v_and_b32_e32 v127, 0xffff0000, v144
	v_mul_f32_e32 v120, 0xbfb8aa3b, v127
	v_exp_f32_e32 v120, v120
	v_mov_b32_e32 v128, v121
	v_mov_b32_e32 v126, v101
	v_add_f32_e32 v120, 1.0, v120
	v_rcp_f32_e32 v129, v120
	s_nop 0
	v_pk_mul_f32 v[120:121], v[128:129], v[126:127]
	s_nop 0
	v_mul_f32_e32 v120, v120, v121
	v_lshlrev_b32_e32 v127, 16, v145
	v_cvt_pk_bf16_f32 v120, v2, v120
	v_mul_f32_e32 v2, 0xbfb8aa3b, v127
	v_exp_f32_e32 v2, v2
	v_mov_b32_e32 v128, v122
	v_mov_b32_e32 v126, v102
	v_add_f32_e32 v2, 1.0, v2
	v_rcp_f32_e32 v129, v2
	s_nop 0
	v_pk_mul_f32 v[126:127], v[128:129], v[126:127]
	s_nop 0
	v_mul_f32_e32 v2, v126, v127
	v_and_b32_e32 v127, 0xffff0000, v145
	v_mul_f32_e32 v121, 0xbfb8aa3b, v127
	v_exp_f32_e32 v121, v121
	v_mov_b32_e32 v128, v123
	v_mov_b32_e32 v126, v103
	v_add_f32_e32 v121, 1.0, v121
	v_rcp_f32_e32 v129, v121
	s_nop 0
	v_pk_mul_f32 v[122:123], v[128:129], v[126:127]
	s_nop 0
	v_mul_f32_e32 v121, v122, v123
	v_lshlrev_b32_e32 v123, 16, v146
	v_cvt_pk_bf16_f32 v121, v2, v121
	v_mul_f32_e32 v2, 0xbfb8aa3b, v123
	v_exp_f32_e32 v2, v2
	v_mov_b32_e32 v126, v116
	v_mov_b32_e32 v122, v92
	v_add_f32_e32 v2, 1.0, v2
	v_rcp_f32_e32 v127, v2
	s_nop 0
	v_pk_mul_f32 v[122:123], v[126:127], v[122:123]
	s_nop 0
	v_mul_f32_e32 v2, v122, v123
	v_and_b32_e32 v123, 0xffff0000, v146
	v_mul_f32_e32 v116, 0xbfb8aa3b, v123
	v_exp_f32_e32 v116, v116
	v_mov_b32_e32 v126, v117
	v_mov_b32_e32 v122, v93
	v_add_f32_e32 v116, 1.0, v116
	v_rcp_f32_e32 v127, v116
	s_nop 0
	v_pk_mul_f32 v[116:117], v[126:127], v[122:123]
	s_nop 0
	v_mul_f32_e32 v116, v116, v117
	v_lshlrev_b32_e32 v117, 16, v147
	v_cvt_pk_bf16_f32 v122, v2, v116
	v_mul_f32_e32 v2, 0xbfb8aa3b, v117
	v_exp_f32_e32 v2, v2
	v_mov_b32_e32 v126, v118
	v_mov_b32_e32 v116, v94
	v_mov_b32_e32 v118, v112
	v_add_f32_e32 v2, 1.0, v2
	v_rcp_f32_e32 v127, v2
	s_nop 0
	v_pk_mul_f32 v[116:117], v[126:127], v[116:117]
	s_nop 0
	v_mul_f32_e32 v2, v116, v117
	v_and_b32_e32 v117, 0xffff0000, v147
	v_mul_f32_e32 v116, 0xbfb8aa3b, v117
	v_exp_f32_e32 v116, v116
	v_mov_b32_e32 v126, v119
	v_lshl_add_u64 v[146:147], v[186:187], 0, s[4:5]
	s_mov_b64 s[4:5], 0xa0
	v_add_f32_e32 v116, 1.0, v116
	v_rcp_f32_e32 v127, v116
	v_mov_b32_e32 v116, v95
	v_lshl_add_u64 v[144:145], v[186:187], 0, s[4:5]
	s_mov_b64 s[4:5], 0xb0
	v_pk_mul_f32 v[116:117], v[126:127], v[116:117]
	v_lshl_add_u64 v[142:143], v[186:187], 0, s[4:5]
	v_mul_f32_e32 v116, v116, v117
	v_cvt_pk_bf16_f32 v123, v2, v116
	v_lshlrev_b64 v[116:117], 12, v[192:193]
	v_lshl_add_u64 v[116:117], s[8:9], 0, v[116:117]
	v_lshl_add_u64 v[128:129], v[116:117], 0, v[140:141]
	v_lshlrev_b32_e32 v117, 16, v132
	v_mul_f32_e32 v2, 0xbfb8aa3b, v117
	v_exp_f32_e32 v2, v2
	v_mov_b32_e32 v116, v100
	flat_store_dwordx4 v[128:129], v[120:123]
	v_lshlrev_b64 v[138:139], 9, v[142:143]
	v_add_f32_e32 v2, 1.0, v2
	v_rcp_f32_e32 v119, v2
	s_nop 0
	v_pk_mul_f32 v[116:117], v[118:119], v[116:117]
	s_nop 0
	v_mul_f32_e32 v2, v116, v117
	v_and_b32_e32 v117, 0xffff0000, v132
	v_mul_f32_e32 v112, 0xbfb8aa3b, v117
	v_exp_f32_e32 v112, v112
	v_mov_b32_e32 v118, v113
	v_mov_b32_e32 v116, v101
	v_add_f32_e32 v112, 1.0, v112
	v_rcp_f32_e32 v119, v112
	s_nop 0
	v_pk_mul_f32 v[112:113], v[118:119], v[116:117]
	s_nop 0
	v_mul_f32_e32 v112, v112, v113
	v_lshlrev_b32_e32 v117, 16, v133
	v_cvt_pk_bf16_f32 v112, v2, v112
	v_mul_f32_e32 v2, 0xbfb8aa3b, v117
	v_exp_f32_e32 v2, v2
	v_mov_b32_e32 v118, v114
	v_mov_b32_e32 v116, v102
	v_add_f32_e32 v2, 1.0, v2
	v_rcp_f32_e32 v119, v2
	s_nop 0
	v_pk_mul_f32 v[116:117], v[118:119], v[116:117]
	s_nop 0
	v_mul_f32_e32 v2, v116, v117
	v_and_b32_e32 v117, 0xffff0000, v133
	v_mul_f32_e32 v113, 0xbfb8aa3b, v117
	v_exp_f32_e32 v113, v113
	v_mov_b32_e32 v118, v115
	v_mov_b32_e32 v116, v103
	v_lshlrev_b64 v[132:133], 9, v[146:147]
	v_add_f32_e32 v113, 1.0, v113
	v_rcp_f32_e32 v119, v113
	s_nop 0
	v_pk_mul_f32 v[114:115], v[118:119], v[116:117]
	s_nop 0
	v_mul_f32_e32 v113, v114, v115
	v_lshlrev_b32_e32 v115, 16, v134
	v_cvt_pk_bf16_f32 v113, v2, v113
	v_mul_f32_e32 v2, 0xbfb8aa3b, v115
	v_exp_f32_e32 v2, v2
; __device__ __forceinline__ size_t pidx(size_t row, int col) { return ((size_t)(col >> 8) * MTOK + row) * PLD + (col & 255); }
; __device__ __forceinline__ float bflo(unsigned v) { return __uint_as_float(v << 16); }
; __device__ __forceinline__ float bfhi(unsigned v) { return __uint_as_float(v & 0xffff0000u); }
; __device__ __forceinline__ float siluf_(float x) { return x * __builtin_amdgcn_rcpf(1.0f + __expf(-x)); }
;   __device__ __forceinline__ void operator()(EPI_ARGS) const {
;     ...
;       for (int ai = 0; ai < 2; ++ai) {
;         u32x4 z[4];
; #pragma unroll
;         for (int m = 0; m < 4; ++m) z[m] = *(const u32x4*)(proj + pidx(row0 + ai * HALF + m * 16, PZ + c));
;         __builtin_amdgcn_sched_barrier(0);
; #pragma unroll
;         for (int m = 0; m < 4; ++m) {
;           const size_t row = row0 + ai * HALF + m * 16;
;           const f32x4 v0 = acc[ai][bj][m][0], v1 = acc[ai][bj][m][1];
;           u32x4 o;
;           o.x = pack2(v0[0] * s0[0] * siluf_(bflo(z[m].x)), v0[1] * s0[1] * siluf_(bfhi(z[m].x)));
;           o.y = pack2(v0[2] * s0[2] * siluf_(bflo(z[m].y)), v0[3] * s0[3] * siluf_(bfhi(z[m].y)));
;           o.z = pack2(v1[0] * s1[0] * siluf_(bflo(z[m].z)), v1[1] * s1[1] * siluf_(bfhi(z[m].z)));
;           o.w = pack2(v1[2] * s1[2] * siluf_(bflo(z[m].w)), v1[3] * s1[3] * siluf_(bfhi(z[m].w)));
;           *(u32x4*)(y0 + row * DM + c) = o;
;         }
	v_mov_b32_e32 v116, v108
	v_mov_b32_e32 v114, v92
	v_add_f32_e32 v2, 1.0, v2
	v_rcp_f32_e32 v117, v2
	s_nop 0
	v_pk_mul_f32 v[114:115], v[116:117], v[114:115]
	s_nop 0
	v_mul_f32_e32 v2, v114, v115
	v_and_b32_e32 v115, 0xffff0000, v134
	v_mul_f32_e32 v108, 0xbfb8aa3b, v115
	v_exp_f32_e32 v108, v108
	v_mov_b32_e32 v116, v109
	v_mov_b32_e32 v114, v93
	v_add_f32_e32 v108, 1.0, v108
	v_rcp_f32_e32 v117, v108
	s_nop 0
	v_pk_mul_f32 v[108:109], v[116:117], v[114:115]
	s_nop 0
	v_mul_f32_e32 v108, v108, v109
	v_lshlrev_b32_e32 v109, 16, v135
	v_cvt_pk_bf16_f32 v114, v2, v108
	v_mul_f32_e32 v2, 0xbfb8aa3b, v109
	v_exp_f32_e32 v2, v2
	v_mov_b32_e32 v116, v110
	v_mov_b32_e32 v108, v94
	v_add_f32_e32 v2, 1.0, v2
	v_rcp_f32_e32 v117, v2
	s_nop 0
	v_pk_mul_f32 v[108:109], v[116:117], v[108:109]
	s_nop 0
	v_mul_f32_e32 v2, v108, v109
	v_and_b32_e32 v109, 0xffff0000, v135
	v_mul_f32_e32 v108, 0xbfb8aa3b, v109
	v_exp_f32_e32 v108, v108
	v_mov_b32_e32 v116, v111
	v_lshlrev_b64 v[134:135], 9, v[144:145]
	v_add_f32_e32 v108, 1.0, v108
	v_rcp_f32_e32 v117, v108
	v_mov_b32_e32 v108, v95
	v_pk_mul_f32 v[108:109], v[116:117], v[108:109]
	s_nop 0
	v_mul_f32_e32 v108, v108, v109
	v_cvt_pk_bf16_f32 v115, v2, v108
	v_lshlrev_b64 v[108:109], 12, v[190:191]
	v_lshl_add_u64 v[108:109], s[8:9], 0, v[108:109]
	v_lshl_add_u64 v[126:127], v[108:109], 0, v[140:141]
	flat_store_dwordx4 v[126:127], v[112:115]
	v_lshl_add_u64 v[108:109], v[188:189], 0, v[130:131]
	flat_load_dwordx4 v[120:123], v[108:109]
	v_lshl_add_u64 v[108:109], v[188:189], 0, v[132:133]
	flat_load_dwordx4 v[116:119], v[108:109]
	v_lshl_add_u64 v[108:109], v[188:189], 0, v[134:135]
	flat_load_dwordx4 v[112:115], v[108:109]
	v_lshl_add_u64 v[108:109], v[188:189], 0, v[138:139]
	flat_load_dwordx4 v[108:111], v[108:109]
	s_waitcnt vmcnt(0) lgkmcnt(0)
	v_lshlrev_b32_e32 v151, 16, v120
	v_mul_f32_e32 v2, 0xbfb8aa3b, v151
	v_exp_f32_e32 v2, v2
	v_mov_b32_e32 v152, v104
	v_mov_b32_e32 v150, v100
	v_mov_b32_e32 v175, v3
	v_add_f32_e32 v2, 1.0, v2
	v_rcp_f32_e32 v153, v2
	s_nop 0
	v_pk_mul_f32 v[150:151], v[152:153], v[150:151]
	s_nop 0
	v_mul_f32_e32 v2, v150, v151
	v_and_b32_e32 v151, 0xffff0000, v120
	v_mul_f32_e32 v104, 0xbfb8aa3b, v151
	v_exp_f32_e32 v104, v104
	v_mov_b32_e32 v152, v105
	v_mov_b32_e32 v150, v101
	v_mov_b32_e32 v120, v103
	v_add_f32_e32 v104, 1.0, v104
	v_rcp_f32_e32 v153, v104
	s_nop 0
	v_pk_mul_f32 v[104:105], v[152:153], v[150:151]
	s_nop 0
	v_mul_f32_e32 v104, v104, v105
	v_lshlrev_b32_e32 v151, 16, v121
	v_cvt_pk_bf16_f32 v104, v2, v104
	v_mul_f32_e32 v2, 0xbfb8aa3b, v151
	v_exp_f32_e32 v2, v2
	v_and_b32_e32 v121, 0xffff0000, v121
	v_mul_f32_e32 v105, 0xbfb8aa3b, v121
	v_exp_f32_e32 v105, v105
	v_add_f32_e32 v2, 1.0, v2
	v_rcp_f32_e32 v153, v2
	v_mov_b32_e32 v152, v106
	v_mov_b32_e32 v150, v102
	v_add_f32_e32 v105, 1.0, v105
	v_pk_mul_f32 v[150:151], v[152:153], v[150:151]
	s_nop 0
	v_mul_f32_e32 v2, v150, v151
	v_rcp_f32_e32 v151, v105
	v_mov_b32_e32 v150, v107
	v_pk_mul_f32 v[106:107], v[150:151], v[120:121]
	s_nop 0
	v_mul_f32_e32 v105, v106, v107
	v_lshlrev_b32_e32 v107, 16, v122
	v_cvt_pk_bf16_f32 v105, v2, v105
	v_mul_f32_e32 v2, 0xbfb8aa3b, v107
	v_exp_f32_e32 v2, v2
	v_mov_b32_e32 v120, v96
	v_mov_b32_e32 v106, v92
	v_add_f32_e32 v2, 1.0, v2
	v_rcp_f32_e32 v121, v2
	s_nop 0
	v_pk_mul_f32 v[106:107], v[120:121], v[106:107]
	s_nop 0
	v_mul_f32_e32 v2, v106, v107
	v_and_b32_e32 v107, 0xffff0000, v122
	v_mul_f32_e32 v96, 0xbfb8aa3b, v107
	v_exp_f32_e32 v96, v96
	v_mov_b32_e32 v120, v97
	v_mov_b32_e32 v106, v93
	v_add_f32_e32 v96, 1.0, v96
	v_rcp_f32_e32 v121, v96
	s_nop 0
	v_pk_mul_f32 v[96:97], v[120:121], v[106:107]
	s_nop 0
	v_mul_f32_e32 v96, v96, v97
	v_lshlrev_b32_e32 v97, 16, v123
	v_cvt_pk_bf16_f32 v106, v2, v96
	v_mul_f32_e32 v2, 0xbfb8aa3b, v97
	v_exp_f32_e32 v2, v2
	v_mov_b32_e32 v120, v98
	v_mov_b32_e32 v96, v94
	v_mov_b32_e32 v98, v100
	v_add_f32_e32 v2, 1.0, v2
	v_rcp_f32_e32 v121, v2
	s_nop 0
	v_pk_mul_f32 v[96:97], v[120:121], v[96:97]
	s_nop 0
	v_mul_f32_e32 v2, v96, v97
	v_and_b32_e32 v97, 0xffff0000, v123
	v_mul_f32_e32 v96, 0xbfb8aa3b, v97
	v_exp_f32_e32 v96, v96
	v_mov_b32_e32 v120, v99
	v_lshlrev_b32_e32 v99, 16, v116
	v_add_f32_e32 v96, 1.0, v96
	v_rcp_f32_e32 v121, v96
	v_mov_b32_e32 v96, v95
	v_pk_mul_f32 v[96:97], v[120:121], v[96:97]
	s_nop 0
	v_mul_f32_e32 v96, v96, v97
	v_cvt_pk_bf16_f32 v107, v2, v96
	v_mul_f32_e32 v2, 0xbfb8aa3b, v99
	v_exp_f32_e32 v2, v2
	v_lshlrev_b64 v[96:97], 12, v[148:149]
	v_lshl_add_u64 v[96:97], s[8:9], 0, v[96:97]
	v_lshl_add_u64 v[96:97], v[96:97], 0, v[140:141]
	v_add_f32_e32 v2, 1.0, v2
	flat_store_dwordx4 v[96:97], v[104:107]
	s_nop 1
	v_rcp_f32_e32 v105, v2
	v_mov_b32_e32 v104, v88
	v_pk_mul_f32 v[98:99], v[104:105], v[98:99]
	s_nop 0
	v_mul_f32_e32 v2, v98, v99
	v_and_b32_e32 v99, 0xffff0000, v116
	v_mul_f32_e32 v88, 0xbfb8aa3b, v99
	v_exp_f32_e32 v88, v88
	v_mov_b32_e32 v104, v89
	v_mov_b32_e32 v98, v101
	v_add_f32_e32 v88, 1.0, v88
	v_rcp_f32_e32 v105, v88
	s_nop 0
	v_pk_mul_f32 v[88:89], v[104:105], v[98:99]
	s_nop 0
	v_mul_f32_e32 v88, v88, v89
	v_lshlrev_b32_e32 v99, 16, v117
	v_cvt_pk_bf16_f32 v88, v2, v88
	v_mul_f32_e32 v2, 0xbfb8aa3b, v99
	v_exp_f32_e32 v2, v2
	v_mov_b32_e32 v104, v90
	v_mov_b32_e32 v98, v102
	v_add_f32_e32 v2, 1.0, v2
	v_rcp_f32_e32 v105, v2
	s_nop 0
	v_pk_mul_f32 v[98:99], v[104:105], v[98:99]
	s_nop 0
	v_mul_f32_e32 v2, v98, v99
	v_and_b32_e32 v99, 0xffff0000, v117
	v_mul_f32_e32 v89, 0xbfb8aa3b, v99
	v_exp_f32_e32 v89, v89
	v_mov_b32_e32 v104, v91
	v_mov_b32_e32 v98, v103
	v_add_f32_e32 v89, 1.0, v89
	v_rcp_f32_e32 v105, v89
	s_nop 0
	v_pk_mul_f32 v[90:91], v[104:105], v[98:99]
	s_nop 0
; __device__ __forceinline__ float bflo(unsigned v) { return __uint_as_float(v << 16); }
; __device__ __forceinline__ float bfhi(unsigned v) { return __uint_as_float(v & 0xffff0000u); }
; __device__ __forceinline__ float siluf_(float x) { return x * __builtin_amdgcn_rcpf(1.0f + __expf(-x)); }
;   __device__ __forceinline__ void operator()(EPI_ARGS) const {
;     ...
;         for (int m = 0; m < 4; ++m) {
;           const size_t row = row0 + ai * HALF + m * 16;
;           const f32x4 v0 = acc[ai][bj][m][0], v1 = acc[ai][bj][m][1];
;           u32x4 o;
;           o.x = pack2(v0[0] * s0[0] * siluf_(bflo(z[m].x)), v0[1] * s0[1] * siluf_(bfhi(z[m].x)));
;           o.y = pack2(v0[2] * s0[2] * siluf_(bflo(z[m].y)), v0[3] * s0[3] * siluf_(bfhi(z[m].y)));
;           o.z = pack2(v1[0] * s1[0] * siluf_(bflo(z[m].z)), v1[1] * s1[1] * siluf_(bfhi(z[m].z)));
;           o.w = pack2(v1[2] * s1[2] * siluf_(bflo(z[m].w)), v1[3] * s1[3] * siluf_(bfhi(z[m].w)));
;           *(u32x4*)(y0 + row * DM + c) = o;
;         }
	v_mul_f32_e32 v89, v90, v91
	v_lshlrev_b32_e32 v91, 16, v118
	v_cvt_pk_bf16_f32 v89, v2, v89
	v_mul_f32_e32 v2, 0xbfb8aa3b, v91
	v_exp_f32_e32 v2, v2
	v_mov_b32_e32 v98, v84
	v_mov_b32_e32 v90, v92
	v_add_f32_e32 v2, 1.0, v2
	v_rcp_f32_e32 v99, v2
	s_nop 0
	v_pk_mul_f32 v[90:91], v[98:99], v[90:91]
	s_nop 0
	v_mul_f32_e32 v2, v90, v91
	v_and_b32_e32 v91, 0xffff0000, v118
	v_mul_f32_e32 v84, 0xbfb8aa3b, v91
	v_exp_f32_e32 v84, v84
	v_mov_b32_e32 v98, v85
	v_mov_b32_e32 v90, v93
	v_add_f32_e32 v84, 1.0, v84
	v_rcp_f32_e32 v99, v84
	s_nop 0
	v_pk_mul_f32 v[84:85], v[98:99], v[90:91]
	s_nop 0
	v_mul_f32_e32 v84, v84, v85
	v_lshlrev_b32_e32 v85, 16, v119
	v_cvt_pk_bf16_f32 v90, v2, v84
	v_mul_f32_e32 v2, 0xbfb8aa3b, v85
	v_exp_f32_e32 v2, v2
	v_mov_b32_e32 v98, v86
	v_mov_b32_e32 v84, v94
	v_mov_b32_e32 v86, v80
	v_add_f32_e32 v2, 1.0, v2
	v_rcp_f32_e32 v99, v2
	s_nop 0
	v_pk_mul_f32 v[84:85], v[98:99], v[84:85]
	s_nop 0
	v_mul_f32_e32 v2, v84, v85
	v_and_b32_e32 v85, 0xffff0000, v119
	v_mul_f32_e32 v84, 0xbfb8aa3b, v85
	v_exp_f32_e32 v84, v84
	v_mov_b32_e32 v98, v87
	v_add_f32_e32 v84, 1.0, v84
	v_rcp_f32_e32 v99, v84
	v_mov_b32_e32 v84, v95
	v_pk_mul_f32 v[84:85], v[98:99], v[84:85]
	s_nop 0
	v_mul_f32_e32 v84, v84, v85
	v_cvt_pk_bf16_f32 v91, v2, v84
	v_lshlrev_b64 v[84:85], 12, v[146:147]
	v_lshl_add_u64 v[84:85], s[8:9], 0, v[84:85]
	v_lshl_add_u64 v[98:99], v[84:85], 0, v[140:141]
	v_lshlrev_b32_e32 v85, 16, v112
	v_mul_f32_e32 v2, 0xbfb8aa3b, v85
	v_exp_f32_e32 v2, v2
	v_mov_b32_e32 v84, v100
	flat_store_dwordx4 v[98:99], v[88:91]
	v_add_f32_e32 v2, 1.0, v2
	v_rcp_f32_e32 v87, v2
	s_nop 0
	v_pk_mul_f32 v[84:85], v[86:87], v[84:85]
	s_nop 0
	v_mul_f32_e32 v2, v84, v85
	v_and_b32_e32 v85, 0xffff0000, v112
	v_mul_f32_e32 v80, 0xbfb8aa3b, v85
	v_exp_f32_e32 v80, v80
	v_mov_b32_e32 v86, v81
	v_mov_b32_e32 v84, v101
	v_add_f32_e32 v80, 1.0, v80
	v_rcp_f32_e32 v87, v80
	s_nop 0
	v_pk_mul_f32 v[80:81], v[86:87], v[84:85]
	s_nop 0
	v_mul_f32_e32 v80, v80, v81
	v_lshlrev_b32_e32 v85, 16, v113
	v_cvt_pk_bf16_f32 v80, v2, v80
	v_mul_f32_e32 v2, 0xbfb8aa3b, v85
	v_exp_f32_e32 v2, v2
	v_mov_b32_e32 v86, v82
	v_mov_b32_e32 v84, v102
	v_add_f32_e32 v2, 1.0, v2
	v_rcp_f32_e32 v87, v2
	s_nop 0
	v_pk_mul_f32 v[84:85], v[86:87], v[84:85]
	s_nop 0
	v_mul_f32_e32 v2, v84, v85
	v_and_b32_e32 v85, 0xffff0000, v113
	v_mul_f32_e32 v81, 0xbfb8aa3b, v85
	v_exp_f32_e32 v81, v81
	v_mov_b32_e32 v86, v83
	v_mov_b32_e32 v84, v103
	v_add_f32_e32 v81, 1.0, v81
	v_rcp_f32_e32 v87, v81
	s_nop 0
	v_pk_mul_f32 v[82:83], v[86:87], v[84:85]
	s_nop 0
	v_mul_f32_e32 v81, v82, v83
	v_lshlrev_b32_e32 v83, 16, v114
	v_cvt_pk_bf16_f32 v81, v2, v81
	v_mul_f32_e32 v2, 0xbfb8aa3b, v83
	v_exp_f32_e32 v2, v2
	v_mov_b32_e32 v84, v76
	v_mov_b32_e32 v82, v92
	v_add_f32_e32 v2, 1.0, v2
	v_rcp_f32_e32 v85, v2
	s_nop 0
	v_pk_mul_f32 v[82:83], v[84:85], v[82:83]
	s_nop 0
	v_mul_f32_e32 v2, v82, v83
	v_and_b32_e32 v83, 0xffff0000, v114
	v_mul_f32_e32 v76, 0xbfb8aa3b, v83
	v_exp_f32_e32 v76, v76
	v_mov_b32_e32 v84, v77
	v_mov_b32_e32 v82, v93
	v_add_f32_e32 v76, 1.0, v76
	v_rcp_f32_e32 v85, v76
	s_nop 0
	v_pk_mul_f32 v[76:77], v[84:85], v[82:83]
	s_nop 0
	v_mul_f32_e32 v76, v76, v77
	v_lshlrev_b32_e32 v77, 16, v115
	v_cvt_pk_bf16_f32 v82, v2, v76
	v_mul_f32_e32 v2, 0xbfb8aa3b, v77
	v_exp_f32_e32 v2, v2
	v_mov_b32_e32 v84, v78
	v_mov_b32_e32 v76, v94
	v_mov_b32_e32 v78, v72
	v_add_f32_e32 v2, 1.0, v2
	v_rcp_f32_e32 v85, v2
	s_nop 0
	v_pk_mul_f32 v[76:77], v[84:85], v[76:77]
	s_nop 0
	v_mul_f32_e32 v2, v76, v77
	v_and_b32_e32 v77, 0xffff0000, v115
	v_mul_f32_e32 v76, 0xbfb8aa3b, v77
	v_exp_f32_e32 v76, v76
	v_mov_b32_e32 v84, v79
	v_add_f32_e32 v76, 1.0, v76
	v_rcp_f32_e32 v85, v76
	v_mov_b32_e32 v76, v95
	v_pk_mul_f32 v[76:77], v[84:85], v[76:77]
	s_nop 0
	v_mul_f32_e32 v76, v76, v77
	v_cvt_pk_bf16_f32 v83, v2, v76
	v_lshlrev_b64 v[76:77], 12, v[144:145]
	v_lshl_add_u64 v[76:77], s[8:9], 0, v[76:77]
	v_lshl_add_u64 v[104:105], v[76:77], 0, v[140:141]
	v_lshlrev_b32_e32 v77, 16, v108
	v_mul_f32_e32 v2, 0xbfb8aa3b, v77
	v_exp_f32_e32 v2, v2
	v_mov_b32_e32 v76, v100
	flat_store_dwordx4 v[104:105], v[80:83]
	v_add_f32_e32 v2, 1.0, v2
	v_rcp_f32_e32 v79, v2
	s_nop 0
	v_pk_mul_f32 v[76:77], v[78:79], v[76:77]
	s_nop 0
	v_mul_f32_e32 v2, v76, v77
	v_and_b32_e32 v77, 0xffff0000, v108
	v_mul_f32_e32 v72, 0xbfb8aa3b, v77
	v_exp_f32_e32 v72, v72
	v_mov_b32_e32 v78, v73
	v_mov_b32_e32 v76, v101
	v_add_f32_e32 v72, 1.0, v72
	v_rcp_f32_e32 v79, v72
	s_nop 0
	v_pk_mul_f32 v[72:73], v[78:79], v[76:77]
	s_nop 0
	v_mul_f32_e32 v72, v72, v73
	v_lshlrev_b32_e32 v77, 16, v109
	v_cvt_pk_bf16_f32 v72, v2, v72
	v_mul_f32_e32 v2, 0xbfb8aa3b, v77
	v_exp_f32_e32 v2, v2
	v_mov_b32_e32 v78, v74
	v_mov_b32_e32 v76, v102
	v_add_f32_e32 v2, 1.0, v2
	v_rcp_f32_e32 v79, v2
	s_nop 0
	v_pk_mul_f32 v[76:77], v[78:79], v[76:77]
	s_nop 0
	v_mul_f32_e32 v2, v76, v77
	v_and_b32_e32 v77, 0xffff0000, v109
	v_mul_f32_e32 v73, 0xbfb8aa3b, v77
	v_exp_f32_e32 v73, v73
	v_mov_b32_e32 v78, v75
	v_mov_b32_e32 v76, v103
	v_add_f32_e32 v73, 1.0, v73
	v_rcp_f32_e32 v79, v73
	s_nop 0
	v_pk_mul_f32 v[74:75], v[78:79], v[76:77]
	s_nop 0
	v_mul_f32_e32 v73, v74, v75
	v_lshlrev_b32_e32 v75, 16, v110
	v_cvt_pk_bf16_f32 v73, v2, v73
	v_mul_f32_e32 v2, 0xbfb8aa3b, v75
	v_exp_f32_e32 v2, v2
	v_mov_b32_e32 v76, v68
	v_mov_b32_e32 v74, v92
	v_add_f32_e32 v2, 1.0, v2
	v_rcp_f32_e32 v77, v2
	s_nop 0
	v_pk_mul_f32 v[74:75], v[76:77], v[74:75]
	s_nop 0
	v_mul_f32_e32 v2, v74, v75
	v_and_b32_e32 v75, 0xffff0000, v110
	v_mul_f32_e32 v68, 0xbfb8aa3b, v75
	v_exp_f32_e32 v68, v68
	v_mov_b32_e32 v76, v69
	v_mov_b32_e32 v74, v93
	v_add_f32_e32 v68, 1.0, v68
; __device__ __forceinline__ size_t pidx(size_t row, int col) { return ((size_t)(col >> 8) * MTOK + row) * PLD + (col & 255); }
; __device__ __forceinline__ float bflo(unsigned v) { return __uint_as_float(v << 16); }
; __device__ __forceinline__ float bfhi(unsigned v) { return __uint_as_float(v & 0xffff0000u); }
; __device__ __forceinline__ float siluf_(float x) { return x * __builtin_amdgcn_rcpf(1.0f + __expf(-x)); }
;   __device__ __forceinline__ void operator()(EPI_ARGS) const {
;     ...
;     for (int bj = 0; bj < 2; ++bj) {
;       const int c = col0 + bj * HALF;
;       const f32x4 s0 = *(const f32x4*)(psc + c), s1 = *(const f32x4*)(psc + c + 4);
; #pragma unroll
;       for (int ai = 0; ai < 2; ++ai) {
;         u32x4 z[4];
; #pragma unroll
;         for (int m = 0; m < 4; ++m) z[m] = *(const u32x4*)(proj + pidx(row0 + ai * HALF + m * 16, PZ + c));
;         __builtin_amdgcn_sched_barrier(0);
; #pragma unroll
;         for (int m = 0; m < 4; ++m) {
;           const size_t row = row0 + ai * HALF + m * 16;
;           const f32x4 v0 = acc[ai][bj][m][0], v1 = acc[ai][bj][m][1];
;           u32x4 o;
;           o.x = pack2(v0[0] * s0[0] * siluf_(bflo(z[m].x)), v0[1] * s0[1] * siluf_(bfhi(z[m].x)));
;           o.y = pack2(v0[2] * s0[2] * siluf_(bflo(z[m].y)), v0[3] * s0[3] * siluf_(bfhi(z[m].y)));
;           o.z = pack2(v1[0] * s1[0] * siluf_(bflo(z[m].z)), v1[1] * s1[1] * siluf_(bfhi(z[m].z)));
;           o.w = pack2(v1[2] * s1[2] * siluf_(bflo(z[m].w)), v1[3] * s1[3] * siluf_(bfhi(z[m].w)));
;           *(u32x4*)(y0 + row * DM + c) = o;
;         }
	v_rcp_f32_e32 v77, v68
	s_nop 0
	v_pk_mul_f32 v[68:69], v[76:77], v[74:75]
	s_nop 0
	v_mul_f32_e32 v68, v68, v69
	v_lshlrev_b32_e32 v69, 16, v111
	v_cvt_pk_bf16_f32 v74, v2, v68
	v_mul_f32_e32 v2, 0xbfb8aa3b, v69
	v_exp_f32_e32 v2, v2
	v_mov_b32_e32 v76, v70
	v_mov_b32_e32 v68, v94
	v_add_f32_e32 v2, 1.0, v2
	v_rcp_f32_e32 v77, v2
	s_nop 0
	v_pk_mul_f32 v[68:69], v[76:77], v[68:69]
	s_nop 0
	v_mul_f32_e32 v2, v68, v69
	v_and_b32_e32 v69, 0xffff0000, v111
	v_mul_f32_e32 v68, 0xbfb8aa3b, v69
	v_exp_f32_e32 v68, v68
	v_mov_b32_e32 v76, v71
	v_add_f32_e32 v68, 1.0, v68
	v_rcp_f32_e32 v77, v68
	v_mov_b32_e32 v68, v95
	v_lshl_add_u64 v[94:95], s[2:3], 0, v[174:175]
	v_pk_mul_f32 v[68:69], v[76:77], v[68:69]
	s_nop 0
	v_mul_f32_e32 v68, v68, v69
	v_cvt_pk_bf16_f32 v75, v2, v68
	v_lshlrev_b64 v[68:69], 12, v[142:143]
	v_lshl_add_u64 v[68:69], s[8:9], 0, v[68:69]
	v_lshl_add_u64 v[92:93], v[68:69], 0, v[140:141]
	flat_store_dwordx4 v[92:93], v[72:75]
	v_lshl_add_u64 v[76:77], v[94:95], 0, v[178:179]
	global_load_dwordx4 v[68:71], v[176:177], off offset:528
	global_load_dwordx4 v[72:75], v[176:177], off offset:512
	flat_load_dwordx4 v[88:91], v[76:77]
	v_lshl_add_u64 v[76:77], v[94:95], 0, v[180:181]
	flat_load_dwordx4 v[84:87], v[76:77]
	v_lshl_add_u64 v[76:77], v[94:95], 0, v[182:183]
	flat_load_dwordx4 v[80:83], v[76:77]
	v_lshl_add_u64 v[76:77], v[94:95], 0, v[184:185]
	flat_load_dwordx4 v[76:79], v[76:77]
	s_waitcnt vmcnt(0) lgkmcnt(0)
	v_lshlrev_b32_e32 v101, 16, v88
	v_mul_f32_e32 v2, 0xbfb8aa3b, v101
	v_exp_f32_e32 v2, v2
	v_mov_b32_e32 v102, v64
	v_mov_b32_e32 v100, v72
	v_add_f32_e32 v2, 1.0, v2
	v_rcp_f32_e32 v103, v2
	s_nop 0
	v_pk_mul_f32 v[100:101], v[102:103], v[100:101]
	s_nop 0
	v_mul_f32_e32 v2, v100, v101
	v_and_b32_e32 v101, 0xffff0000, v88
	v_mul_f32_e32 v64, 0xbfb8aa3b, v101
	v_exp_f32_e32 v64, v64
	v_mov_b32_e32 v102, v65
	v_mov_b32_e32 v100, v73
	v_mov_b32_e32 v88, v75
	v_add_f32_e32 v64, 1.0, v64
	v_rcp_f32_e32 v103, v64
	s_nop 0
	v_pk_mul_f32 v[64:65], v[102:103], v[100:101]
	s_nop 0
	v_mul_f32_e32 v64, v64, v65
	v_lshlrev_b32_e32 v101, 16, v89
	v_cvt_pk_bf16_f32 v64, v2, v64
	v_mul_f32_e32 v2, 0xbfb8aa3b, v101
	v_exp_f32_e32 v2, v2
	v_and_b32_e32 v89, 0xffff0000, v89
	v_mul_f32_e32 v65, 0xbfb8aa3b, v89
	v_exp_f32_e32 v65, v65
	v_add_f32_e32 v2, 1.0, v2
	v_rcp_f32_e32 v103, v2
	v_mov_b32_e32 v102, v66
	v_mov_b32_e32 v100, v74
	v_add_f32_e32 v65, 1.0, v65
	v_pk_mul_f32 v[100:101], v[102:103], v[100:101]
	s_nop 0
	v_mul_f32_e32 v2, v100, v101
	v_rcp_f32_e32 v101, v65
	v_mov_b32_e32 v100, v67
	v_pk_mul_f32 v[66:67], v[100:101], v[88:89]
	s_nop 0
	v_mul_f32_e32 v65, v66, v67
	v_lshlrev_b32_e32 v67, 16, v90
	v_cvt_pk_bf16_f32 v65, v2, v65
	v_mul_f32_e32 v2, 0xbfb8aa3b, v67
	v_exp_f32_e32 v2, v2
	v_mov_b32_e32 v88, v60
	v_mov_b32_e32 v66, v68
	v_add_f32_e32 v2, 1.0, v2
	v_rcp_f32_e32 v89, v2
	s_nop 0
	v_pk_mul_f32 v[66:67], v[88:89], v[66:67]
	s_nop 0
	v_mul_f32_e32 v2, v66, v67
	v_and_b32_e32 v67, 0xffff0000, v90
	v_mul_f32_e32 v60, 0xbfb8aa3b, v67
	v_exp_f32_e32 v60, v60
	v_mov_b32_e32 v88, v61
	v_mov_b32_e32 v66, v69
	v_add_f32_e32 v60, 1.0, v60
	v_rcp_f32_e32 v89, v60
	s_nop 0
	v_pk_mul_f32 v[60:61], v[88:89], v[66:67]
	s_nop 0
	v_mul_f32_e32 v60, v60, v61
	v_lshlrev_b32_e32 v61, 16, v91
	v_cvt_pk_bf16_f32 v66, v2, v60
	v_mul_f32_e32 v2, 0xbfb8aa3b, v61
	v_exp_f32_e32 v2, v2
	v_mov_b32_e32 v88, v62
	v_mov_b32_e32 v60, v70
	v_mov_b32_e32 v62, v56
	v_add_f32_e32 v2, 1.0, v2
	v_rcp_f32_e32 v89, v2
	s_nop 0
	v_pk_mul_f32 v[60:61], v[88:89], v[60:61]
	s_nop 0
	v_mul_f32_e32 v2, v60, v61
	v_and_b32_e32 v61, 0xffff0000, v91
	v_mul_f32_e32 v60, 0xbfb8aa3b, v61
	v_exp_f32_e32 v60, v60
	v_mov_b32_e32 v88, v63
	v_add_f32_e32 v60, 1.0, v60
	v_rcp_f32_e32 v89, v60
	v_mov_b32_e32 v60, v71
	v_pk_mul_f32 v[60:61], v[88:89], v[60:61]
	s_nop 0
	v_mul_f32_e32 v60, v60, v61
	v_lshlrev_b32_e32 v61, 16, v84
	v_cvt_pk_bf16_f32 v67, v2, v60
	v_mul_f32_e32 v2, 0xbfb8aa3b, v61
	v_exp_f32_e32 v2, v2
	v_mov_b32_e32 v60, v72
	flat_store_dwordx4 v[136:137], v[64:67] offset:256
	v_add_f32_e32 v2, 1.0, v2
	v_rcp_f32_e32 v63, v2
	s_nop 0
	v_pk_mul_f32 v[60:61], v[62:63], v[60:61]
	s_nop 0
	v_mul_f32_e32 v2, v60, v61
	v_and_b32_e32 v61, 0xffff0000, v84
	v_mul_f32_e32 v56, 0xbfb8aa3b, v61
	v_exp_f32_e32 v56, v56
	v_mov_b32_e32 v62, v57
	v_mov_b32_e32 v60, v73
	v_add_f32_e32 v56, 1.0, v56
	v_rcp_f32_e32 v63, v56
	s_nop 0
	v_pk_mul_f32 v[56:57], v[62:63], v[60:61]
	s_nop 0
	v_mul_f32_e32 v56, v56, v57
	v_lshlrev_b32_e32 v61, 16, v85
	v_cvt_pk_bf16_f32 v56, v2, v56
	v_mul_f32_e32 v2, 0xbfb8aa3b, v61
	v_exp_f32_e32 v2, v2
	v_mov_b32_e32 v62, v58
	v_mov_b32_e32 v60, v74
	v_add_f32_e32 v2, 1.0, v2
	v_rcp_f32_e32 v63, v2
	s_nop 0
	v_pk_mul_f32 v[60:61], v[62:63], v[60:61]
	s_nop 0
	v_mul_f32_e32 v2, v60, v61
	v_and_b32_e32 v61, 0xffff0000, v85
	v_mul_f32_e32 v57, 0xbfb8aa3b, v61
	v_exp_f32_e32 v57, v57
	v_mov_b32_e32 v62, v59
	v_mov_b32_e32 v60, v75
	v_add_f32_e32 v57, 1.0, v57
	v_rcp_f32_e32 v63, v57
	s_nop 0
	v_pk_mul_f32 v[58:59], v[62:63], v[60:61]
	s_nop 0
	v_mul_f32_e32 v57, v58, v59
	v_lshlrev_b32_e32 v59, 16, v86
	v_cvt_pk_bf16_f32 v57, v2, v57
	v_mul_f32_e32 v2, 0xbfb8aa3b, v59
	v_exp_f32_e32 v2, v2
	v_mov_b32_e32 v60, v52
	v_mov_b32_e32 v58, v68
	v_add_f32_e32 v2, 1.0, v2
	v_rcp_f32_e32 v61, v2
	s_nop 0
	v_pk_mul_f32 v[58:59], v[60:61], v[58:59]
	s_nop 0
	v_mul_f32_e32 v2, v58, v59
	v_and_b32_e32 v59, 0xffff0000, v86
	v_mul_f32_e32 v52, 0xbfb8aa3b, v59
	v_exp_f32_e32 v52, v52
	v_mov_b32_e32 v60, v53
	v_mov_b32_e32 v58, v69
	v_add_f32_e32 v52, 1.0, v52
	v_rcp_f32_e32 v61, v52
	s_nop 0
	v_pk_mul_f32 v[52:53], v[60:61], v[58:59]
	s_nop 0
	v_mul_f32_e32 v52, v52, v53
; __device__ __forceinline__ size_t pidx(size_t row, int col) { return ((size_t)(col >> 8) * MTOK + row) * PLD + (col & 255); }
; __device__ __forceinline__ float bflo(unsigned v) { return __uint_as_float(v << 16); }
; __device__ __forceinline__ float bfhi(unsigned v) { return __uint_as_float(v & 0xffff0000u); }
; __device__ __forceinline__ float siluf_(float x) { return x * __builtin_amdgcn_rcpf(1.0f + __expf(-x)); }
;   __device__ __forceinline__ void operator()(EPI_ARGS) const {
;     ...
;       for (int ai = 0; ai < 2; ++ai) {
;         u32x4 z[4];
; #pragma unroll
;         for (int m = 0; m < 4; ++m) z[m] = *(const u32x4*)(proj + pidx(row0 + ai * HALF + m * 16, PZ + c));
;         __builtin_amdgcn_sched_barrier(0);
; #pragma unroll
;         for (int m = 0; m < 4; ++m) {
;           const size_t row = row0 + ai * HALF + m * 16;
;           const f32x4 v0 = acc[ai][bj][m][0], v1 = acc[ai][bj][m][1];
;           u32x4 o;
;           o.x = pack2(v0[0] * s0[0] * siluf_(bflo(z[m].x)), v0[1] * s0[1] * siluf_(bfhi(z[m].x)));
;           o.y = pack2(v0[2] * s0[2] * siluf_(bflo(z[m].y)), v0[3] * s0[3] * siluf_(bfhi(z[m].y)));
;           o.z = pack2(v1[0] * s1[0] * siluf_(bflo(z[m].z)), v1[1] * s1[1] * siluf_(bfhi(z[m].z)));
;           o.w = pack2(v1[2] * s1[2] * siluf_(bflo(z[m].w)), v1[3] * s1[3] * siluf_(bfhi(z[m].w)));
;           *(u32x4*)(y0 + row * DM + c) = o;
;         }
	v_lshlrev_b32_e32 v53, 16, v87
	v_cvt_pk_bf16_f32 v58, v2, v52
	v_mul_f32_e32 v2, 0xbfb8aa3b, v53
	v_exp_f32_e32 v2, v2
	v_mov_b32_e32 v60, v54
	v_mov_b32_e32 v52, v70
	v_mov_b32_e32 v54, v48
	v_add_f32_e32 v2, 1.0, v2
	v_rcp_f32_e32 v61, v2
	s_nop 0
	v_pk_mul_f32 v[52:53], v[60:61], v[52:53]
	s_nop 0
	v_mul_f32_e32 v2, v52, v53
	v_and_b32_e32 v53, 0xffff0000, v87
	v_mul_f32_e32 v52, 0xbfb8aa3b, v53
	v_exp_f32_e32 v52, v52
	v_mov_b32_e32 v60, v55
	v_add_f32_e32 v52, 1.0, v52
	v_rcp_f32_e32 v61, v52
	v_mov_b32_e32 v52, v71
	v_pk_mul_f32 v[52:53], v[60:61], v[52:53]
	s_nop 0
	v_mul_f32_e32 v52, v52, v53
	v_lshlrev_b32_e32 v53, 16, v80
	v_cvt_pk_bf16_f32 v59, v2, v52
	v_mul_f32_e32 v2, 0xbfb8aa3b, v53
	v_exp_f32_e32 v2, v2
	v_mov_b32_e32 v52, v72
	flat_store_dwordx4 v[124:125], v[56:59] offset:256
	v_add_f32_e32 v2, 1.0, v2
	v_rcp_f32_e32 v55, v2
	s_nop 0
	v_pk_mul_f32 v[52:53], v[54:55], v[52:53]
	s_nop 0
	v_mul_f32_e32 v2, v52, v53
	v_and_b32_e32 v53, 0xffff0000, v80
	v_mul_f32_e32 v48, 0xbfb8aa3b, v53
	v_exp_f32_e32 v48, v48
	v_mov_b32_e32 v54, v49
	v_mov_b32_e32 v52, v73
	v_add_f32_e32 v48, 1.0, v48
	v_rcp_f32_e32 v55, v48
	s_nop 0
	v_pk_mul_f32 v[48:49], v[54:55], v[52:53]
	s_nop 0
	v_mul_f32_e32 v48, v48, v49
	v_lshlrev_b32_e32 v53, 16, v81
	v_cvt_pk_bf16_f32 v48, v2, v48
	v_mul_f32_e32 v2, 0xbfb8aa3b, v53
	v_exp_f32_e32 v2, v2
	v_mov_b32_e32 v54, v50
	v_mov_b32_e32 v52, v74
	v_add_f32_e32 v2, 1.0, v2
	v_rcp_f32_e32 v55, v2
	s_nop 0
	v_pk_mul_f32 v[52:53], v[54:55], v[52:53]
	s_nop 0
	v_mul_f32_e32 v2, v52, v53
	v_and_b32_e32 v53, 0xffff0000, v81
	v_mul_f32_e32 v49, 0xbfb8aa3b, v53
	v_exp_f32_e32 v49, v49
	v_mov_b32_e32 v54, v51
	v_mov_b32_e32 v52, v75
	v_add_f32_e32 v49, 1.0, v49
	v_rcp_f32_e32 v55, v49
	s_nop 0
	v_pk_mul_f32 v[50:51], v[54:55], v[52:53]
	s_nop 0
	v_mul_f32_e32 v49, v50, v51
	v_lshlrev_b32_e32 v51, 16, v82
	v_cvt_pk_bf16_f32 v49, v2, v49
	v_mul_f32_e32 v2, 0xbfb8aa3b, v51
	v_exp_f32_e32 v2, v2
	v_mov_b32_e32 v52, v44
	v_mov_b32_e32 v50, v68
	v_add_f32_e32 v2, 1.0, v2
	v_rcp_f32_e32 v53, v2
	s_nop 0
	v_pk_mul_f32 v[50:51], v[52:53], v[50:51]
	s_nop 0
	v_mul_f32_e32 v2, v50, v51
	v_and_b32_e32 v51, 0xffff0000, v82
	v_mul_f32_e32 v44, 0xbfb8aa3b, v51
	v_exp_f32_e32 v44, v44
	v_mov_b32_e32 v52, v45
	v_mov_b32_e32 v50, v69
	v_add_f32_e32 v44, 1.0, v44
	v_rcp_f32_e32 v53, v44
	s_nop 0
	v_pk_mul_f32 v[44:45], v[52:53], v[50:51]
	s_nop 0
	v_mul_f32_e32 v44, v44, v45
	v_lshlrev_b32_e32 v45, 16, v83
	v_cvt_pk_bf16_f32 v50, v2, v44
	v_mul_f32_e32 v2, 0xbfb8aa3b, v45
	v_exp_f32_e32 v2, v2
	v_mov_b32_e32 v52, v46
	v_mov_b32_e32 v44, v70
	v_mov_b32_e32 v46, v40
	v_add_f32_e32 v2, 1.0, v2
	v_rcp_f32_e32 v53, v2
	s_nop 0
	v_pk_mul_f32 v[44:45], v[52:53], v[44:45]
	s_nop 0
	v_mul_f32_e32 v2, v44, v45
	v_and_b32_e32 v45, 0xffff0000, v83
	v_mul_f32_e32 v44, 0xbfb8aa3b, v45
	v_exp_f32_e32 v44, v44
	v_mov_b32_e32 v52, v47
	v_add_f32_e32 v44, 1.0, v44
	v_rcp_f32_e32 v53, v44
	v_mov_b32_e32 v44, v71
	v_pk_mul_f32 v[44:45], v[52:53], v[44:45]
	s_nop 0
	v_mul_f32_e32 v44, v44, v45
	v_lshlrev_b32_e32 v45, 16, v76
	v_cvt_pk_bf16_f32 v51, v2, v44
	v_mul_f32_e32 v2, 0xbfb8aa3b, v45
	v_exp_f32_e32 v2, v2
	v_mov_b32_e32 v44, v72
	flat_store_dwordx4 v[128:129], v[48:51] offset:256
	v_add_f32_e32 v2, 1.0, v2
	v_rcp_f32_e32 v47, v2
	s_nop 0
	v_pk_mul_f32 v[44:45], v[46:47], v[44:45]
	s_nop 0
	v_mul_f32_e32 v2, v44, v45
	v_and_b32_e32 v45, 0xffff0000, v76
	v_mul_f32_e32 v40, 0xbfb8aa3b, v45
	v_exp_f32_e32 v40, v40
	v_mov_b32_e32 v46, v41
	v_mov_b32_e32 v44, v73
	v_add_f32_e32 v40, 1.0, v40
	v_rcp_f32_e32 v47, v40
	s_nop 0
	v_pk_mul_f32 v[40:41], v[46:47], v[44:45]
	s_nop 0
	v_mul_f32_e32 v40, v40, v41
	v_lshlrev_b32_e32 v45, 16, v77
	v_cvt_pk_bf16_f32 v40, v2, v40
	v_mul_f32_e32 v2, 0xbfb8aa3b, v45
	v_exp_f32_e32 v2, v2
	v_mov_b32_e32 v46, v42
	v_mov_b32_e32 v44, v74
	v_add_f32_e32 v2, 1.0, v2
	v_rcp_f32_e32 v47, v2
	s_nop 0
	v_pk_mul_f32 v[44:45], v[46:47], v[44:45]
	s_nop 0
	v_mul_f32_e32 v2, v44, v45
	v_and_b32_e32 v45, 0xffff0000, v77
	v_mul_f32_e32 v41, 0xbfb8aa3b, v45
	v_exp_f32_e32 v41, v41
	v_mov_b32_e32 v46, v43
	v_mov_b32_e32 v44, v75
	v_add_f32_e32 v41, 1.0, v41
	v_rcp_f32_e32 v47, v41
	s_nop 0
	v_pk_mul_f32 v[42:43], v[46:47], v[44:45]
	s_nop 0
	v_mul_f32_e32 v41, v42, v43
	v_lshlrev_b32_e32 v43, 16, v78
	v_cvt_pk_bf16_f32 v41, v2, v41
	v_mul_f32_e32 v2, 0xbfb8aa3b, v43
	v_exp_f32_e32 v2, v2
	v_mov_b32_e32 v44, v36
	v_mov_b32_e32 v42, v68
	v_add_f32_e32 v2, 1.0, v2
	v_rcp_f32_e32 v45, v2
	s_nop 0
	v_pk_mul_f32 v[42:43], v[44:45], v[42:43]
	s_nop 0
	v_mul_f32_e32 v2, v42, v43
	v_and_b32_e32 v43, 0xffff0000, v78
	v_mul_f32_e32 v36, 0xbfb8aa3b, v43
	v_exp_f32_e32 v36, v36
	v_mov_b32_e32 v44, v37
	v_mov_b32_e32 v42, v69
	v_add_f32_e32 v36, 1.0, v36
	v_rcp_f32_e32 v45, v36
	s_nop 0
	v_pk_mul_f32 v[36:37], v[44:45], v[42:43]
	s_nop 0
	v_mul_f32_e32 v36, v36, v37
	v_lshlrev_b32_e32 v37, 16, v79
	v_cvt_pk_bf16_f32 v42, v2, v36
	v_mul_f32_e32 v2, 0xbfb8aa3b, v37
	v_exp_f32_e32 v2, v2
	v_mov_b32_e32 v44, v38
	v_mov_b32_e32 v36, v70
	v_add_f32_e32 v2, 1.0, v2
	v_rcp_f32_e32 v45, v2
	s_nop 0
	v_pk_mul_f32 v[36:37], v[44:45], v[36:37]
	s_nop 0
	v_mul_f32_e32 v2, v36, v37
	v_and_b32_e32 v37, 0xffff0000, v79
	v_mul_f32_e32 v36, 0xbfb8aa3b, v37
	v_exp_f32_e32 v36, v36
	v_mov_b32_e32 v44, v39
	v_add_f32_e32 v36, 1.0, v36
	v_rcp_f32_e32 v45, v36
	v_mov_b32_e32 v36, v71
	v_pk_mul_f32 v[36:37], v[44:45], v[36:37]
	s_nop 0
	v_mul_f32_e32 v36, v36, v37
	v_cvt_pk_bf16_f32 v43, v2, v36
	flat_store_dwordx4 v[126:127], v[40:43] offset:256
	v_lshl_add_u64 v[36:37], v[94:95], 0, v[130:131]
	flat_load_dwordx4 v[48:51], v[36:37]
	v_lshl_add_u64 v[36:37], v[94:95], 0, v[132:133]
	flat_load_dwordx4 v[44:47], v[36:37]
	v_lshl_add_u64 v[36:37], v[94:95], 0, v[134:135]
	flat_load_dwordx4 v[40:43], v[36:37]
	v_lshl_add_u64 v[36:37], v[94:95], 0, v[138:139]
	flat_load_dwordx4 v[36:39], v[36:37]
	s_waitcnt vmcnt(0) lgkmcnt(0)
; __device__ __forceinline__ float bflo(unsigned v) { return __uint_as_float(v << 16); }
; __device__ __forceinline__ float bfhi(unsigned v) { return __uint_as_float(v & 0xffff0000u); }
; __device__ __forceinline__ float siluf_(float x) { return x * __builtin_amdgcn_rcpf(1.0f + __expf(-x)); }
; template <class Epi, class AddrA, class AddrB>
; __device__ __forceinline__ void gemm_phase(const Sched S, const int lda, const int ldb, const int K, const AddrA addrA,
;                                            const AddrB addrB, const Epi E) {
;     ...
;     cur = nxt; cA = nA; cB = nB; ++ui;
;   __device__ __forceinline__ void operator()(EPI_ARGS) const {
;     ...
;         for (int m = 0; m < 4; ++m) {
;           const size_t row = row0 + ai * HALF + m * 16;
;           const f32x4 v0 = acc[ai][bj][m][0], v1 = acc[ai][bj][m][1];
;           u32x4 o;
;           o.x = pack2(v0[0] * s0[0] * siluf_(bflo(z[m].x)), v0[1] * s0[1] * siluf_(bfhi(z[m].x)));
;           o.y = pack2(v0[2] * s0[2] * siluf_(bflo(z[m].y)), v0[3] * s0[3] * siluf_(bfhi(z[m].y)));
;           o.z = pack2(v1[0] * s1[0] * siluf_(bflo(z[m].z)), v1[1] * s1[1] * siluf_(bfhi(z[m].z)));
;           o.w = pack2(v1[2] * s1[2] * siluf_(bflo(z[m].w)), v1[3] * s1[3] * siluf_(bfhi(z[m].w)));
;           *(u32x4*)(y0 + row * DM + c) = o;
;         }
	v_lshlrev_b32_e32 v53, 16, v48
	v_mul_f32_e32 v2, 0xbfb8aa3b, v53
	v_exp_f32_e32 v2, v2
	v_mov_b32_e32 v54, v32
	v_mov_b32_e32 v52, v72
	s_and_b64 vcc, exec, s[18:19]
	v_add_f32_e32 v2, 1.0, v2
	v_rcp_f32_e32 v55, v2
	s_mov_b32 s33, s16
	s_mov_b32 s2, s14
	s_mov_b64 s[4:5], s[22:23]
	v_pk_mul_f32 v[52:53], v[54:55], v[52:53]
	v_mov_b32_e32 v54, v33
	v_mul_f32_e32 v2, v52, v53
	v_and_b32_e32 v53, 0xffff0000, v48
	v_mul_f32_e32 v32, 0xbfb8aa3b, v53
	v_exp_f32_e32 v32, v32
	v_mov_b32_e32 v52, v73
	v_mov_b32_e32 v48, v75
	s_mov_b64 s[6:7], s[20:21]
	v_add_f32_e32 v32, 1.0, v32
	v_rcp_f32_e32 v55, v32
	s_nop 0
	v_pk_mul_f32 v[32:33], v[54:55], v[52:53]
	s_nop 0
	v_mul_f32_e32 v32, v32, v33
	v_lshlrev_b32_e32 v53, 16, v49
	v_cvt_pk_bf16_f32 v32, v2, v32
	v_mul_f32_e32 v2, 0xbfb8aa3b, v53
	v_exp_f32_e32 v2, v2
	v_and_b32_e32 v49, 0xffff0000, v49
	v_mul_f32_e32 v33, 0xbfb8aa3b, v49
	v_exp_f32_e32 v33, v33
	v_add_f32_e32 v2, 1.0, v2
	v_rcp_f32_e32 v55, v2
	v_mov_b32_e32 v54, v34
	v_mov_b32_e32 v52, v74
	v_add_f32_e32 v33, 1.0, v33
	v_pk_mul_f32 v[52:53], v[54:55], v[52:53]
	s_nop 0
	v_mul_f32_e32 v2, v52, v53
	v_rcp_f32_e32 v53, v33
	v_mov_b32_e32 v52, v35
	v_pk_mul_f32 v[34:35], v[52:53], v[48:49]
	s_nop 0
	v_mul_f32_e32 v33, v34, v35
	v_lshlrev_b32_e32 v35, 16, v50
	v_cvt_pk_bf16_f32 v33, v2, v33
	v_mul_f32_e32 v2, 0xbfb8aa3b, v35
	v_exp_f32_e32 v2, v2
	v_mov_b32_e32 v48, v28
	v_mov_b32_e32 v34, v68
	v_add_f32_e32 v2, 1.0, v2
	v_rcp_f32_e32 v49, v2
	s_nop 0
	v_pk_mul_f32 v[34:35], v[48:49], v[34:35]
	s_nop 0
	v_mul_f32_e32 v2, v34, v35
	v_and_b32_e32 v35, 0xffff0000, v50
	v_mul_f32_e32 v28, 0xbfb8aa3b, v35
	v_exp_f32_e32 v28, v28
	v_mov_b32_e32 v48, v29
	v_mov_b32_e32 v34, v69
	v_add_f32_e32 v28, 1.0, v28
	v_rcp_f32_e32 v49, v28
	s_nop 0
	v_pk_mul_f32 v[28:29], v[48:49], v[34:35]
	s_nop 0
	v_mul_f32_e32 v28, v28, v29
	v_lshlrev_b32_e32 v29, 16, v51
	v_cvt_pk_bf16_f32 v34, v2, v28
	v_mul_f32_e32 v2, 0xbfb8aa3b, v29
	v_exp_f32_e32 v2, v2
	v_mov_b32_e32 v48, v30
	v_mov_b32_e32 v28, v70
	v_mov_b32_e32 v30, v24
	v_add_f32_e32 v2, 1.0, v2
	v_rcp_f32_e32 v49, v2
	s_nop 0
	v_pk_mul_f32 v[28:29], v[48:49], v[28:29]
	s_nop 0
	v_mul_f32_e32 v2, v28, v29
	v_and_b32_e32 v29, 0xffff0000, v51
	v_mul_f32_e32 v28, 0xbfb8aa3b, v29
	v_exp_f32_e32 v28, v28
	v_mov_b32_e32 v48, v31
	v_add_f32_e32 v28, 1.0, v28
	v_rcp_f32_e32 v49, v28
	v_mov_b32_e32 v28, v71
	v_pk_mul_f32 v[28:29], v[48:49], v[28:29]
	s_nop 0
	v_mul_f32_e32 v28, v28, v29
	v_lshlrev_b32_e32 v29, 16, v44
	v_cvt_pk_bf16_f32 v35, v2, v28
	v_mul_f32_e32 v2, 0xbfb8aa3b, v29
	v_exp_f32_e32 v2, v2
	v_mov_b32_e32 v28, v72
	flat_store_dwordx4 v[96:97], v[32:35] offset:256
	v_add_f32_e32 v2, 1.0, v2
	v_rcp_f32_e32 v31, v2
	s_nop 0
	v_pk_mul_f32 v[28:29], v[30:31], v[28:29]
	s_nop 0
	v_mul_f32_e32 v2, v28, v29
	v_and_b32_e32 v29, 0xffff0000, v44
	v_mul_f32_e32 v24, 0xbfb8aa3b, v29
	v_exp_f32_e32 v24, v24
	v_mov_b32_e32 v30, v25
	v_mov_b32_e32 v28, v73
	v_add_f32_e32 v24, 1.0, v24
	v_rcp_f32_e32 v31, v24
	s_nop 0
	v_pk_mul_f32 v[24:25], v[30:31], v[28:29]
	s_nop 0
	v_mul_f32_e32 v24, v24, v25
	v_lshlrev_b32_e32 v29, 16, v45
	v_cvt_pk_bf16_f32 v24, v2, v24
	v_mul_f32_e32 v2, 0xbfb8aa3b, v29
	v_exp_f32_e32 v2, v2
	v_mov_b32_e32 v30, v26
	v_mov_b32_e32 v28, v74
	v_add_f32_e32 v2, 1.0, v2
	v_rcp_f32_e32 v31, v2
	s_nop 0
	v_pk_mul_f32 v[28:29], v[30:31], v[28:29]
	s_nop 0
	v_mul_f32_e32 v2, v28, v29
	v_and_b32_e32 v29, 0xffff0000, v45
	v_mul_f32_e32 v25, 0xbfb8aa3b, v29
	v_exp_f32_e32 v25, v25
	v_mov_b32_e32 v30, v27
	v_mov_b32_e32 v28, v75
	v_add_f32_e32 v25, 1.0, v25
	v_rcp_f32_e32 v31, v25
	s_nop 0
	v_pk_mul_f32 v[26:27], v[30:31], v[28:29]
	s_nop 0
	v_mul_f32_e32 v25, v26, v27
	v_lshlrev_b32_e32 v27, 16, v46
	v_cvt_pk_bf16_f32 v25, v2, v25
	v_mul_f32_e32 v2, 0xbfb8aa3b, v27
	v_exp_f32_e32 v2, v2
	v_mov_b32_e32 v28, v20
	v_mov_b32_e32 v26, v68
	v_add_f32_e32 v2, 1.0, v2
	v_rcp_f32_e32 v29, v2
	s_nop 0
	v_pk_mul_f32 v[26:27], v[28:29], v[26:27]
	s_nop 0
	v_mul_f32_e32 v2, v26, v27
	v_and_b32_e32 v27, 0xffff0000, v46
	v_mul_f32_e32 v20, 0xbfb8aa3b, v27
	v_exp_f32_e32 v20, v20
	v_mov_b32_e32 v28, v21
	v_mov_b32_e32 v26, v69
	v_add_f32_e32 v20, 1.0, v20
	v_rcp_f32_e32 v29, v20
	s_nop 0
	v_pk_mul_f32 v[20:21], v[28:29], v[26:27]
	s_nop 0
	v_mul_f32_e32 v20, v20, v21
	v_lshlrev_b32_e32 v21, 16, v47
	v_cvt_pk_bf16_f32 v26, v2, v20
	v_mul_f32_e32 v2, 0xbfb8aa3b, v21
	v_exp_f32_e32 v2, v2
	v_mov_b32_e32 v28, v22
	v_mov_b32_e32 v20, v70
	v_mov_b32_e32 v22, v16
	v_add_f32_e32 v2, 1.0, v2
	v_rcp_f32_e32 v29, v2
	s_nop 0
	v_pk_mul_f32 v[20:21], v[28:29], v[20:21]
	s_nop 0
	v_mul_f32_e32 v2, v20, v21
	v_and_b32_e32 v21, 0xffff0000, v47
	v_mul_f32_e32 v20, 0xbfb8aa3b, v21
	v_exp_f32_e32 v20, v20
	v_mov_b32_e32 v28, v23
	v_add_f32_e32 v20, 1.0, v20
	v_rcp_f32_e32 v29, v20
	v_mov_b32_e32 v20, v71
	v_pk_mul_f32 v[20:21], v[28:29], v[20:21]
	s_nop 0
	v_mul_f32_e32 v20, v20, v21
	v_lshlrev_b32_e32 v21, 16, v40
	v_cvt_pk_bf16_f32 v27, v2, v20
	v_mul_f32_e32 v2, 0xbfb8aa3b, v21
	v_exp_f32_e32 v2, v2
	v_mov_b32_e32 v20, v72
	flat_store_dwordx4 v[98:99], v[24:27] offset:256
; __device__ __forceinline__ float bflo(unsigned v) { return __uint_as_float(v << 16); }
; __device__ __forceinline__ float bfhi(unsigned v) { return __uint_as_float(v & 0xffff0000u); }
; __device__ __forceinline__ float siluf_(float x) { return x * __builtin_amdgcn_rcpf(1.0f + __expf(-x)); }
; #define PG8_WAIT_V(n) asm volatile("s_waitcnt vmcnt(" #n ")" ::: "memory")
; #define PG8_BAR __builtin_amdgcn_s_barrier()
; template <class Epi, class AddrA, class AddrB>
; __device__ __forceinline__ void gemm_phase(const Sched S, const int lda, const int ldb, const int K, const AddrA addrA,
;                                            const AddrB addrB, const Epi E) {
;     ...
;   PG8_WAIT_V(0);
;   if (wr == 0) PG8_BAR;
;   PG8_BAR;
;   __device__ __forceinline__ void operator()(EPI_ARGS) const {
;     ...
;         for (int m = 0; m < 4; ++m) {
;           const size_t row = row0 + ai * HALF + m * 16;
;           const f32x4 v0 = acc[ai][bj][m][0], v1 = acc[ai][bj][m][1];
;           u32x4 o;
;           o.x = pack2(v0[0] * s0[0] * siluf_(bflo(z[m].x)), v0[1] * s0[1] * siluf_(bfhi(z[m].x)));
;           o.y = pack2(v0[2] * s0[2] * siluf_(bflo(z[m].y)), v0[3] * s0[3] * siluf_(bfhi(z[m].y)));
;           o.z = pack2(v1[0] * s1[0] * siluf_(bflo(z[m].z)), v1[1] * s1[1] * siluf_(bfhi(z[m].z)));
;           o.w = pack2(v1[2] * s1[2] * siluf_(bflo(z[m].w)), v1[3] * s1[3] * siluf_(bfhi(z[m].w)));
;           *(u32x4*)(y0 + row * DM + c) = o;
;         }
	v_add_f32_e32 v2, 1.0, v2
	v_rcp_f32_e32 v23, v2
	s_nop 0
	v_pk_mul_f32 v[20:21], v[22:23], v[20:21]
	s_nop 0
	v_mul_f32_e32 v2, v20, v21
	v_and_b32_e32 v21, 0xffff0000, v40
	v_mul_f32_e32 v16, 0xbfb8aa3b, v21
	v_exp_f32_e32 v16, v16
	v_mov_b32_e32 v22, v17
	v_mov_b32_e32 v20, v73
	v_add_f32_e32 v16, 1.0, v16
	v_rcp_f32_e32 v23, v16
	s_nop 0
	v_pk_mul_f32 v[16:17], v[22:23], v[20:21]
	s_nop 0
	v_mul_f32_e32 v16, v16, v17
	v_lshlrev_b32_e32 v21, 16, v41
	v_cvt_pk_bf16_f32 v16, v2, v16
	v_mul_f32_e32 v2, 0xbfb8aa3b, v21
	v_exp_f32_e32 v2, v2
	v_mov_b32_e32 v22, v18
	v_mov_b32_e32 v20, v74
	v_add_f32_e32 v2, 1.0, v2
	v_rcp_f32_e32 v23, v2
	s_nop 0
	v_pk_mul_f32 v[20:21], v[22:23], v[20:21]
	s_nop 0
	v_mul_f32_e32 v2, v20, v21
	v_and_b32_e32 v21, 0xffff0000, v41
	v_mul_f32_e32 v17, 0xbfb8aa3b, v21
	v_exp_f32_e32 v17, v17
	v_mov_b32_e32 v22, v19
	v_mov_b32_e32 v20, v75
	v_add_f32_e32 v17, 1.0, v17
	v_rcp_f32_e32 v23, v17
	s_nop 0
	v_pk_mul_f32 v[18:19], v[22:23], v[20:21]
	s_nop 0
	v_mul_f32_e32 v17, v18, v19
	v_lshlrev_b32_e32 v19, 16, v42
	v_cvt_pk_bf16_f32 v17, v2, v17
	v_mul_f32_e32 v2, 0xbfb8aa3b, v19
	v_exp_f32_e32 v2, v2
	v_mov_b32_e32 v20, v12
	v_mov_b32_e32 v18, v68
	v_add_f32_e32 v2, 1.0, v2
	v_rcp_f32_e32 v21, v2
	s_nop 0
	v_pk_mul_f32 v[18:19], v[20:21], v[18:19]
	s_nop 0
	v_mul_f32_e32 v2, v18, v19
	v_and_b32_e32 v19, 0xffff0000, v42
	v_mul_f32_e32 v12, 0xbfb8aa3b, v19
	v_exp_f32_e32 v12, v12
	v_mov_b32_e32 v20, v13
	v_mov_b32_e32 v18, v69
	v_add_f32_e32 v12, 1.0, v12
	v_rcp_f32_e32 v21, v12
	s_nop 0
	v_pk_mul_f32 v[12:13], v[20:21], v[18:19]
	s_nop 0
	v_mul_f32_e32 v12, v12, v13
	v_lshlrev_b32_e32 v13, 16, v43
	v_cvt_pk_bf16_f32 v18, v2, v12
	v_mul_f32_e32 v2, 0xbfb8aa3b, v13
	v_exp_f32_e32 v2, v2
	v_mov_b32_e32 v20, v14
	v_mov_b32_e32 v12, v70
	v_mov_b32_e32 v14, v8
	v_add_f32_e32 v2, 1.0, v2
	v_rcp_f32_e32 v21, v2
	s_nop 0
	v_pk_mul_f32 v[12:13], v[20:21], v[12:13]
	s_nop 0
	v_mul_f32_e32 v2, v12, v13
	v_and_b32_e32 v13, 0xffff0000, v43
	v_mul_f32_e32 v12, 0xbfb8aa3b, v13
	v_exp_f32_e32 v12, v12
	v_mov_b32_e32 v20, v15
	v_add_f32_e32 v12, 1.0, v12
	v_rcp_f32_e32 v21, v12
	v_mov_b32_e32 v12, v71
	v_pk_mul_f32 v[12:13], v[20:21], v[12:13]
	s_nop 0
	v_mul_f32_e32 v12, v12, v13
	v_lshlrev_b32_e32 v13, 16, v36
	v_cvt_pk_bf16_f32 v19, v2, v12
	v_mul_f32_e32 v2, 0xbfb8aa3b, v13
	v_exp_f32_e32 v2, v2
	v_mov_b32_e32 v12, v72
	flat_store_dwordx4 v[104:105], v[16:19] offset:256
	v_add_f32_e32 v2, 1.0, v2
	v_rcp_f32_e32 v15, v2
	s_nop 0
	v_pk_mul_f32 v[12:13], v[14:15], v[12:13]
	s_nop 0
	v_mul_f32_e32 v2, v12, v13
	v_and_b32_e32 v13, 0xffff0000, v36
	v_mul_f32_e32 v8, 0xbfb8aa3b, v13
	v_exp_f32_e32 v8, v8
	v_mov_b32_e32 v14, v9
	v_mov_b32_e32 v12, v73
	v_add_f32_e32 v8, 1.0, v8
	v_rcp_f32_e32 v15, v8
	s_nop 0
	v_pk_mul_f32 v[8:9], v[14:15], v[12:13]
	s_nop 0
	v_mul_f32_e32 v8, v8, v9
	v_lshlrev_b32_e32 v13, 16, v37
	v_cvt_pk_bf16_f32 v8, v2, v8
	v_mul_f32_e32 v2, 0xbfb8aa3b, v13
	v_exp_f32_e32 v2, v2
	v_mov_b32_e32 v14, v10
	v_mov_b32_e32 v12, v74
	v_add_f32_e32 v2, 1.0, v2
	v_rcp_f32_e32 v15, v2
	s_nop 0
	v_pk_mul_f32 v[12:13], v[14:15], v[12:13]
	s_nop 0
	v_mul_f32_e32 v2, v12, v13
	v_and_b32_e32 v13, 0xffff0000, v37
	v_mul_f32_e32 v9, 0xbfb8aa3b, v13
	v_exp_f32_e32 v9, v9
	v_mov_b32_e32 v14, v11
	v_mov_b32_e32 v12, v75
	v_add_f32_e32 v9, 1.0, v9
	v_rcp_f32_e32 v15, v9
	s_nop 0
	v_pk_mul_f32 v[10:11], v[14:15], v[12:13]
	s_nop 0
	v_mul_f32_e32 v9, v10, v11
	v_lshlrev_b32_e32 v11, 16, v38
	v_cvt_pk_bf16_f32 v9, v2, v9
	v_mul_f32_e32 v2, 0xbfb8aa3b, v11
	v_exp_f32_e32 v2, v2
	v_mov_b32_e32 v12, v4
	v_mov_b32_e32 v10, v68
	v_add_f32_e32 v2, 1.0, v2
	v_rcp_f32_e32 v13, v2
	s_nop 0
	v_pk_mul_f32 v[10:11], v[12:13], v[10:11]
	s_nop 0
	v_mul_f32_e32 v2, v10, v11
	v_and_b32_e32 v11, 0xffff0000, v38
	v_mul_f32_e32 v4, 0xbfb8aa3b, v11
	v_exp_f32_e32 v4, v4
	v_mov_b32_e32 v12, v5
	v_mov_b32_e32 v10, v69
	v_add_f32_e32 v4, 1.0, v4
	v_rcp_f32_e32 v13, v4
	s_nop 0
	v_pk_mul_f32 v[4:5], v[12:13], v[10:11]
	s_nop 0
	v_mul_f32_e32 v4, v4, v5
	v_lshlrev_b32_e32 v5, 16, v39
	v_cvt_pk_bf16_f32 v10, v2, v4
	v_mul_f32_e32 v2, 0xbfb8aa3b, v5
	v_exp_f32_e32 v2, v2
	v_mov_b32_e32 v12, v6
	v_mov_b32_e32 v4, v70
	v_add_f32_e32 v2, 1.0, v2
	v_rcp_f32_e32 v13, v2
	s_nop 0
	v_pk_mul_f32 v[4:5], v[12:13], v[4:5]
	s_nop 0
	v_mul_f32_e32 v2, v4, v5
	v_and_b32_e32 v5, 0xffff0000, v39
	v_mul_f32_e32 v4, 0xbfb8aa3b, v5
	v_exp_f32_e32 v4, v4
	v_mov_b32_e32 v12, v7
	v_add_f32_e32 v4, 1.0, v4
	v_rcp_f32_e32 v13, v4
	v_mov_b32_e32 v4, v71
	v_pk_mul_f32 v[4:5], v[12:13], v[4:5]
	s_nop 0
	v_mul_f32_e32 v4, v4, v5
	v_cvt_pk_bf16_f32 v11, v2, v4
	flat_store_dwordx4 v[92:93], v[8:11] offset:256
	s_cbranch_vccz .LBB0_482
	s_waitcnt vmcnt(0)
	v_readlane_b32 s44, v244, 59
	v_readlane_b32 s40, v243, 18
	s_cmpk_gt_u32 s24, 0xff
	s_mov_b32 s43, 0x800000
	v_readlane_b32 s45, v244, 60
	v_readlane_b32 s46, v244, 61
	v_readlane_b32 s47, v244, 62
	v_readlane_b32 s48, v244, 63
	v_readlane_b32 s49, v243, 0
	v_readlane_b32 s50, v243, 1
	v_readlane_b32 s51, v243, 2
	v_readlane_b32 s41, v243, 19
	s_cbranch_scc1 .LBB0_489
	s_barrier

; #define PG8_WAIT_V(n) asm volatile("s_waitcnt vmcnt(" #n ")" ::: "memory")
; #define PG8_WAIT_L(n) asm volatile("s_waitcnt lgkmcnt(" #n ")" ::: "memory")
; #define PG8_BAR __builtin_amdgcn_s_barrier()
; #define PG8_SCHED __builtin_amdgcn_sched_barrier(0)
; template <class Epi, class AddrA, class AddrB>
; __device__ __forceinline__ void gemm_phase(const Sched S, const int lda, const int ldb, const int K, const AddrA addrA,
;                                            const AddrB addrB, const Epi E) {
;     ...
;     for (int t = 0; t < nt; t += 2) {
;       const bool last = (t == nt - 2);
;       const char* a1 = cA + (size_t)(t + 1) * kstep;
;       const char* a2 = last ? nA : cA + (size_t)(t + 2) * kstep;
;       const char* b2 = last ? nB : cB + (size_t)(t + 2) * kstep;
;       const char* a3 = a2 + kstep;
;       const char* b3 = b2 + kstep;
;       PG8_LDB(B0, 0, 0); PG8_SCHED; PG8_LDA(At, 0, 0); PG8_STAGE(PG8_SA(1, 1), a1 + hstepA, voffA);
;       PG8_WAIT_L(8); PG8_BAR; PG8_WAIT_L(0); PG8_MMA(0, 0, At, B0); PG8_BAR; PG8_SCHED;
;       PG8_LDB(B1, 0, 1); PG8_STAGE(PG8_SB(0, 0), b2, voffB);
;       PG8_BAR; PG8_WAIT_L(0); PG8_MMA(0, 1, At, B1); PG8_BAR;
;       PG8_LDA(At, 0, 1); PG8_STAGE(PG8_SA(0, 0), a2, voffA);
;       PG8_BAR; PG8_WAIT_L(0); PG8_MMA(1, 0, At, B0); PG8_BAR; PG8_SCHED;
;       PG8_STAGE(PG8_SB(0, 1), b2 + hstepB, voffB);
;       PG8_WAIT_V(6); PG8_BAR; PG8_MMA(1, 1, At, B1); PG8_BAR;
.LBB0_543:
	s_add_u32 s4, s2, 0xfff80080
	s_addc_u32 s5, s3, -1
	s_add_i32 s43, 0, 0x10000
	v_add_u32_e32 v0, s43, v167
	ds_read_b128 v[132:135], v0
	ds_read_b128 v[136:139], v0 offset:1024
	ds_read_b128 v[140:143], v0 offset:2048
	ds_read_b128 v[144:147], v0 offset:3072
	s_cmp_eq_u32 s42, 28
	s_cselect_b32 s7, s1, s5
	s_cselect_b32 s6, s9, s4
	s_cselect_b32 s5, s13, s41
	s_cselect_b32 s4, s15, s33
	v_lshl_add_u64 v[0:1], s[2:3], 0, v[180:181]
	s_add_i32 m0, s28, 0xc000
	ds_read_b128 v[148:151], v188
	ds_read_b128 v[152:155], v188 offset:1024
	ds_read_b128 v[156:159], v188 offset:2048
	ds_read_b128 v[160:163], v188 offset:3072
	ds_read_b128 v[182:185], v188 offset:4096
	ds_read_b128 v[190:193], v188 offset:5120
	ds_read_b128 v[194:197], v188 offset:6144
	ds_read_b128 v[212:215], v188 offset:7168
	global_load_lds_dwordx4 v[0:1], off
	v_lshl_add_u64 v[0:1], s[2:3], 0, v[178:179]
	s_add_i32 m0, s28, 0xe000
	s_nop 0
	global_load_lds_dwordx4 v[0:1], off
	s_waitcnt lgkmcnt(8)
	s_setprio 1
	s_barrier
	s_waitcnt lgkmcnt(0)
	v_mfma_f32_16x16x32_bf16 v[128:131], v[132:135], v[148:151], v[128:131]
	v_mfma_f32_16x16x32_bf16 v[128:131], v[136:139], v[152:155], v[128:131]
	v_mfma_f32_16x16x32_bf16 v[120:123], v[132:135], v[156:159], v[120:123]
	v_mfma_f32_16x16x32_bf16 v[120:123], v[136:139], v[160:163], v[120:123]
	v_mfma_f32_16x16x32_bf16 v[112:115], v[132:135], v[182:185], v[112:115]
	v_mfma_f32_16x16x32_bf16 v[112:115], v[136:139], v[190:193], v[112:115]
	v_mfma_f32_16x16x32_bf16 v[104:107], v[132:135], v[194:197], v[104:107]
	v_mfma_f32_16x16x32_bf16 v[104:107], v[136:139], v[212:215], v[104:107]
	v_mfma_f32_16x16x32_bf16 v[124:127], v[140:143], v[148:151], v[124:127]
	v_mfma_f32_16x16x32_bf16 v[124:127], v[144:147], v[152:155], v[124:127]
	v_mfma_f32_16x16x32_bf16 v[116:119], v[140:143], v[156:159], v[116:119]
	v_mfma_f32_16x16x32_bf16 v[116:119], v[144:147], v[160:163], v[116:119]
	v_mfma_f32_16x16x32_bf16 v[108:111], v[140:143], v[182:185], v[108:111]
	v_mfma_f32_16x16x32_bf16 v[108:111], v[144:147], v[190:193], v[108:111]
	v_mfma_f32_16x16x32_bf16 v[100:103], v[140:143], v[194:197], v[100:103]
	v_mfma_f32_16x16x32_bf16 v[100:103], v[144:147], v[212:215], v[100:103]
	s_barrier
	s_setprio 0
	s_add_i32 s46, 0, 0x14000
	v_add_u32_e32 v0, s46, v167
	s_add_i32 s43, s43, s27
	ds_read_b128 v[216:219], v0
	ds_read_b128 v[220:223], v0 offset:1024
	ds_read_b128 v[224:227], v0 offset:2048
	ds_read_b128 v[228:231], v0 offset:3072
	v_lshl_add_u64 v[0:1], s[4:5], 0, v[172:173]
	s_mov_b32 m0, s43
	v_lshl_add_u64 v[232:233], s[4:5], 0, v[168:169]
	global_load_lds_dwordx4 v[0:1], off
	s_add_i32 m0, s43, 0x2000
	s_nop 0
	global_load_lds_dwordx4 v[232:233], off
	s_setprio 1
	s_barrier
	s_waitcnt lgkmcnt(0)
	v_mfma_f32_16x16x32_bf16 v[96:99], v[216:219], v[148:151], v[96:99]
	v_mfma_f32_16x16x32_bf16 v[96:99], v[220:223], v[152:155], v[96:99]
	v_mfma_f32_16x16x32_bf16 v[88:91], v[216:219], v[156:159], v[88:91]
	v_mfma_f32_16x16x32_bf16 v[88:91], v[220:223], v[160:163], v[88:91]
	v_mfma_f32_16x16x32_bf16 v[80:83], v[216:219], v[182:185], v[80:83]
	v_mfma_f32_16x16x32_bf16 v[80:83], v[220:223], v[190:193], v[80:83]
	v_mfma_f32_16x16x32_bf16 v[72:75], v[216:219], v[194:197], v[72:75]
	v_mfma_f32_16x16x32_bf16 v[72:75], v[220:223], v[212:215], v[72:75]
	v_mfma_f32_16x16x32_bf16 v[92:95], v[224:227], v[148:151], v[92:95]
	v_mfma_f32_16x16x32_bf16 v[92:95], v[228:231], v[152:155], v[92:95]
	v_mfma_f32_16x16x32_bf16 v[84:87], v[224:227], v[156:159], v[84:87]
	v_mfma_f32_16x16x32_bf16 v[84:87], v[228:231], v[160:163], v[84:87]
	v_mfma_f32_16x16x32_bf16 v[76:79], v[224:227], v[182:185], v[76:79]
	v_mfma_f32_16x16x32_bf16 v[76:79], v[228:231], v[190:193], v[76:79]
	v_mfma_f32_16x16x32_bf16 v[68:71], v[224:227], v[194:197], v[68:71]
	v_mfma_f32_16x16x32_bf16 v[68:71], v[228:231], v[212:215], v[68:71]
	s_mov_b32 m0, s28
	v_lshl_add_u64 v[234:235], s[6:7], 0, v[174:175]
	s_barrier
	s_setprio 0
	ds_read_b128 v[148:151], v188 offset:16384
	ds_read_b128 v[152:155], v188 offset:17408
	ds_read_b128 v[156:159], v188 offset:18432
	ds_read_b128 v[160:163], v188 offset:19456
	ds_read_b128 v[182:185], v188 offset:20480
	ds_read_b128 v[190:193], v188 offset:21504
	ds_read_b128 v[194:197], v188 offset:22528
	ds_read_b128 v[212:215], v188 offset:23552
	global_load_lds_dwordx4 v[234:235], off
	v_lshl_add_u64 v[236:237], s[6:7], 0, v[170:171]
	s_mov_b32 m0, s29
	s_nop 0
	global_load_lds_dwordx4 v[236:237], off
	s_setprio 1
	s_barrier
	s_waitcnt lgkmcnt(0)
	v_mfma_f32_16x16x32_bf16 v[64:67], v[132:135], v[148:151], v[64:67]
	v_mfma_f32_16x16x32_bf16 v[64:67], v[136:139], v[152:155], v[64:67]
	v_mfma_f32_16x16x32_bf16 v[56:59], v[132:135], v[156:159], v[56:59]
	v_mfma_f32_16x16x32_bf16 v[56:59], v[136:139], v[160:163], v[56:59]
	v_mfma_f32_16x16x32_bf16 v[48:51], v[132:135], v[182:185], v[48:51]
	v_mfma_f32_16x16x32_bf16 v[48:51], v[136:139], v[190:193], v[48:51]
	v_mfma_f32_16x16x32_bf16 v[40:43], v[132:135], v[194:197], v[40:43]
	v_mfma_f32_16x16x32_bf16 v[40:43], v[136:139], v[212:215], v[40:43]
	v_mfma_f32_16x16x32_bf16 v[60:63], v[140:143], v[148:151], v[60:63]
	v_mfma_f32_16x16x32_bf16 v[60:63], v[144:147], v[152:155], v[60:63]
	v_mfma_f32_16x16x32_bf16 v[52:55], v[140:143], v[156:159], v[52:55]
	v_mfma_f32_16x16x32_bf16 v[52:55], v[144:147], v[160:163], v[52:55]
	v_mfma_f32_16x16x32_bf16 v[44:47], v[140:143], v[182:185], v[44:47]
	v_mfma_f32_16x16x32_bf16 v[44:47], v[144:147], v[190:193], v[44:47]
	v_mfma_f32_16x16x32_bf16 v[36:39], v[140:143], v[194:197], v[36:39]
	v_mfma_f32_16x16x32_bf16 v[36:39], v[144:147], v[212:215], v[36:39]
	s_barrier
; #define PG8_WAIT_V(n) asm volatile("s_waitcnt vmcnt(" #n ")" ::: "memory")
; #define PG8_WAIT_L(n) asm volatile("s_waitcnt lgkmcnt(" #n ")" ::: "memory")
; #define PG8_BAR __builtin_amdgcn_s_barrier()
; #define PG8_SCHED __builtin_amdgcn_sched_barrier(0)
; template <class Epi, class AddrA, class AddrB>
; __device__ __forceinline__ void gemm_phase(const Sched S, const int lda, const int ldb, const int K, const AddrA addrA,
;                                            const AddrB addrB, const Epi E) {
;     ...
;       PG8_STAGE(PG8_SB(0, 1), b2 + hstepB, voffB);
;       PG8_WAIT_V(6); PG8_BAR; PG8_MMA(1, 1, At, B1); PG8_BAR;
;       PG8_LDB(B0, 1, 0); PG8_SCHED; PG8_LDA(At, 1, 0); PG8_STAGE(PG8_SA(0, 1), a2 + hstepA, voffA);
;       PG8_WAIT_L(8); PG8_BAR; PG8_WAIT_L(0); PG8_MMA(0, 0, At, B0); PG8_BAR; PG8_SCHED;
;       PG8_LDB(B1, 1, 1); PG8_STAGE(PG8_SB(1, 0), b3, voffB);
;       PG8_BAR; PG8_WAIT_L(0); PG8_MMA(0, 1, At, B1); PG8_BAR;
;       PG8_LDA(At, 1, 1); PG8_STAGE(PG8_SA(1, 0), a3, voffA);
;       PG8_BAR; PG8_WAIT_L(0); PG8_MMA(1, 0, At, B0); PG8_BAR; PG8_SCHED;
	s_setprio 0
	s_add_u32 s44, s4, 0x80000
	s_addc_u32 s45, s5, 0
	s_add_i32 s43, s46, s27
	v_lshl_add_u64 v[132:133], s[44:45], 0, v[172:173]
	s_mov_b32 m0, s43
	s_nop 0
	global_load_lds_dwordx4 v[132:133], off
	v_lshl_add_u64 v[132:133], s[44:45], 0, v[168:169]
	s_add_i32 m0, s43, 0x2000
	s_nop 0
	global_load_lds_dwordx4 v[132:133], off
	s_waitcnt vmcnt(6)
	s_setprio 1
	s_barrier
	v_mfma_f32_16x16x32_bf16 v[32:35], v[216:219], v[148:151], v[32:35]
	v_mfma_f32_16x16x32_bf16 v[32:35], v[220:223], v[152:155], v[32:35]
	v_mfma_f32_16x16x32_bf16 v[24:27], v[216:219], v[156:159], v[24:27]
	v_mfma_f32_16x16x32_bf16 v[24:27], v[220:223], v[160:163], v[24:27]
	v_mfma_f32_16x16x32_bf16 v[16:19], v[216:219], v[182:185], v[16:19]
	v_mfma_f32_16x16x32_bf16 v[16:19], v[220:223], v[190:193], v[16:19]
	v_mfma_f32_16x16x32_bf16 v[8:11], v[216:219], v[194:197], v[8:11]
	v_mfma_f32_16x16x32_bf16 v[8:11], v[220:223], v[212:215], v[8:11]
	v_mfma_f32_16x16x32_bf16 v[28:31], v[224:227], v[148:151], v[28:31]
	v_mfma_f32_16x16x32_bf16 v[28:31], v[228:231], v[152:155], v[28:31]
	v_mfma_f32_16x16x32_bf16 v[20:23], v[224:227], v[156:159], v[20:23]
	v_mfma_f32_16x16x32_bf16 v[20:23], v[228:231], v[160:163], v[20:23]
	v_mfma_f32_16x16x32_bf16 v[12:15], v[224:227], v[182:185], v[12:15]
	v_mfma_f32_16x16x32_bf16 v[12:15], v[228:231], v[190:193], v[12:15]
	v_mfma_f32_16x16x32_bf16 v[4:7], v[224:227], v[194:197], v[4:7]
	v_mfma_f32_16x16x32_bf16 v[4:7], v[228:231], v[212:215], v[4:7]
	s_add_i32 s43, 0, 0x18000
	v_add_u32_e32 v2, s43, v167
	s_barrier
	s_setprio 0
	ds_read_b128 v[132:135], v2
	ds_read_b128 v[136:139], v2 offset:1024
	ds_read_b128 v[140:143], v2 offset:2048
	ds_read_b128 v[144:147], v2 offset:3072
	s_add_u32 s6, s6, 0x80000
	s_addc_u32 s7, s7, 0
	s_mov_b32 m0, s30
	v_lshl_add_u64 v[216:217], s[6:7], 0, v[174:175]
	ds_read_b128 v[148:151], v188 offset:32768
	ds_read_b128 v[152:155], v188 offset:33792
	ds_read_b128 v[156:159], v188 offset:34816
	ds_read_b128 v[160:163], v188 offset:35840
	ds_read_b128 v[182:185], v188 offset:36864
	ds_read_b128 v[190:193], v188 offset:37888
	ds_read_b128 v[194:197], v188 offset:38912
	ds_read_b128 v[212:215], v188 offset:39936
	global_load_lds_dwordx4 v[216:217], off
	v_lshl_add_u64 v[216:217], s[6:7], 0, v[170:171]
	s_mov_b32 m0, s31
	s_nop 0
	global_load_lds_dwordx4 v[216:217], off
	s_waitcnt lgkmcnt(8)
	s_setprio 1
	s_barrier
	s_waitcnt lgkmcnt(0)
	v_mfma_f32_16x16x32_bf16 v[128:131], v[132:135], v[148:151], v[128:131]
	v_mfma_f32_16x16x32_bf16 v[128:131], v[136:139], v[152:155], v[128:131]
	v_mfma_f32_16x16x32_bf16 v[120:123], v[132:135], v[156:159], v[120:123]
	v_mfma_f32_16x16x32_bf16 v[120:123], v[136:139], v[160:163], v[120:123]
	v_mfma_f32_16x16x32_bf16 v[112:115], v[132:135], v[182:185], v[112:115]
	v_mfma_f32_16x16x32_bf16 v[112:115], v[136:139], v[190:193], v[112:115]
	v_mfma_f32_16x16x32_bf16 v[104:107], v[132:135], v[194:197], v[104:107]
	v_mfma_f32_16x16x32_bf16 v[104:107], v[136:139], v[212:215], v[104:107]
	v_mfma_f32_16x16x32_bf16 v[124:127], v[140:143], v[148:151], v[124:127]
	v_mfma_f32_16x16x32_bf16 v[124:127], v[144:147], v[152:155], v[124:127]
	v_mfma_f32_16x16x32_bf16 v[116:119], v[140:143], v[156:159], v[116:119]
	v_mfma_f32_16x16x32_bf16 v[116:119], v[144:147], v[160:163], v[116:119]
	v_mfma_f32_16x16x32_bf16 v[108:111], v[140:143], v[182:185], v[108:111]
	v_mfma_f32_16x16x32_bf16 v[108:111], v[144:147], v[190:193], v[108:111]
	v_mfma_f32_16x16x32_bf16 v[100:103], v[140:143], v[194:197], v[100:103]
	v_mfma_f32_16x16x32_bf16 v[100:103], v[144:147], v[212:215], v[100:103]
	s_barrier
	s_setprio 0
	s_add_i32 s6, 0, 0x1c000
	s_add_i32 s7, s43, s27
	v_add_u32_e32 v2, s6, v167
	v_lshl_add_u64 v[0:1], v[0:1], 0, s[52:53]
	s_mov_b32 m0, s7
	ds_read_b128 v[216:219], v2
	ds_read_b128 v[220:223], v2 offset:1024
	ds_read_b128 v[224:227], v2 offset:2048
	ds_read_b128 v[228:231], v2 offset:3072
	global_load_lds_dwordx4 v[0:1], off
	v_lshl_add_u64 v[0:1], v[232:233], 0, s[52:53]
	s_add_i32 m0, s7, 0x2000
	s_nop 0
	global_load_lds_dwordx4 v[0:1], off
	s_setprio 1
	s_barrier
	s_waitcnt lgkmcnt(0)
	v_mfma_f32_16x16x32_bf16 v[96:99], v[216:219], v[148:151], v[96:99]
	v_mfma_f32_16x16x32_bf16 v[96:99], v[220:223], v[152:155], v[96:99]
	v_mfma_f32_16x16x32_bf16 v[88:91], v[216:219], v[156:159], v[88:91]
	v_mfma_f32_16x16x32_bf16 v[88:91], v[220:223], v[160:163], v[88:91]
	v_mfma_f32_16x16x32_bf16 v[80:83], v[216:219], v[182:185], v[80:83]
	v_mfma_f32_16x16x32_bf16 v[80:83], v[220:223], v[190:193], v[80:83]
	v_mfma_f32_16x16x32_bf16 v[72:75], v[216:219], v[194:197], v[72:75]
	v_mfma_f32_16x16x32_bf16 v[72:75], v[220:223], v[212:215], v[72:75]
	v_mfma_f32_16x16x32_bf16 v[92:95], v[224:227], v[148:151], v[92:95]
	v_mfma_f32_16x16x32_bf16 v[92:95], v[228:231], v[152:155], v[92:95]
	v_mfma_f32_16x16x32_bf16 v[84:87], v[224:227], v[156:159], v[84:87]
	v_mfma_f32_16x16x32_bf16 v[84:87], v[228:231], v[160:163], v[84:87]
	v_mfma_f32_16x16x32_bf16 v[76:79], v[224:227], v[182:185], v[76:79]
	v_mfma_f32_16x16x32_bf16 v[76:79], v[228:231], v[190:193], v[76:79]
	v_mfma_f32_16x16x32_bf16 v[68:71], v[224:227], v[194:197], v[68:71]
	v_mfma_f32_16x16x32_bf16 v[68:71], v[228:231], v[212:215], v[68:71]
	s_mov_b32 m0, s38
	v_lshl_add_u64 v[0:1], v[234:235], 0, s[52:53]
	s_barrier
	s_setprio 0
	ds_read_b128 v[148:151], v188 offset:49152
	ds_read_b128 v[152:155], v188 offset:50176
	ds_read_b128 v[156:159], v188 offset:51200
	ds_read_b128 v[160:163], v188 offset:52224
	ds_read_b128 v[182:185], v188 offset:53248
	ds_read_b128 v[190:193], v188 offset:54272
	ds_read_b128 v[194:197], v188 offset:55296
	ds_read_b128 v[212:215], v188 offset:56320
	global_load_lds_dwordx4 v[0:1], off
	v_lshl_add_u64 v[0:1], v[236:237], 0, s[52:53]
	s_mov_b32 m0, s39
	s_nop 0
	global_load_lds_dwordx4 v[0:1], off
	s_setprio 1
	s_barrier
; #define PG8_WAIT_V(n) asm volatile("s_waitcnt vmcnt(" #n ")" ::: "memory")
; #define PG8_WAIT_L(n) asm volatile("s_waitcnt lgkmcnt(" #n ")" ::: "memory")
; #define PG8_BAR __builtin_amdgcn_s_barrier()
; #define PG8_SCHED __builtin_amdgcn_sched_barrier(0)
; template <class Epi, class AddrA, class AddrB>
; __device__ __forceinline__ void gemm_phase(const Sched S, const int lda, const int ldb, const int K, const AddrA addrA,
;                                            const AddrB addrB, const Epi E) {
;     ...
;       PG8_BAR; PG8_WAIT_L(0); PG8_MMA(1, 0, At, B0); PG8_BAR; PG8_SCHED;
;       PG8_STAGE(PG8_SB(1, 1), b3 + hstepB, voffB);
;       PG8_WAIT_V(6); PG8_BAR; PG8_MMA(1, 1, At, B1); PG8_BAR;
;   __device__ __forceinline__ void operator()(EPI_ARGS) const {
;     const int col0 = u.pn * 256 + wc * 32 + 8 * fq;
;     const int br = u.br, brn = br < 2 ? br + 1 : 2;
;     const unsigned loff0 = (unsigned)((wr * 64 + fr) * PLD + wc * 32 + 8 * fq);
;     const bf16_t* pc = proj + ((size_t)((GT + br * DM) / 256 + u.pn) * MTOK + (size_t)u.pm * 256) * PLD;
;     const bf16_t* pn_ = proj + ((size_t)((GT + brn * DM) / 256 + u.pn) * MTOK + (size_t)u.pm * 256) * PLD;
;     bf16_t* mrow = merged + ((size_t)u.pm * 256 + wr * 64 + fr) * DM + col0;
; #pragma unroll
;     for (int bj = 0; bj < 2; ++bj) {
;       const int c = col0 + bj * HALF;
;       float gc[8], gn[8];
;       {
;         const f32x4 a0 = *(const f32x4*)(bg + br * DM + c), a1 = *(const f32x4*)(bg + br * DM + c + 4);
;         const f32x4 b0 = *(const f32x4*)(bg + brn * DM + c), b1 = *(const f32x4*)(bg + brn * DM + c + 4);
; #pragma unroll
;         for (int k = 0; k < 4; ++k) { gc[k] = a0[k]; gc[4 + k] = a1[k]; gn[k] = b0[k]; gn[4 + k] = b1[k]; }
;       }
; #pragma unroll
;       for (int ai = 0; ai < 2; ++ai) {
;         unsigned loff = loff0;
;         asm volatile("" : "+v"(loff));
;         u32x4 zc[4], zn[4];
; #pragma unroll
;         for (int m = 0; m < 4; ++m) {
;           const unsigned o = loff + (unsigned)((ai * HALF + m * 16) * PLD + bj * HALF);
;           zc[m] = *(const u32x4*)(pc + o);
;           zn[m] = *(const u32x4*)(pn_ + o);
;         }
	s_waitcnt lgkmcnt(0)
	v_mfma_f32_16x16x32_bf16 v[64:67], v[132:135], v[148:151], v[64:67]
	v_mfma_f32_16x16x32_bf16 v[64:67], v[136:139], v[152:155], v[64:67]
	v_mfma_f32_16x16x32_bf16 v[56:59], v[132:135], v[156:159], v[56:59]
	v_mfma_f32_16x16x32_bf16 v[56:59], v[136:139], v[160:163], v[56:59]
	v_mfma_f32_16x16x32_bf16 v[48:51], v[132:135], v[182:185], v[48:51]
	v_mfma_f32_16x16x32_bf16 v[48:51], v[136:139], v[190:193], v[48:51]
	v_mfma_f32_16x16x32_bf16 v[40:43], v[132:135], v[194:197], v[40:43]
	v_mfma_f32_16x16x32_bf16 v[40:43], v[136:139], v[212:215], v[40:43]
	v_mfma_f32_16x16x32_bf16 v[60:63], v[140:143], v[148:151], v[60:63]
	v_mfma_f32_16x16x32_bf16 v[60:63], v[144:147], v[152:155], v[60:63]
	v_mfma_f32_16x16x32_bf16 v[52:55], v[140:143], v[156:159], v[52:55]
	v_mfma_f32_16x16x32_bf16 v[52:55], v[144:147], v[160:163], v[52:55]
	v_mfma_f32_16x16x32_bf16 v[44:47], v[140:143], v[182:185], v[44:47]
	v_mfma_f32_16x16x32_bf16 v[44:47], v[144:147], v[190:193], v[44:47]
	v_mfma_f32_16x16x32_bf16 v[36:39], v[140:143], v[194:197], v[36:39]
	v_mfma_f32_16x16x32_bf16 v[36:39], v[144:147], v[212:215], v[36:39]
	s_barrier
	s_setprio 0
	s_add_u32 s4, s4, 0x80080
	s_addc_u32 s5, s5, 0
	s_add_i32 s6, s6, s27
	v_lshl_add_u64 v[0:1], s[4:5], 0, v[172:173]
	s_mov_b32 m0, s6
	s_nop 0
	global_load_lds_dwordx4 v[0:1], off
	v_lshl_add_u64 v[0:1], s[4:5], 0, v[168:169]
	s_add_i32 m0, s6, 0x2000
	s_nop 0
	global_load_lds_dwordx4 v[0:1], off
	s_waitcnt vmcnt(6)
	s_setprio 1
	s_barrier
	v_mfma_f32_16x16x32_bf16 v[32:35], v[216:219], v[148:151], v[32:35]
	v_mfma_f32_16x16x32_bf16 v[32:35], v[220:223], v[152:155], v[32:35]
	v_mfma_f32_16x16x32_bf16 v[24:27], v[216:219], v[156:159], v[24:27]
	v_mfma_f32_16x16x32_bf16 v[24:27], v[220:223], v[160:163], v[24:27]
	v_mfma_f32_16x16x32_bf16 v[16:19], v[216:219], v[182:185], v[16:19]
	v_mfma_f32_16x16x32_bf16 v[16:19], v[220:223], v[190:193], v[16:19]
	v_mfma_f32_16x16x32_bf16 v[8:11], v[216:219], v[194:197], v[8:11]
	v_mfma_f32_16x16x32_bf16 v[8:11], v[220:223], v[212:215], v[8:11]
	v_mfma_f32_16x16x32_bf16 v[28:31], v[224:227], v[148:151], v[28:31]
	v_mfma_f32_16x16x32_bf16 v[28:31], v[228:231], v[152:155], v[28:31]
	v_mfma_f32_16x16x32_bf16 v[20:23], v[224:227], v[156:159], v[20:23]
	v_mfma_f32_16x16x32_bf16 v[20:23], v[228:231], v[160:163], v[20:23]
	v_mfma_f32_16x16x32_bf16 v[12:15], v[224:227], v[182:185], v[12:15]
	v_mfma_f32_16x16x32_bf16 v[12:15], v[228:231], v[190:193], v[12:15]
	v_mfma_f32_16x16x32_bf16 v[4:7], v[224:227], v[194:197], v[4:7]
	v_mfma_f32_16x16x32_bf16 v[4:7], v[228:231], v[212:215], v[4:7]
	s_add_i32 s42, s42, 2
	s_add_u32 s33, s33, 0x100
	s_addc_u32 s41, s41, 0
	s_add_u32 s2, s2, 0x100
	s_addc_u32 s3, s3, 0
	s_cmp_gt_u32 s42, 29
	s_barrier
	s_setprio 0
	s_cbranch_scc0 .LBB0_543
	s_cmp_gt_i32 s10, 1
	s_cselect_b64 s[6:7], -1, 0
	s_lshl_b32 s42, s10, 11
	s_add_i32 s2, s42, 0x4c00
	s_ashr_i32 s2, s2, 8
	s_add_i32 s2, s2, s11
	s_ashr_i32 s3, s2, 31
	s_min_i32 s1, s10, 1
	s_ashr_i32 s9, s8, 31
	s_lshl_b64 s[2:3], s[2:3], 23
	s_add_u32 s2, s34, s2
	s_addc_u32 s3, s35, s3
	s_lshl_b64 s[4:5], s[8:9], 17
	s_add_u32 s2, s2, s4
	s_addc_u32 s3, s3, s5
	s_lshl_b32 s1, s1, 11
	s_add_i32 s44, s1, 0x800
	s_addk_i32 s1, 0x5400
	s_ashr_i32 s1, s1, 8
	s_add_i32 s46, s1, s11
	s_ashr_i32 s47, s46, 31
	s_lshl_b64 s[46:47], s[46:47], 23
	s_add_u32 s1, s34, s46
	v_lshl_or_b32 v132, s11, 8, v187
	s_addc_u32 s11, s35, s47
	s_add_u32 s4, s1, s4
	s_addc_u32 s5, s11, s5
	s_ashr_i32 s43, s42, 31
	s_lshl_b64 s[8:9], s[8:9], 20
	s_ashr_i32 s45, s44, 31
	s_lshl_b64 s[42:43], s[42:43], 2
	s_add_u32 s42, s36, s42
	s_addc_u32 s43, s37, s43
	s_lshl_b64 s[44:45], s[44:45], 2
	s_add_u32 s44, s36, s44
	v_lshl_add_u64 v[0:1], v[176:177], 0, s[8:9]
	v_ashrrev_i32_e32 v133, 31, v132
	s_addc_u32 s45, s37, s45
	v_lshl_add_u64 v[0:1], v[132:133], 1, v[0:1]
	v_lshlrev_b64 v[132:133], 2, v[132:133]
	v_lshl_add_u64 v[182:183], s[42:43], 0, v[132:133]
	v_lshl_add_u64 v[184:185], s[44:45], 0, v[132:133]
	v_mov_b32_e32 v2, v186
	global_load_dwordx4 v[144:147], v[182:183], off
	global_load_dwordx4 v[136:139], v[182:183], off offset:16
	global_load_dwordx4 v[140:143], v[184:185], off
	global_load_dwordx4 v[132:135], v[184:185], off offset:16
	s_cmp_lt_i32 s10, 2
	v_lshlrev_b64 v[148:149], 1, v[2:3]
	v_lshl_add_u64 v[150:151], s[2:3], 0, v[148:149]
	v_lshl_add_u64 v[148:149], s[4:5], 0, v[148:149]
	flat_load_dwordx4 v[190:193], v[150:151]
	flat_load_dwordx4 v[160:163], v[148:149]
	v_add_u32_e32 v148, 0x1000, v2
	v_mov_b32_e32 v149, v3
	v_lshlrev_b64 v[148:149], 1, v[148:149]
	v_lshl_add_u64 v[150:151], s[2:3], 0, v[148:149]
	v_lshl_add_u64 v[148:149], s[4:5], 0, v[148:149]
	flat_load_dwordx4 v[194:197], v[150:151]
	flat_load_dwordx4 v[156:159], v[148:149]
	v_add_u32_e32 v148, 0x2000, v2
	v_mov_b32_e32 v149, v3
	v_lshlrev_b64 v[148:149], 1, v[148:149]
	v_lshl_add_u64 v[150:151], s[2:3], 0, v[148:149]
	v_lshl_add_u64 v[148:149], s[4:5], 0, v[148:149]
	v_add_u32_e32 v2, 0x3000, v2
	flat_load_dwordx4 v[234:237], v[150:151]
	flat_load_dwordx4 v[152:155], v[148:149]
	v_lshlrev_b64 v[148:149], 1, v[2:3]
	v_lshl_add_u64 v[150:151], s[2:3], 0, v[148:149]
	v_lshl_add_u64 v[148:149], s[4:5], 0, v[148:149]
	flat_load_dwordx4 v[238:241], v[150:151]
	s_nop 0
	flat_load_dwordx4 v[148:151], v[148:149]
	s_waitcnt vmcnt(0) lgkmcnt(0)
; __device__ __forceinline__ float sigmoidf_(float x) { return __builtin_amdgcn_rcpf(1.0f + __expf(-x)); }
;   __device__ __forceinline__ void operator()(EPI_ARGS) const {
;     ...
;         if (br < 2) {
; #pragma unroll
;           for (int m = 0; m < 4; ++m) {
;             float xc[8], xn[8];
;             unpack8(zc[m], xc);
;             unpack8(zn[m], xn);
; #pragma unroll
;             for (int k = 0; k < 8; ++k) {
;               const float ec = __expf(-fmaxf(xc[k] + gc[k], -40.f)), en = __expf(-fmaxf(xn[k] + gn[k], -40.f));
;               const float f = (1.0f + en) * __builtin_amdgcn_rcpf(1.0f + ec);
;               acc[ai][bj][m][k >> 2][k & 3] *= f;
;             }
;           }
;         } else {
; #pragma unroll
;           for (int m = 0; m < 4; ++m) {
;             float xc[8], y[8];
;             unpack8(zc[m], xc);
; #pragma unroll
;             for (int k = 0; k < 8; ++k) y[k] = acc[ai][bj][m][k >> 2][k & 3] * sigmoidf_(fmaxf(xc[k] + gc[k], -40.f));
	v_lshlrev_b32_e32 v2, 16, v190
	v_and_b32_e32 v189, 0xffff0000, v190
	v_lshlrev_b32_e32 v190, 16, v191
	v_and_b32_e32 v191, 0xffff0000, v191
	v_lshlrev_b32_e32 v212, 16, v192
	v_and_b32_e32 v192, 0xffff0000, v192
	v_lshlrev_b32_e32 v213, 16, v193
	v_and_b32_e32 v193, 0xffff0000, v193
	v_add_f32_e32 v2, v144, v2
	v_add_f32_e32 v189, v145, v189
	v_add_f32_e32 v190, v146, v190
	v_add_f32_e32 v191, v147, v191
	v_add_f32_e32 v212, v136, v212
	v_add_f32_e32 v192, v137, v192
	v_add_f32_e32 v213, v138, v213
	v_add_f32_e32 v193, v139, v193
	s_mov_b64 s[8:9], -1
	v_max_f32_e32 v233, 0xc2200000, v2
	v_max_f32_e32 v232, 0xc2200000, v189
	v_max_f32_e32 v231, 0xc2200000, v190
	v_max_f32_e32 v230, 0xc2200000, v191
	v_max_f32_e32 v229, 0xc2200000, v212
	v_max_f32_e32 v228, 0xc2200000, v192
	v_max_f32_e32 v227, 0xc2200000, v213
	v_max_f32_e32 v226, 0xc2200000, v193
	v_lshlrev_b32_e32 v225, 16, v194
	v_and_b32_e32 v224, 0xffff0000, v194
	v_lshlrev_b32_e32 v223, 16, v195
	v_and_b32_e32 v222, 0xffff0000, v195
	v_lshlrev_b32_e32 v221, 16, v196
	v_and_b32_e32 v220, 0xffff0000, v196
	v_lshlrev_b32_e32 v219, 16, v197
	v_and_b32_e32 v218, 0xffff0000, v197
	v_lshlrev_b32_e32 v217, 16, v234
	v_and_b32_e32 v216, 0xffff0000, v234
	v_lshlrev_b32_e32 v215, 16, v235
	v_and_b32_e32 v214, 0xffff0000, v235
	v_lshlrev_b32_e32 v213, 16, v236
	v_and_b32_e32 v212, 0xffff0000, v236
	v_lshlrev_b32_e32 v197, 16, v237
	v_and_b32_e32 v196, 0xffff0000, v237
	v_lshlrev_b32_e32 v195, 16, v238
	v_and_b32_e32 v194, 0xffff0000, v238
	v_lshlrev_b32_e32 v193, 16, v239
	v_and_b32_e32 v192, 0xffff0000, v239
	v_lshlrev_b32_e32 v191, 16, v240
	v_and_b32_e32 v190, 0xffff0000, v240
	v_lshlrev_b32_e32 v189, 16, v241
	v_and_b32_e32 v2, 0xffff0000, v241
	s_cbranch_scc1 .LBB0_546
	v_mul_f32_e32 v234, 0xbfb8aa3b, v233
	v_mul_f32_e32 v235, 0xbfb8aa3b, v232
	v_mul_f32_e32 v236, 0xbfb8aa3b, v231
	v_exp_f32_e32 v234, v234
	v_exp_f32_e32 v235, v235
	v_exp_f32_e32 v236, v236
	v_mul_f32_e32 v237, 0xbfb8aa3b, v230
	v_exp_f32_e32 v237, v237
	v_mul_f32_e32 v238, 0xbfb8aa3b, v229
	v_mul_f32_e32 v239, 0xbfb8aa3b, v228
	v_add_f32_e32 v234, 1.0, v234
	v_add_f32_e32 v235, 1.0, v235
	v_add_f32_e32 v236, 1.0, v236
	v_exp_f32_e32 v238, v238
	v_exp_f32_e32 v239, v239
	v_mul_f32_e32 v240, 0xbfb8aa3b, v227
	v_mul_f32_e32 v241, 0xbfb8aa3b, v226
	v_rcp_f32_e32 v234, v234
	v_rcp_f32_e32 v235, v235
	v_rcp_f32_e32 v236, v236
	v_add_f32_e32 v237, 1.0, v237
	v_exp_f32_e32 v240, v240
	v_exp_f32_e32 v241, v241
	v_rcp_f32_e32 v237, v237
	v_add_f32_e32 v238, 1.0, v238
	v_add_f32_e32 v239, 1.0, v239
	v_mul_f32_e32 v234, v128, v234
	v_mul_f32_e32 v235, v129, v235
	v_mul_f32_e32 v236, v130, v236
	v_rcp_f32_e32 v238, v238
	v_rcp_f32_e32 v239, v239
	v_add_f32_e32 v240, 1.0, v240
	v_add_f32_e32 v241, 1.0, v241
	v_mul_f32_e32 v237, v131, v237
	v_rcp_f32_e32 v240, v240
	v_rcp_f32_e32 v241, v241
	v_cvt_pk_bf16_f32 v234, v234, v235
	v_cvt_pk_bf16_f32 v235, v236, v237
	v_add_f32_e32 v236, v144, v225
	v_max_f32_e32 v236, 0xc2200000, v236
	v_mul_f32_e32 v236, 0xbfb8aa3b, v236
	v_mul_f32_e32 v238, v124, v238
	v_mul_f32_e32 v239, v125, v239
	v_exp_f32_e32 v242, v236
	v_cvt_pk_bf16_f32 v236, v238, v239
	v_mul_f32_e32 v240, v126, v240
	v_mul_f32_e32 v241, v127, v241
	v_cvt_pk_bf16_f32 v237, v240, v241
	flat_store_dwordx4 v[0:1], v[234:237]
	v_add_f32_e32 v238, v136, v221
	v_max_f32_e32 v238, 0xc2200000, v238
	v_add_f32_e32 v235, v145, v224
	v_add_f32_e32 v236, v146, v223
	v_max_f32_e32 v235, 0xc2200000, v235
	v_max_f32_e32 v236, 0xc2200000, v236
	v_add_f32_e32 v237, v147, v222
	v_add_f32_e32 v239, v137, v220
	v_mul_f32_e32 v235, 0xbfb8aa3b, v235
	v_mul_f32_e32 v236, 0xbfb8aa3b, v236
	v_max_f32_e32 v237, 0xc2200000, v237
	v_mul_f32_e32 v238, 0xbfb8aa3b, v238
	v_max_f32_e32 v239, 0xc2200000, v239
	v_exp_f32_e32 v235, v235
	v_exp_f32_e32 v236, v236
	v_mul_f32_e32 v237, 0xbfb8aa3b, v237
	v_exp_f32_e32 v238, v238
	v_mul_f32_e32 v239, 0xbfb8aa3b, v239
	v_add_f32_e32 v240, v138, v219
	v_exp_f32_e32 v237, v237
	v_exp_f32_e32 v239, v239
	v_max_f32_e32 v240, 0xc2200000, v240
	v_add_f32_e32 v241, v139, v218
	v_mul_f32_e32 v240, 0xbfb8aa3b, v240
	v_max_f32_e32 v241, 0xc2200000, v241
	v_exp_f32_e32 v240, v240
	v_mul_f32_e32 v241, 0xbfb8aa3b, v241
	v_add_f32_e32 v234, 1.0, v242
	v_add_f32_e32 v235, 1.0, v235
	v_add_f32_e32 v236, 1.0, v236
	v_add_f32_e32 v238, 1.0, v238
	v_exp_f32_e32 v241, v241
	v_rcp_f32_e32 v234, v234
	v_rcp_f32_e32 v235, v235
	v_rcp_f32_e32 v236, v236
	v_add_f32_e32 v237, 1.0, v237
	v_rcp_f32_e32 v238, v238
	v_add_f32_e32 v239, 1.0, v239
	v_rcp_f32_e32 v237, v237
	v_rcp_f32_e32 v239, v239
	v_add_f32_e32 v240, 1.0, v240
	v_rcp_f32_e32 v240, v240
	v_add_f32_e32 v241, 1.0, v241
	v_mul_f32_e32 v234, v120, v234
; __device__ __forceinline__ float sigmoidf_(float x) { return __builtin_amdgcn_rcpf(1.0f + __expf(-x)); }
;   __device__ __forceinline__ void operator()(EPI_ARGS) const {
;     ...
;           for (int m = 0; m < 4; ++m) {
;             float xc[8], y[8];
;             unpack8(zc[m], xc);
; #pragma unroll
;             for (int k = 0; k < 8; ++k) y[k] = acc[ai][bj][m][k >> 2][k & 3] * sigmoidf_(fmaxf(xc[k] + gc[k], -40.f));
;             u32x4 o;
;             o.x = pack2(y[0], y[1]); o.y = pack2(y[2], y[3]); o.z = pack2(y[4], y[5]); o.w = pack2(y[6], y[7]);
;             *(u32x4*)(mrow + (size_t)(ai * HALF + m * 16) * DM + bj * HALF) = o;
;           }
	v_mul_f32_e32 v235, v121, v235
	v_mul_f32_e32 v236, v122, v236
	v_rcp_f32_e32 v241, v241
	v_mul_f32_e32 v238, v116, v238
	v_mul_f32_e32 v237, v123, v237
	v_mul_f32_e32 v239, v117, v239
	v_cvt_pk_bf16_f32 v234, v234, v235
	v_cvt_pk_bf16_f32 v235, v236, v237
	v_cvt_pk_bf16_f32 v236, v238, v239
	v_add_f32_e32 v238, v144, v217
	v_max_f32_e32 v238, 0xc2200000, v238
	v_mul_f32_e32 v240, v118, v240
	v_mul_f32_e32 v238, 0xbfb8aa3b, v238
	v_mul_f32_e32 v241, v119, v241
	v_cvt_pk_bf16_f32 v237, v240, v241
	v_exp_f32_e32 v240, v238
	v_add_co_u32_e32 v238, vcc, s67, v0
	v_add_f32_e32 v241, v139, v196
	s_nop 0
	v_addc_co_u32_e32 v239, vcc, 0, v1, vcc
	flat_store_dwordx4 v[238:239], v[234:237]
	v_add_f32_e32 v238, v136, v213
	v_max_f32_e32 v238, 0xc2200000, v238
	v_add_f32_e32 v235, v145, v216
	v_add_f32_e32 v236, v146, v215
	v_max_f32_e32 v235, 0xc2200000, v235
	v_max_f32_e32 v236, 0xc2200000, v236
	v_add_f32_e32 v237, v147, v214
	v_add_f32_e32 v239, v137, v212
	v_mul_f32_e32 v235, 0xbfb8aa3b, v235
	v_mul_f32_e32 v236, 0xbfb8aa3b, v236
	v_max_f32_e32 v237, 0xc2200000, v237
	v_mul_f32_e32 v238, 0xbfb8aa3b, v238
	v_max_f32_e32 v239, 0xc2200000, v239
	v_add_f32_e32 v234, 1.0, v240
	v_exp_f32_e32 v235, v235
	v_exp_f32_e32 v236, v236
	v_mul_f32_e32 v237, 0xbfb8aa3b, v237
	v_exp_f32_e32 v238, v238
	v_mul_f32_e32 v239, 0xbfb8aa3b, v239
	v_add_f32_e32 v240, v138, v197
	v_exp_f32_e32 v237, v237
	v_exp_f32_e32 v239, v239
	v_max_f32_e32 v240, 0xc2200000, v240
	v_mul_f32_e32 v240, 0xbfb8aa3b, v240
	v_max_f32_e32 v241, 0xc2200000, v241
	v_exp_f32_e32 v240, v240
	v_mul_f32_e32 v241, 0xbfb8aa3b, v241
	v_add_f32_e32 v235, 1.0, v235
	v_add_f32_e32 v236, 1.0, v236
	v_add_f32_e32 v238, 1.0, v238
	v_exp_f32_e32 v241, v241
	v_rcp_f32_e32 v234, v234
	v_rcp_f32_e32 v235, v235
	v_rcp_f32_e32 v236, v236
	v_add_f32_e32 v237, 1.0, v237
	v_rcp_f32_e32 v238, v238
	v_add_f32_e32 v239, 1.0, v239
	v_rcp_f32_e32 v237, v237
	v_rcp_f32_e32 v239, v239
	v_add_f32_e32 v240, 1.0, v240
	v_rcp_f32_e32 v240, v240
	v_add_f32_e32 v241, 1.0, v241
	v_mul_f32_e32 v234, v112, v234
	v_mul_f32_e32 v235, v113, v235
	v_mul_f32_e32 v236, v114, v236
	v_rcp_f32_e32 v241, v241
	v_mul_f32_e32 v238, v108, v238
	v_mul_f32_e32 v237, v115, v237
	v_mul_f32_e32 v239, v109, v239
	v_cvt_pk_bf16_f32 v234, v234, v235
	v_cvt_pk_bf16_f32 v235, v236, v237
	v_cvt_pk_bf16_f32 v236, v238, v239
	v_add_f32_e32 v238, v144, v195
	v_max_f32_e32 v238, 0xc2200000, v238
	v_mul_f32_e32 v240, v110, v240
	v_mul_f32_e32 v238, 0xbfb8aa3b, v238
	s_mov_b32 s1, 0x20000
	v_mul_f32_e32 v241, v111, v241
	v_cvt_pk_bf16_f32 v237, v240, v241
	v_exp_f32_e32 v240, v238
	v_add_co_u32_e32 v238, vcc, s1, v0
	v_add_f32_e32 v241, v139, v2
	s_nop 0
	v_addc_co_u32_e32 v239, vcc, 0, v1, vcc
	flat_store_dwordx4 v[238:239], v[234:237]
	v_add_f32_e32 v238, v136, v191
	v_max_f32_e32 v238, 0xc2200000, v238
	v_add_f32_e32 v235, v145, v194
	v_add_f32_e32 v236, v146, v193
	v_max_f32_e32 v235, 0xc2200000, v235
	v_max_f32_e32 v236, 0xc2200000, v236
	v_add_f32_e32 v237, v147, v192
	v_add_f32_e32 v239, v137, v190
	v_mul_f32_e32 v235, 0xbfb8aa3b, v235
	v_mul_f32_e32 v236, 0xbfb8aa3b, v236
	v_max_f32_e32 v237, 0xc2200000, v237
	v_mul_f32_e32 v238, 0xbfb8aa3b, v238
	v_max_f32_e32 v239, 0xc2200000, v239
	v_add_f32_e32 v234, 1.0, v240
	v_exp_f32_e32 v235, v235
	v_exp_f32_e32 v236, v236
	v_mul_f32_e32 v237, 0xbfb8aa3b, v237
	v_exp_f32_e32 v238, v238
	v_mul_f32_e32 v239, 0xbfb8aa3b, v239
	v_add_f32_e32 v240, v138, v189
	v_exp_f32_e32 v237, v237
	v_exp_f32_e32 v239, v239
	v_max_f32_e32 v240, 0xc2200000, v240
	v_max_f32_e32 v241, 0xc2200000, v241
	v_mul_f32_e32 v240, 0xbfb8aa3b, v240
	v_mul_f32_e32 v241, 0xbfb8aa3b, v241
	v_exp_f32_e32 v240, v240
	v_exp_f32_e32 v241, v241
	v_add_f32_e32 v235, 1.0, v235
	v_add_f32_e32 v236, 1.0, v236
	v_add_f32_e32 v238, 1.0, v238
	v_rcp_f32_e32 v234, v234
	v_rcp_f32_e32 v235, v235
	v_rcp_f32_e32 v236, v236
	v_add_f32_e32 v237, 1.0, v237
	v_rcp_f32_e32 v238, v238
	v_add_f32_e32 v239, 1.0, v239
	v_rcp_f32_e32 v237, v237
	v_rcp_f32_e32 v239, v239
	v_add_f32_e32 v240, 1.0, v240
	v_add_f32_e32 v241, 1.0, v241
	v_rcp_f32_e32 v240, v240
	v_rcp_f32_e32 v241, v241
	v_mul_f32_e32 v234, v104, v234
	v_mul_f32_e32 v235, v105, v235
	v_mul_f32_e32 v236, v106, v236
	v_mul_f32_e32 v238, v100, v238
	v_mul_f32_e32 v237, v107, v237
	v_mul_f32_e32 v239, v101, v239
	v_cvt_pk_bf16_f32 v234, v234, v235
	v_cvt_pk_bf16_f32 v235, v236, v237
	v_cvt_pk_bf16_f32 v236, v238, v239
	v_add_co_u32_e32 v238, vcc, 0x30000, v0
	s_mov_b64 s[8:9], 0
	s_nop 0
	v_addc_co_u32_e32 v239, vcc, 0, v1, vcc
	v_mul_f32_e32 v240, v102, v240
	v_mul_f32_e32 v241, v103, v241
	v_cvt_pk_bf16_f32 v237, v240, v241
	flat_store_dwordx4 v[238:239], v[234:237]

; #define PG8_WAIT_V(n) asm volatile("s_waitcnt vmcnt(" #n ")" ::: "memory")
; #define PG8_WAIT_L(n) asm volatile("s_waitcnt lgkmcnt(" #n ")" ::: "memory")
; #define PG8_BAR __builtin_amdgcn_s_barrier()
; #define PG8_SCHED __builtin_amdgcn_sched_barrier(0)
; template <class Epi, class AddrA, class AddrB>
; __device__ __forceinline__ void gemm_phase(const Sched S, const int lda, const int ldb, const int K, const AddrA addrA,
;                                            const AddrB addrB, const Epi E) {
;     ...
;   for (;;) {
;     const bool has_next = S.next(ui + 1, nxt);
;     const char* nA = has_next ? addrA(nxt) : cA;
;     const char* nB = has_next ? addrB(nxt) : cB;
;     for (int t = 0; t < nt; t += 2) {
;       const bool last = (t == nt - 2);
;       const char* a1 = cA + (size_t)(t + 1) * kstep;
;       const char* a2 = last ? nA : cA + (size_t)(t + 2) * kstep;
;       const char* b2 = last ? nB : cB + (size_t)(t + 2) * kstep;
;       const char* a3 = a2 + kstep;
;       const char* b3 = b2 + kstep;
;       PG8_LDB(B0, 0, 0); PG8_SCHED; PG8_LDA(At, 0, 0); PG8_STAGE(PG8_SA(1, 1), a1 + hstepA, voffA);
;       PG8_WAIT_L(8); PG8_BAR; PG8_WAIT_L(0); PG8_MMA(0, 0, At, B0); PG8_BAR; PG8_SCHED;
;       PG8_LDB(B1, 0, 1); PG8_STAGE(PG8_SB(0, 0), b2, voffB);
;       PG8_BAR; PG8_WAIT_L(0); PG8_MMA(0, 1, At, B1); PG8_BAR;
;       PG8_LDA(At, 0, 1); PG8_STAGE(PG8_SA(0, 0), a2, voffA);
;       PG8_BAR; PG8_WAIT_L(0); PG8_MMA(1, 0, At, B0); PG8_BAR; PG8_SCHED;
;       PG8_STAGE(PG8_SB(0, 1), b2 + hstepB, voffB);
;       PG8_WAIT_V(6); PG8_BAR; PG8_MMA(1, 1, At, B1); PG8_BAR;
.LBB0_618:
	s_ashr_i32 s3, s2, 31
	s_lshl_b64 s[8:9], s[2:3], 20
	s_add_u32 s8, s23, s8
	s_addc_u32 s9, s24, s9
	s_and_b64 s[10:11], s[18:19], exec
	s_cselect_b32 s3, s9, s17
	s_cselect_b32 s13, s8, s16
	s_ashr_i32 s5, s4, 31
	s_lshl_b64 s[10:11], s[4:5], 20
	s_add_u32 s10, s21, s10
	s_addc_u32 s11, s22, s11
	s_and_b64 s[18:19], s[18:19], exec
	s_cselect_b32 s5, s11, s15
	s_cselect_b32 s35, s10, s14
	s_add_u32 s36, s14, 0x100
	s_addc_u32 s37, s15, 0
	s_add_u32 s14, s16, 0x80080
	s_addc_u32 s15, s17, 0
	s_mov_b32 s38, -2
	s_add_u32 s16, s14, 0xfff80080
	s_addc_u32 s17, s15, -1
	s_add_i32 s39, 0, 0x10000
	v_add_u32_e32 v142, s39, v144
	ds_read_b128 v[148:151], v142
	ds_read_b128 v[152:155], v142 offset:1024
	ds_read_b128 v[156:159], v142 offset:2048
	ds_read_b128 v[160:163], v142 offset:3072
	s_cmp_eq_u32 s38, 28
	s_cselect_b32 s19, s3, s17
	s_cselect_b32 s18, s13, s16
	s_cselect_b32 s17, s5, s37
	s_cselect_b32 s16, s35, s36
	v_lshl_add_u64 v[142:143], s[14:15], 0, v[140:141]
	s_add_i32 m0, s26, 0xc000
	ds_read_b128 v[168:171], v146
	ds_read_b128 v[172:175], v146 offset:1024
	ds_read_b128 v[176:179], v146 offset:2048
	ds_read_b128 v[180:183], v146 offset:3072
	ds_read_b128 v[184:187], v146 offset:4096
	ds_read_b128 v[188:191], v146 offset:5120
	ds_read_b128 v[192:195], v146 offset:6144
	ds_read_b128 v[212:215], v146 offset:7168
	global_load_lds_dwordx4 v[142:143], off
	v_lshl_add_u64 v[142:143], s[14:15], 0, v[138:139]
	s_add_i32 m0, s26, 0xe000
	s_nop 0
	global_load_lds_dwordx4 v[142:143], off
	s_waitcnt lgkmcnt(8)
	s_setprio 1
	s_barrier
	s_waitcnt lgkmcnt(0)
	v_mfma_f32_16x16x32_bf16 v[128:131], v[148:151], v[168:171], 0
	v_mfma_f32_16x16x32_bf16 v[128:131], v[152:155], v[172:175], v[128:131]
	v_mfma_f32_16x16x32_bf16 v[120:123], v[148:151], v[176:179], 0
	v_mfma_f32_16x16x32_bf16 v[120:123], v[152:155], v[180:183], v[120:123]
	v_mfma_f32_16x16x32_bf16 v[112:115], v[148:151], v[184:187], 0
	v_mfma_f32_16x16x32_bf16 v[112:115], v[152:155], v[188:191], v[112:115]
	v_mfma_f32_16x16x32_bf16 v[104:107], v[148:151], v[192:195], 0
	v_mfma_f32_16x16x32_bf16 v[104:107], v[152:155], v[212:215], v[104:107]
	v_mfma_f32_16x16x32_bf16 v[124:127], v[156:159], v[168:171], 0
	v_mfma_f32_16x16x32_bf16 v[124:127], v[160:163], v[172:175], v[124:127]
	v_mfma_f32_16x16x32_bf16 v[116:119], v[156:159], v[176:179], 0
	v_mfma_f32_16x16x32_bf16 v[116:119], v[160:163], v[180:183], v[116:119]
	v_mfma_f32_16x16x32_bf16 v[108:111], v[156:159], v[184:187], 0
	v_mfma_f32_16x16x32_bf16 v[108:111], v[160:163], v[188:191], v[108:111]
	v_mfma_f32_16x16x32_bf16 v[100:103], v[156:159], v[192:195], 0
	v_mfma_f32_16x16x32_bf16 v[100:103], v[160:163], v[212:215], v[100:103]
	s_barrier
	s_setprio 0
	s_add_i32 s42, 0, 0x14000
	v_add_u32_e32 v142, s42, v144
	s_add_i32 s39, s39, s25
	ds_read_b128 v[216:219], v142
	ds_read_b128 v[220:223], v142 offset:1024
	ds_read_b128 v[224:227], v142 offset:2048
	ds_read_b128 v[228:231], v142 offset:3072
	v_lshl_add_u64 v[142:143], s[16:17], 0, v[2:3]
	s_mov_b32 m0, s39
	v_lshl_add_u64 v[196:197], s[16:17], 0, v[0:1]
	global_load_lds_dwordx4 v[142:143], off
	s_add_i32 m0, s39, 0x2000
	s_nop 0
	global_load_lds_dwordx4 v[196:197], off
	s_setprio 1
	s_barrier
	s_waitcnt lgkmcnt(0)
	v_mfma_f32_16x16x32_bf16 v[96:99], v[216:219], v[168:171], 0
	v_mfma_f32_16x16x32_bf16 v[96:99], v[220:223], v[172:175], v[96:99]
	v_mfma_f32_16x16x32_bf16 v[88:91], v[216:219], v[176:179], 0
	v_mfma_f32_16x16x32_bf16 v[88:91], v[220:223], v[180:183], v[88:91]
	v_mfma_f32_16x16x32_bf16 v[80:83], v[216:219], v[184:187], 0
	v_mfma_f32_16x16x32_bf16 v[80:83], v[220:223], v[188:191], v[80:83]
	v_mfma_f32_16x16x32_bf16 v[72:75], v[216:219], v[192:195], 0
	v_mfma_f32_16x16x32_bf16 v[72:75], v[220:223], v[212:215], v[72:75]
	v_mfma_f32_16x16x32_bf16 v[92:95], v[224:227], v[168:171], 0
	v_mfma_f32_16x16x32_bf16 v[92:95], v[228:231], v[172:175], v[92:95]
	v_mfma_f32_16x16x32_bf16 v[84:87], v[224:227], v[176:179], 0
	v_mfma_f32_16x16x32_bf16 v[84:87], v[228:231], v[180:183], v[84:87]
	v_mfma_f32_16x16x32_bf16 v[76:79], v[224:227], v[184:187], 0
	v_mfma_f32_16x16x32_bf16 v[76:79], v[228:231], v[188:191], v[76:79]
	v_mfma_f32_16x16x32_bf16 v[68:71], v[224:227], v[192:195], 0
	v_mfma_f32_16x16x32_bf16 v[68:71], v[228:231], v[212:215], v[68:71]
	s_mov_b32 m0, s26
	v_lshl_add_u64 v[232:233], s[18:19], 0, v[134:135]
	s_barrier
	s_setprio 0
	ds_read_b128 v[168:171], v146 offset:16384
	ds_read_b128 v[172:175], v146 offset:17408
	ds_read_b128 v[176:179], v146 offset:18432
	ds_read_b128 v[180:183], v146 offset:19456
	ds_read_b128 v[184:187], v146 offset:20480
	ds_read_b128 v[188:191], v146 offset:21504
	ds_read_b128 v[192:195], v146 offset:22528
	ds_read_b128 v[212:215], v146 offset:23552
	global_load_lds_dwordx4 v[232:233], off
	v_lshl_add_u64 v[234:235], s[18:19], 0, v[132:133]
	s_mov_b32 m0, s27
	s_nop 0
	global_load_lds_dwordx4 v[234:235], off
	s_setprio 1
	s_barrier
	s_waitcnt lgkmcnt(0)
	v_mfma_f32_16x16x32_bf16 v[64:67], v[148:151], v[168:171], 0
	v_mfma_f32_16x16x32_bf16 v[64:67], v[152:155], v[172:175], v[64:67]
	v_mfma_f32_16x16x32_bf16 v[56:59], v[148:151], v[176:179], 0
	v_mfma_f32_16x16x32_bf16 v[56:59], v[152:155], v[180:183], v[56:59]
	v_mfma_f32_16x16x32_bf16 v[48:51], v[148:151], v[184:187], 0
	v_mfma_f32_16x16x32_bf16 v[48:51], v[152:155], v[188:191], v[48:51]
	v_mfma_f32_16x16x32_bf16 v[40:43], v[148:151], v[192:195], 0
	v_mfma_f32_16x16x32_bf16 v[40:43], v[152:155], v[212:215], v[40:43]
	v_mfma_f32_16x16x32_bf16 v[60:63], v[156:159], v[168:171], 0
	v_mfma_f32_16x16x32_bf16 v[60:63], v[160:163], v[172:175], v[60:63]
	v_mfma_f32_16x16x32_bf16 v[52:55], v[156:159], v[176:179], 0
	v_mfma_f32_16x16x32_bf16 v[52:55], v[160:163], v[180:183], v[52:55]
	v_mfma_f32_16x16x32_bf16 v[44:47], v[156:159], v[184:187], 0
	v_mfma_f32_16x16x32_bf16 v[44:47], v[160:163], v[188:191], v[44:47]
	v_mfma_f32_16x16x32_bf16 v[36:39], v[156:159], v[192:195], 0
	v_mfma_f32_16x16x32_bf16 v[36:39], v[160:163], v[212:215], v[36:39]
	s_barrier
; #define PG8_WAIT_V(n) asm volatile("s_waitcnt vmcnt(" #n ")" ::: "memory")
; #define PG8_WAIT_L(n) asm volatile("s_waitcnt lgkmcnt(" #n ")" ::: "memory")
; #define PG8_BAR __builtin_amdgcn_s_barrier()
; #define PG8_SCHED __builtin_amdgcn_sched_barrier(0)
; template <class Epi, class AddrA, class AddrB>
; __device__ __forceinline__ void gemm_phase(const Sched S, const int lda, const int ldb, const int K, const AddrA addrA,
;                                            const AddrB addrB, const Epi E) {
;     ...
;       PG8_STAGE(PG8_SB(0, 1), b2 + hstepB, voffB);
;       PG8_WAIT_V(6); PG8_BAR; PG8_MMA(1, 1, At, B1); PG8_BAR;
;       PG8_LDB(B0, 1, 0); PG8_SCHED; PG8_LDA(At, 1, 0); PG8_STAGE(PG8_SA(0, 1), a2 + hstepA, voffA);
;       PG8_WAIT_L(8); PG8_BAR; PG8_WAIT_L(0); PG8_MMA(0, 0, At, B0); PG8_BAR; PG8_SCHED;
;       PG8_LDB(B1, 1, 1); PG8_STAGE(PG8_SB(1, 0), b3, voffB);
;       PG8_BAR; PG8_WAIT_L(0); PG8_MMA(0, 1, At, B1); PG8_BAR;
;       PG8_LDA(At, 1, 1); PG8_STAGE(PG8_SA(1, 0), a3, voffA);
;       PG8_BAR; PG8_WAIT_L(0); PG8_MMA(1, 0, At, B0); PG8_BAR; PG8_SCHED;
	s_setprio 0
	s_add_u32 s40, s16, 0x80000
	s_addc_u32 s41, s17, 0
	s_add_i32 s39, s42, s25
	v_lshl_add_u64 v[148:149], s[40:41], 0, v[2:3]
	s_mov_b32 m0, s39
	s_nop 0
	global_load_lds_dwordx4 v[148:149], off
	v_lshl_add_u64 v[148:149], s[40:41], 0, v[0:1]
	s_add_i32 m0, s39, 0x2000
	s_nop 0
	global_load_lds_dwordx4 v[148:149], off
	s_waitcnt vmcnt(6)
	s_setprio 1
	s_barrier
	v_mfma_f32_16x16x32_bf16 v[32:35], v[216:219], v[168:171], 0
	v_mfma_f32_16x16x32_bf16 v[32:35], v[220:223], v[172:175], v[32:35]
	v_mfma_f32_16x16x32_bf16 v[24:27], v[216:219], v[176:179], 0
	v_mfma_f32_16x16x32_bf16 v[24:27], v[220:223], v[180:183], v[24:27]
	v_mfma_f32_16x16x32_bf16 v[16:19], v[216:219], v[184:187], 0
	v_mfma_f32_16x16x32_bf16 v[16:19], v[220:223], v[188:191], v[16:19]
	v_mfma_f32_16x16x32_bf16 v[8:11], v[216:219], v[192:195], 0
	v_mfma_f32_16x16x32_bf16 v[8:11], v[220:223], v[212:215], v[8:11]
	v_mfma_f32_16x16x32_bf16 v[28:31], v[224:227], v[168:171], 0
	v_mfma_f32_16x16x32_bf16 v[28:31], v[228:231], v[172:175], v[28:31]
	v_mfma_f32_16x16x32_bf16 v[20:23], v[224:227], v[176:179], 0
	v_mfma_f32_16x16x32_bf16 v[20:23], v[228:231], v[180:183], v[20:23]
	v_mfma_f32_16x16x32_bf16 v[12:15], v[224:227], v[184:187], 0
	v_mfma_f32_16x16x32_bf16 v[12:15], v[228:231], v[188:191], v[12:15]
	v_mfma_f32_16x16x32_bf16 v[4:7], v[224:227], v[192:195], 0
	v_mfma_f32_16x16x32_bf16 v[4:7], v[228:231], v[212:215], v[4:7]
	s_add_i32 s39, 0, 0x18000
	v_add_u32_e32 v147, s39, v144
	s_barrier
	s_setprio 0
	ds_read_b128 v[148:151], v147
	ds_read_b128 v[152:155], v147 offset:1024
	ds_read_b128 v[156:159], v147 offset:2048
	ds_read_b128 v[160:163], v147 offset:3072
	s_add_u32 s18, s18, 0x80000
	s_addc_u32 s19, s19, 0
	s_mov_b32 m0, s28
	v_lshl_add_u64 v[216:217], s[18:19], 0, v[134:135]
	ds_read_b128 v[168:171], v146 offset:32768
	ds_read_b128 v[172:175], v146 offset:33792
	ds_read_b128 v[176:179], v146 offset:34816
	ds_read_b128 v[180:183], v146 offset:35840
	ds_read_b128 v[184:187], v146 offset:36864
	ds_read_b128 v[188:191], v146 offset:37888
	ds_read_b128 v[192:195], v146 offset:38912
	ds_read_b128 v[212:215], v146 offset:39936
	global_load_lds_dwordx4 v[216:217], off
	v_lshl_add_u64 v[216:217], s[18:19], 0, v[132:133]
	s_mov_b32 m0, s29
	s_nop 0
	global_load_lds_dwordx4 v[216:217], off
	s_waitcnt lgkmcnt(8)
	s_setprio 1
	s_barrier
	s_waitcnt lgkmcnt(0)
	v_mfma_f32_16x16x32_bf16 v[128:131], v[148:151], v[168:171], v[128:131]
	v_mfma_f32_16x16x32_bf16 v[128:131], v[152:155], v[172:175], v[128:131]
	v_mfma_f32_16x16x32_bf16 v[120:123], v[148:151], v[176:179], v[120:123]
	v_mfma_f32_16x16x32_bf16 v[120:123], v[152:155], v[180:183], v[120:123]
	v_mfma_f32_16x16x32_bf16 v[112:115], v[148:151], v[184:187], v[112:115]
	v_mfma_f32_16x16x32_bf16 v[112:115], v[152:155], v[188:191], v[112:115]
	v_mfma_f32_16x16x32_bf16 v[104:107], v[148:151], v[192:195], v[104:107]
	v_mfma_f32_16x16x32_bf16 v[104:107], v[152:155], v[212:215], v[104:107]
	v_mfma_f32_16x16x32_bf16 v[124:127], v[156:159], v[168:171], v[124:127]
	v_mfma_f32_16x16x32_bf16 v[124:127], v[160:163], v[172:175], v[124:127]
	v_mfma_f32_16x16x32_bf16 v[116:119], v[156:159], v[176:179], v[116:119]
	v_mfma_f32_16x16x32_bf16 v[116:119], v[160:163], v[180:183], v[116:119]
	v_mfma_f32_16x16x32_bf16 v[108:111], v[156:159], v[184:187], v[108:111]
	v_mfma_f32_16x16x32_bf16 v[108:111], v[160:163], v[188:191], v[108:111]
	v_mfma_f32_16x16x32_bf16 v[100:103], v[156:159], v[192:195], v[100:103]
	v_mfma_f32_16x16x32_bf16 v[100:103], v[160:163], v[212:215], v[100:103]
	s_barrier
	s_setprio 0
	s_add_i32 s18, 0, 0x1c000
	s_add_i32 s19, s39, s25
	v_add_u32_e32 v147, s18, v144
	v_lshl_add_u64 v[142:143], v[142:143], 0, s[52:53]
	s_mov_b32 m0, s19
	ds_read_b128 v[216:219], v147
	ds_read_b128 v[220:223], v147 offset:1024
	ds_read_b128 v[224:227], v147 offset:2048
	ds_read_b128 v[228:231], v147 offset:3072
	global_load_lds_dwordx4 v[142:143], off
	v_lshl_add_u64 v[142:143], v[196:197], 0, s[52:53]
	s_add_i32 m0, s19, 0x2000
	s_nop 0
	global_load_lds_dwordx4 v[142:143], off
	s_setprio 1
	s_barrier
	s_waitcnt lgkmcnt(0)
	v_mfma_f32_16x16x32_bf16 v[96:99], v[216:219], v[168:171], v[96:99]
	v_mfma_f32_16x16x32_bf16 v[96:99], v[220:223], v[172:175], v[96:99]
	v_mfma_f32_16x16x32_bf16 v[88:91], v[216:219], v[176:179], v[88:91]
	v_mfma_f32_16x16x32_bf16 v[88:91], v[220:223], v[180:183], v[88:91]
	v_mfma_f32_16x16x32_bf16 v[80:83], v[216:219], v[184:187], v[80:83]
	v_mfma_f32_16x16x32_bf16 v[80:83], v[220:223], v[188:191], v[80:83]
	v_mfma_f32_16x16x32_bf16 v[72:75], v[216:219], v[192:195], v[72:75]
	v_mfma_f32_16x16x32_bf16 v[72:75], v[220:223], v[212:215], v[72:75]
	v_mfma_f32_16x16x32_bf16 v[92:95], v[224:227], v[168:171], v[92:95]
	v_mfma_f32_16x16x32_bf16 v[92:95], v[228:231], v[172:175], v[92:95]
	v_mfma_f32_16x16x32_bf16 v[84:87], v[224:227], v[176:179], v[84:87]
	v_mfma_f32_16x16x32_bf16 v[84:87], v[228:231], v[180:183], v[84:87]
	v_mfma_f32_16x16x32_bf16 v[76:79], v[224:227], v[184:187], v[76:79]
	v_mfma_f32_16x16x32_bf16 v[76:79], v[228:231], v[188:191], v[76:79]
	v_mfma_f32_16x16x32_bf16 v[68:71], v[224:227], v[192:195], v[68:71]
	v_mfma_f32_16x16x32_bf16 v[68:71], v[228:231], v[212:215], v[68:71]
	s_mov_b32 m0, s30
	v_lshl_add_u64 v[142:143], v[232:233], 0, s[52:53]
	s_barrier
	s_setprio 0
	ds_read_b128 v[168:171], v146 offset:49152
	ds_read_b128 v[172:175], v146 offset:50176
	ds_read_b128 v[176:179], v146 offset:51200
	ds_read_b128 v[180:183], v146 offset:52224
	ds_read_b128 v[184:187], v146 offset:53248
	ds_read_b128 v[188:191], v146 offset:54272
	ds_read_b128 v[192:195], v146 offset:55296
	ds_read_b128 v[212:215], v146 offset:56320
	global_load_lds_dwordx4 v[142:143], off
	v_lshl_add_u64 v[142:143], v[234:235], 0, s[52:53]
	s_mov_b32 m0, s31
	s_nop 0
	global_load_lds_dwordx4 v[142:143], off
	s_setprio 1
	s_barrier
; #define PG8_WAIT_V(n) asm volatile("s_waitcnt vmcnt(" #n ")" ::: "memory")
; #define PG8_WAIT_L(n) asm volatile("s_waitcnt lgkmcnt(" #n ")" ::: "memory")
; #define PG8_BAR __builtin_amdgcn_s_barrier()
; #define PG8_SCHED __builtin_amdgcn_sched_barrier(0)
; template <class Epi, class AddrA, class AddrB>
; __device__ __forceinline__ void gemm_phase(const Sched S, const int lda, const int ldb, const int K, const AddrA addrA,
;                                            const AddrB addrB, const Epi E) {
;     ...
;     for (int t = 0; t < nt; t += 2) {
;       const bool last = (t == nt - 2);
;       const char* a1 = cA + (size_t)(t + 1) * kstep;
;       const char* a2 = last ? nA : cA + (size_t)(t + 2) * kstep;
;       const char* b2 = last ? nB : cB + (size_t)(t + 2) * kstep;
;       const char* a3 = a2 + kstep;
;       const char* b3 = b2 + kstep;
;       PG8_LDB(B0, 0, 0); PG8_SCHED; PG8_LDA(At, 0, 0); PG8_STAGE(PG8_SA(1, 1), a1 + hstepA, voffA);
;       PG8_WAIT_L(8); PG8_BAR; PG8_WAIT_L(0); PG8_MMA(0, 0, At, B0); PG8_BAR; PG8_SCHED;
;       PG8_LDB(B1, 0, 1); PG8_STAGE(PG8_SB(0, 0), b2, voffB);
;       PG8_BAR; PG8_WAIT_L(0); PG8_MMA(0, 1, At, B1); PG8_BAR;
;       PG8_LDA(At, 0, 1); PG8_STAGE(PG8_SA(0, 0), a2, voffA);
;       PG8_BAR; PG8_WAIT_L(0); PG8_MMA(1, 0, At, B0); PG8_BAR; PG8_SCHED;
;       PG8_STAGE(PG8_SB(0, 1), b2 + hstepB, voffB);
;       PG8_WAIT_V(6); PG8_BAR; PG8_MMA(1, 1, At, B1); PG8_BAR;
;       PG8_LDB(B0, 1, 0); PG8_SCHED; PG8_LDA(At, 1, 0); PG8_STAGE(PG8_SA(0, 1), a2 + hstepA, voffA);
;       PG8_WAIT_L(8); PG8_BAR; PG8_WAIT_L(0); PG8_MMA(0, 0, At, B0); PG8_BAR; PG8_SCHED;
	s_waitcnt lgkmcnt(0)
	v_mfma_f32_16x16x32_bf16 v[64:67], v[148:151], v[168:171], v[64:67]
	v_mfma_f32_16x16x32_bf16 v[64:67], v[152:155], v[172:175], v[64:67]
	v_mfma_f32_16x16x32_bf16 v[56:59], v[148:151], v[176:179], v[56:59]
	v_mfma_f32_16x16x32_bf16 v[56:59], v[152:155], v[180:183], v[56:59]
	v_mfma_f32_16x16x32_bf16 v[48:51], v[148:151], v[184:187], v[48:51]
	v_mfma_f32_16x16x32_bf16 v[48:51], v[152:155], v[188:191], v[48:51]
	v_mfma_f32_16x16x32_bf16 v[40:43], v[148:151], v[192:195], v[40:43]
	v_mfma_f32_16x16x32_bf16 v[40:43], v[152:155], v[212:215], v[40:43]
	v_mfma_f32_16x16x32_bf16 v[60:63], v[156:159], v[168:171], v[60:63]
	v_mfma_f32_16x16x32_bf16 v[60:63], v[160:163], v[172:175], v[60:63]
	v_mfma_f32_16x16x32_bf16 v[52:55], v[156:159], v[176:179], v[52:55]
	v_mfma_f32_16x16x32_bf16 v[52:55], v[160:163], v[180:183], v[52:55]
	v_mfma_f32_16x16x32_bf16 v[44:47], v[156:159], v[184:187], v[44:47]
	v_mfma_f32_16x16x32_bf16 v[44:47], v[160:163], v[188:191], v[44:47]
	v_mfma_f32_16x16x32_bf16 v[36:39], v[156:159], v[192:195], v[36:39]
	v_mfma_f32_16x16x32_bf16 v[36:39], v[160:163], v[212:215], v[36:39]
	s_barrier
	s_setprio 0
	s_add_u32 s16, s16, 0x80080
	s_addc_u32 s17, s17, 0
	s_add_i32 s18, s18, s25
	v_lshl_add_u64 v[142:143], s[16:17], 0, v[2:3]
	s_mov_b32 m0, s18
	s_nop 0
	global_load_lds_dwordx4 v[142:143], off
	v_lshl_add_u64 v[142:143], s[16:17], 0, v[0:1]
	s_add_i32 m0, s18, 0x2000
	s_nop 0
	global_load_lds_dwordx4 v[142:143], off
	s_waitcnt vmcnt(6)
	s_setprio 1
	s_barrier
	v_mfma_f32_16x16x32_bf16 v[32:35], v[216:219], v[168:171], v[32:35]
	v_mfma_f32_16x16x32_bf16 v[32:35], v[220:223], v[172:175], v[32:35]
	v_mfma_f32_16x16x32_bf16 v[24:27], v[216:219], v[176:179], v[24:27]
	v_mfma_f32_16x16x32_bf16 v[24:27], v[220:223], v[180:183], v[24:27]
	v_mfma_f32_16x16x32_bf16 v[16:19], v[216:219], v[184:187], v[16:19]
	v_mfma_f32_16x16x32_bf16 v[16:19], v[220:223], v[188:191], v[16:19]
	v_mfma_f32_16x16x32_bf16 v[8:11], v[216:219], v[192:195], v[8:11]
	v_mfma_f32_16x16x32_bf16 v[8:11], v[220:223], v[212:215], v[8:11]
	v_mfma_f32_16x16x32_bf16 v[28:31], v[224:227], v[168:171], v[28:31]
	v_mfma_f32_16x16x32_bf16 v[28:31], v[228:231], v[172:175], v[28:31]
	v_mfma_f32_16x16x32_bf16 v[20:23], v[224:227], v[176:179], v[20:23]
	v_mfma_f32_16x16x32_bf16 v[20:23], v[228:231], v[180:183], v[20:23]
	v_mfma_f32_16x16x32_bf16 v[12:15], v[224:227], v[184:187], v[12:15]
	v_mfma_f32_16x16x32_bf16 v[12:15], v[228:231], v[188:191], v[12:15]
	v_mfma_f32_16x16x32_bf16 v[4:7], v[224:227], v[192:195], v[4:7]
	v_mfma_f32_16x16x32_bf16 v[4:7], v[228:231], v[212:215], v[4:7]
	s_add_i32 s38, s38, 2
	s_add_u32 s36, s36, 0x100
	s_addc_u32 s37, s37, 0
	s_add_u32 s14, s14, 0x100
	s_addc_u32 s15, s15, 0
	s_cmp_gt_u32 s38, 29
	s_barrier
	s_setprio 0
.LBB0_619:
	s_add_u32 s16, s14, 0xfff80080
	s_addc_u32 s17, s15, -1
	s_add_i32 s39, 0, 0x10000
	v_add_u32_e32 v142, s39, v144
	ds_read_b128 v[148:151], v142
	ds_read_b128 v[152:155], v142 offset:1024
	ds_read_b128 v[156:159], v142 offset:2048
	ds_read_b128 v[160:163], v142 offset:3072
	s_cmp_eq_u32 s38, 28
	s_cselect_b32 s19, s3, s17
	s_cselect_b32 s18, s13, s16
	s_cselect_b32 s17, s5, s37
	s_cselect_b32 s16, s35, s36
	v_lshl_add_u64 v[142:143], s[14:15], 0, v[140:141]
	s_add_i32 m0, s26, 0xc000
	ds_read_b128 v[168:171], v146
	ds_read_b128 v[172:175], v146 offset:1024
	ds_read_b128 v[176:179], v146 offset:2048
	ds_read_b128 v[180:183], v146 offset:3072
	ds_read_b128 v[184:187], v146 offset:4096
	ds_read_b128 v[188:191], v146 offset:5120
	ds_read_b128 v[192:195], v146 offset:6144
	ds_read_b128 v[212:215], v146 offset:7168
	global_load_lds_dwordx4 v[142:143], off
	v_lshl_add_u64 v[142:143], s[14:15], 0, v[138:139]
	s_add_i32 m0, s26, 0xe000
	s_nop 0
	global_load_lds_dwordx4 v[142:143], off
	s_waitcnt lgkmcnt(8)
	s_setprio 1
	s_barrier
	s_waitcnt lgkmcnt(0)
	v_mfma_f32_16x16x32_bf16 v[128:131], v[148:151], v[168:171], v[128:131]
	v_mfma_f32_16x16x32_bf16 v[128:131], v[152:155], v[172:175], v[128:131]
	v_mfma_f32_16x16x32_bf16 v[120:123], v[148:151], v[176:179], v[120:123]
	v_mfma_f32_16x16x32_bf16 v[120:123], v[152:155], v[180:183], v[120:123]
	v_mfma_f32_16x16x32_bf16 v[112:115], v[148:151], v[184:187], v[112:115]
	v_mfma_f32_16x16x32_bf16 v[112:115], v[152:155], v[188:191], v[112:115]
	v_mfma_f32_16x16x32_bf16 v[104:107], v[148:151], v[192:195], v[104:107]
	v_mfma_f32_16x16x32_bf16 v[104:107], v[152:155], v[212:215], v[104:107]
	v_mfma_f32_16x16x32_bf16 v[124:127], v[156:159], v[168:171], v[124:127]
	v_mfma_f32_16x16x32_bf16 v[124:127], v[160:163], v[172:175], v[124:127]
	v_mfma_f32_16x16x32_bf16 v[116:119], v[156:159], v[176:179], v[116:119]
	v_mfma_f32_16x16x32_bf16 v[116:119], v[160:163], v[180:183], v[116:119]
	v_mfma_f32_16x16x32_bf16 v[108:111], v[156:159], v[184:187], v[108:111]
	v_mfma_f32_16x16x32_bf16 v[108:111], v[160:163], v[188:191], v[108:111]
	v_mfma_f32_16x16x32_bf16 v[100:103], v[156:159], v[192:195], v[100:103]
	v_mfma_f32_16x16x32_bf16 v[100:103], v[160:163], v[212:215], v[100:103]
	s_barrier
	s_setprio 0
	s_add_i32 s42, 0, 0x14000
	v_add_u32_e32 v142, s42, v144
	s_add_i32 s39, s39, s25
	ds_read_b128 v[216:219], v142
	ds_read_b128 v[220:223], v142 offset:1024
	ds_read_b128 v[224:227], v142 offset:2048
	ds_read_b128 v[228:231], v142 offset:3072
	v_lshl_add_u64 v[142:143], s[16:17], 0, v[2:3]
	s_mov_b32 m0, s39
	v_lshl_add_u64 v[196:197], s[16:17], 0, v[0:1]
	global_load_lds_dwordx4 v[142:143], off
	s_add_i32 m0, s39, 0x2000
	s_nop 0
	global_load_lds_dwordx4 v[196:197], off
	s_setprio 1
	s_barrier
; #define PG8_WAIT_V(n) asm volatile("s_waitcnt vmcnt(" #n ")" ::: "memory")
; #define PG8_WAIT_L(n) asm volatile("s_waitcnt lgkmcnt(" #n ")" ::: "memory")
; #define PG8_BAR __builtin_amdgcn_s_barrier()
; #define PG8_SCHED __builtin_amdgcn_sched_barrier(0)
; template <class Epi, class AddrA, class AddrB>
; __device__ __forceinline__ void gemm_phase(const Sched S, const int lda, const int ldb, const int K, const AddrA addrA,
;                                            const AddrB addrB, const Epi E) {
;     ...
;       PG8_BAR; PG8_WAIT_L(0); PG8_MMA(0, 1, At, B1); PG8_BAR;
;       PG8_LDA(At, 0, 1); PG8_STAGE(PG8_SA(0, 0), a2, voffA);
;       PG8_BAR; PG8_WAIT_L(0); PG8_MMA(1, 0, At, B0); PG8_BAR; PG8_SCHED;
;       PG8_STAGE(PG8_SB(0, 1), b2 + hstepB, voffB);
;       PG8_WAIT_V(6); PG8_BAR; PG8_MMA(1, 1, At, B1); PG8_BAR;
;       PG8_LDB(B0, 1, 0); PG8_SCHED; PG8_LDA(At, 1, 0); PG8_STAGE(PG8_SA(0, 1), a2 + hstepA, voffA);
;       PG8_WAIT_L(8); PG8_BAR; PG8_WAIT_L(0); PG8_MMA(0, 0, At, B0); PG8_BAR; PG8_SCHED;
;       PG8_LDB(B1, 1, 1); PG8_STAGE(PG8_SB(1, 0), b3, voffB);
;       PG8_BAR; PG8_WAIT_L(0); PG8_MMA(0, 1, At, B1); PG8_BAR;
	s_waitcnt lgkmcnt(0)
	v_mfma_f32_16x16x32_bf16 v[96:99], v[216:219], v[168:171], v[96:99]
	v_mfma_f32_16x16x32_bf16 v[96:99], v[220:223], v[172:175], v[96:99]
	v_mfma_f32_16x16x32_bf16 v[88:91], v[216:219], v[176:179], v[88:91]
	v_mfma_f32_16x16x32_bf16 v[88:91], v[220:223], v[180:183], v[88:91]
	v_mfma_f32_16x16x32_bf16 v[80:83], v[216:219], v[184:187], v[80:83]
	v_mfma_f32_16x16x32_bf16 v[80:83], v[220:223], v[188:191], v[80:83]
	v_mfma_f32_16x16x32_bf16 v[72:75], v[216:219], v[192:195], v[72:75]
	v_mfma_f32_16x16x32_bf16 v[72:75], v[220:223], v[212:215], v[72:75]
	v_mfma_f32_16x16x32_bf16 v[92:95], v[224:227], v[168:171], v[92:95]
	v_mfma_f32_16x16x32_bf16 v[92:95], v[228:231], v[172:175], v[92:95]
	v_mfma_f32_16x16x32_bf16 v[84:87], v[224:227], v[176:179], v[84:87]
	v_mfma_f32_16x16x32_bf16 v[84:87], v[228:231], v[180:183], v[84:87]
	v_mfma_f32_16x16x32_bf16 v[76:79], v[224:227], v[184:187], v[76:79]
	v_mfma_f32_16x16x32_bf16 v[76:79], v[228:231], v[188:191], v[76:79]
	v_mfma_f32_16x16x32_bf16 v[68:71], v[224:227], v[192:195], v[68:71]
	v_mfma_f32_16x16x32_bf16 v[68:71], v[228:231], v[212:215], v[68:71]
	s_mov_b32 m0, s26
	v_lshl_add_u64 v[232:233], s[18:19], 0, v[134:135]
	s_barrier
	s_setprio 0
	ds_read_b128 v[168:171], v146 offset:16384
	ds_read_b128 v[172:175], v146 offset:17408
	ds_read_b128 v[176:179], v146 offset:18432
	ds_read_b128 v[180:183], v146 offset:19456
	ds_read_b128 v[184:187], v146 offset:20480
	ds_read_b128 v[188:191], v146 offset:21504
	ds_read_b128 v[192:195], v146 offset:22528
	ds_read_b128 v[212:215], v146 offset:23552
	global_load_lds_dwordx4 v[232:233], off
	v_lshl_add_u64 v[234:235], s[18:19], 0, v[132:133]
	s_mov_b32 m0, s27
	s_nop 0
	global_load_lds_dwordx4 v[234:235], off
	s_setprio 1
	s_barrier
	s_waitcnt lgkmcnt(0)
	v_mfma_f32_16x16x32_bf16 v[64:67], v[148:151], v[168:171], v[64:67]
	v_mfma_f32_16x16x32_bf16 v[64:67], v[152:155], v[172:175], v[64:67]
	v_mfma_f32_16x16x32_bf16 v[56:59], v[148:151], v[176:179], v[56:59]
	v_mfma_f32_16x16x32_bf16 v[56:59], v[152:155], v[180:183], v[56:59]
	v_mfma_f32_16x16x32_bf16 v[48:51], v[148:151], v[184:187], v[48:51]
	v_mfma_f32_16x16x32_bf16 v[48:51], v[152:155], v[188:191], v[48:51]
	v_mfma_f32_16x16x32_bf16 v[40:43], v[148:151], v[192:195], v[40:43]
	v_mfma_f32_16x16x32_bf16 v[40:43], v[152:155], v[212:215], v[40:43]
	v_mfma_f32_16x16x32_bf16 v[60:63], v[156:159], v[168:171], v[60:63]
	v_mfma_f32_16x16x32_bf16 v[60:63], v[160:163], v[172:175], v[60:63]
	v_mfma_f32_16x16x32_bf16 v[52:55], v[156:159], v[176:179], v[52:55]
	v_mfma_f32_16x16x32_bf16 v[52:55], v[160:163], v[180:183], v[52:55]
	v_mfma_f32_16x16x32_bf16 v[44:47], v[156:159], v[184:187], v[44:47]
	v_mfma_f32_16x16x32_bf16 v[44:47], v[160:163], v[188:191], v[44:47]
	v_mfma_f32_16x16x32_bf16 v[36:39], v[156:159], v[192:195], v[36:39]
	v_mfma_f32_16x16x32_bf16 v[36:39], v[160:163], v[212:215], v[36:39]
	s_barrier
	s_setprio 0
	s_add_u32 s40, s16, 0x80000
	s_addc_u32 s41, s17, 0
	s_add_i32 s39, s42, s25
	v_lshl_add_u64 v[148:149], s[40:41], 0, v[2:3]
	s_mov_b32 m0, s39
	s_nop 0
	global_load_lds_dwordx4 v[148:149], off
	v_lshl_add_u64 v[148:149], s[40:41], 0, v[0:1]
	s_add_i32 m0, s39, 0x2000
	s_nop 0
	global_load_lds_dwordx4 v[148:149], off
	s_waitcnt vmcnt(6)
	s_setprio 1
	s_barrier
	v_mfma_f32_16x16x32_bf16 v[32:35], v[216:219], v[168:171], v[32:35]
	v_mfma_f32_16x16x32_bf16 v[32:35], v[220:223], v[172:175], v[32:35]
	v_mfma_f32_16x16x32_bf16 v[24:27], v[216:219], v[176:179], v[24:27]
	v_mfma_f32_16x16x32_bf16 v[24:27], v[220:223], v[180:183], v[24:27]
	v_mfma_f32_16x16x32_bf16 v[16:19], v[216:219], v[184:187], v[16:19]
	v_mfma_f32_16x16x32_bf16 v[16:19], v[220:223], v[188:191], v[16:19]
	v_mfma_f32_16x16x32_bf16 v[8:11], v[216:219], v[192:195], v[8:11]
	v_mfma_f32_16x16x32_bf16 v[8:11], v[220:223], v[212:215], v[8:11]
	v_mfma_f32_16x16x32_bf16 v[28:31], v[224:227], v[168:171], v[28:31]
	v_mfma_f32_16x16x32_bf16 v[28:31], v[228:231], v[172:175], v[28:31]
	v_mfma_f32_16x16x32_bf16 v[20:23], v[224:227], v[176:179], v[20:23]
	v_mfma_f32_16x16x32_bf16 v[20:23], v[228:231], v[180:183], v[20:23]
	v_mfma_f32_16x16x32_bf16 v[12:15], v[224:227], v[184:187], v[12:15]
	v_mfma_f32_16x16x32_bf16 v[12:15], v[228:231], v[188:191], v[12:15]
	v_mfma_f32_16x16x32_bf16 v[4:7], v[224:227], v[192:195], v[4:7]
	v_mfma_f32_16x16x32_bf16 v[4:7], v[228:231], v[212:215], v[4:7]
	s_add_i32 s39, 0, 0x18000
	v_add_u32_e32 v147, s39, v144
	s_barrier
	s_setprio 0
	ds_read_b128 v[148:151], v147
	ds_read_b128 v[152:155], v147 offset:1024
	ds_read_b128 v[156:159], v147 offset:2048
	ds_read_b128 v[160:163], v147 offset:3072
	s_add_u32 s18, s18, 0x80000
	s_addc_u32 s19, s19, 0
	s_mov_b32 m0, s28
	v_lshl_add_u64 v[216:217], s[18:19], 0, v[134:135]
	ds_read_b128 v[168:171], v146 offset:32768
	ds_read_b128 v[172:175], v146 offset:33792
	ds_read_b128 v[176:179], v146 offset:34816
	ds_read_b128 v[180:183], v146 offset:35840
	ds_read_b128 v[184:187], v146 offset:36864
	ds_read_b128 v[188:191], v146 offset:37888
	ds_read_b128 v[192:195], v146 offset:38912
	ds_read_b128 v[212:215], v146 offset:39936
	global_load_lds_dwordx4 v[216:217], off
	v_lshl_add_u64 v[216:217], s[18:19], 0, v[132:133]
	s_mov_b32 m0, s29
	s_nop 0
	global_load_lds_dwordx4 v[216:217], off
	s_waitcnt lgkmcnt(8)
	s_setprio 1
	s_barrier
; #define PG8_WAIT_V(n) asm volatile("s_waitcnt vmcnt(" #n ")" ::: "memory")
; #define PG8_WAIT_L(n) asm volatile("s_waitcnt lgkmcnt(" #n ")" ::: "memory")
; #define PG8_BAR __builtin_amdgcn_s_barrier()
; #define PG8_SCHED __builtin_amdgcn_sched_barrier(0)
; template <class Epi, class AddrA, class AddrB>
; __device__ __forceinline__ void gemm_phase(const Sched S, const int lda, const int ldb, const int K, const AddrA addrA,
;                                            const AddrB addrB, const Epi E) {
;     ...
;       PG8_WAIT_L(8); PG8_BAR; PG8_WAIT_L(0); PG8_MMA(0, 0, At, B0); PG8_BAR; PG8_SCHED;
;       PG8_LDB(B1, 1, 1); PG8_STAGE(PG8_SB(1, 0), b3, voffB);
;       PG8_BAR; PG8_WAIT_L(0); PG8_MMA(0, 1, At, B1); PG8_BAR;
;       PG8_LDA(At, 1, 1); PG8_STAGE(PG8_SA(1, 0), a3, voffA);
;       PG8_BAR; PG8_WAIT_L(0); PG8_MMA(1, 0, At, B0); PG8_BAR; PG8_SCHED;
;       PG8_STAGE(PG8_SB(1, 1), b3 + hstepB, voffB);
;       PG8_WAIT_V(6); PG8_BAR; PG8_MMA(1, 1, At, B1); PG8_BAR;
	s_waitcnt lgkmcnt(0)
	v_mfma_f32_16x16x32_bf16 v[128:131], v[148:151], v[168:171], v[128:131]
	v_mfma_f32_16x16x32_bf16 v[128:131], v[152:155], v[172:175], v[128:131]
	v_mfma_f32_16x16x32_bf16 v[120:123], v[148:151], v[176:179], v[120:123]
	v_mfma_f32_16x16x32_bf16 v[120:123], v[152:155], v[180:183], v[120:123]
	v_mfma_f32_16x16x32_bf16 v[112:115], v[148:151], v[184:187], v[112:115]
	v_mfma_f32_16x16x32_bf16 v[112:115], v[152:155], v[188:191], v[112:115]
	v_mfma_f32_16x16x32_bf16 v[104:107], v[148:151], v[192:195], v[104:107]
	v_mfma_f32_16x16x32_bf16 v[104:107], v[152:155], v[212:215], v[104:107]
	v_mfma_f32_16x16x32_bf16 v[124:127], v[156:159], v[168:171], v[124:127]
	v_mfma_f32_16x16x32_bf16 v[124:127], v[160:163], v[172:175], v[124:127]
	v_mfma_f32_16x16x32_bf16 v[116:119], v[156:159], v[176:179], v[116:119]
	v_mfma_f32_16x16x32_bf16 v[116:119], v[160:163], v[180:183], v[116:119]
	v_mfma_f32_16x16x32_bf16 v[108:111], v[156:159], v[184:187], v[108:111]
	v_mfma_f32_16x16x32_bf16 v[108:111], v[160:163], v[188:191], v[108:111]
	v_mfma_f32_16x16x32_bf16 v[100:103], v[156:159], v[192:195], v[100:103]
	v_mfma_f32_16x16x32_bf16 v[100:103], v[160:163], v[212:215], v[100:103]
	s_barrier
	s_setprio 0
	s_add_i32 s18, 0, 0x1c000
	s_add_i32 s19, s39, s25
	v_add_u32_e32 v147, s18, v144
	v_lshl_add_u64 v[142:143], v[142:143], 0, s[52:53]
	s_mov_b32 m0, s19
	ds_read_b128 v[216:219], v147
	ds_read_b128 v[220:223], v147 offset:1024
	ds_read_b128 v[224:227], v147 offset:2048
	ds_read_b128 v[228:231], v147 offset:3072
	global_load_lds_dwordx4 v[142:143], off
	v_lshl_add_u64 v[142:143], v[196:197], 0, s[52:53]
	s_add_i32 m0, s19, 0x2000
	s_nop 0
	global_load_lds_dwordx4 v[142:143], off
	s_setprio 1
	s_barrier
	s_waitcnt lgkmcnt(0)
	v_mfma_f32_16x16x32_bf16 v[96:99], v[216:219], v[168:171], v[96:99]
	v_mfma_f32_16x16x32_bf16 v[96:99], v[220:223], v[172:175], v[96:99]
	v_mfma_f32_16x16x32_bf16 v[88:91], v[216:219], v[176:179], v[88:91]
	v_mfma_f32_16x16x32_bf16 v[88:91], v[220:223], v[180:183], v[88:91]
	v_mfma_f32_16x16x32_bf16 v[80:83], v[216:219], v[184:187], v[80:83]
	v_mfma_f32_16x16x32_bf16 v[80:83], v[220:223], v[188:191], v[80:83]
	v_mfma_f32_16x16x32_bf16 v[72:75], v[216:219], v[192:195], v[72:75]
	v_mfma_f32_16x16x32_bf16 v[72:75], v[220:223], v[212:215], v[72:75]
	v_mfma_f32_16x16x32_bf16 v[92:95], v[224:227], v[168:171], v[92:95]
	v_mfma_f32_16x16x32_bf16 v[92:95], v[228:231], v[172:175], v[92:95]
	v_mfma_f32_16x16x32_bf16 v[84:87], v[224:227], v[176:179], v[84:87]
	v_mfma_f32_16x16x32_bf16 v[84:87], v[228:231], v[180:183], v[84:87]
	v_mfma_f32_16x16x32_bf16 v[76:79], v[224:227], v[184:187], v[76:79]
	v_mfma_f32_16x16x32_bf16 v[76:79], v[228:231], v[188:191], v[76:79]
	v_mfma_f32_16x16x32_bf16 v[68:71], v[224:227], v[192:195], v[68:71]
	v_mfma_f32_16x16x32_bf16 v[68:71], v[228:231], v[212:215], v[68:71]
	s_mov_b32 m0, s30
	v_lshl_add_u64 v[142:143], v[232:233], 0, s[52:53]
	s_barrier
	s_setprio 0
	ds_read_b128 v[168:171], v146 offset:49152
	ds_read_b128 v[172:175], v146 offset:50176
	ds_read_b128 v[176:179], v146 offset:51200
	ds_read_b128 v[180:183], v146 offset:52224
	ds_read_b128 v[184:187], v146 offset:53248
	ds_read_b128 v[188:191], v146 offset:54272
	ds_read_b128 v[192:195], v146 offset:55296
	ds_read_b128 v[212:215], v146 offset:56320
	global_load_lds_dwordx4 v[142:143], off
	v_lshl_add_u64 v[142:143], v[234:235], 0, s[52:53]
	s_mov_b32 m0, s31
	s_nop 0
	global_load_lds_dwordx4 v[142:143], off
	s_setprio 1
	s_barrier
	s_waitcnt lgkmcnt(0)
	v_mfma_f32_16x16x32_bf16 v[64:67], v[148:151], v[168:171], v[64:67]
	v_mfma_f32_16x16x32_bf16 v[64:67], v[152:155], v[172:175], v[64:67]
	v_mfma_f32_16x16x32_bf16 v[56:59], v[148:151], v[176:179], v[56:59]
	v_mfma_f32_16x16x32_bf16 v[56:59], v[152:155], v[180:183], v[56:59]
	v_mfma_f32_16x16x32_bf16 v[48:51], v[148:151], v[184:187], v[48:51]
	v_mfma_f32_16x16x32_bf16 v[48:51], v[152:155], v[188:191], v[48:51]
	v_mfma_f32_16x16x32_bf16 v[40:43], v[148:151], v[192:195], v[40:43]
	v_mfma_f32_16x16x32_bf16 v[40:43], v[152:155], v[212:215], v[40:43]
	v_mfma_f32_16x16x32_bf16 v[60:63], v[156:159], v[168:171], v[60:63]
	v_mfma_f32_16x16x32_bf16 v[60:63], v[160:163], v[172:175], v[60:63]
	v_mfma_f32_16x16x32_bf16 v[52:55], v[156:159], v[176:179], v[52:55]
	v_mfma_f32_16x16x32_bf16 v[52:55], v[160:163], v[180:183], v[52:55]
	v_mfma_f32_16x16x32_bf16 v[44:47], v[156:159], v[184:187], v[44:47]
	v_mfma_f32_16x16x32_bf16 v[44:47], v[160:163], v[188:191], v[44:47]
	v_mfma_f32_16x16x32_bf16 v[36:39], v[156:159], v[192:195], v[36:39]
	v_mfma_f32_16x16x32_bf16 v[36:39], v[160:163], v[212:215], v[36:39]
	s_barrier
	s_setprio 0
	s_add_u32 s16, s16, 0x80080
	s_addc_u32 s17, s17, 0
	s_add_i32 s18, s18, s25
	v_lshl_add_u64 v[142:143], s[16:17], 0, v[2:3]
	s_mov_b32 m0, s18
	s_nop 0
	global_load_lds_dwordx4 v[142:143], off
	v_lshl_add_u64 v[142:143], s[16:17], 0, v[0:1]
	s_add_i32 m0, s18, 0x2000
	s_nop 0
	global_load_lds_dwordx4 v[142:143], off
	s_waitcnt vmcnt(6)
	s_setprio 1
	s_barrier
	v_mfma_f32_16x16x32_bf16 v[32:35], v[216:219], v[168:171], v[32:35]
	v_mfma_f32_16x16x32_bf16 v[32:35], v[220:223], v[172:175], v[32:35]
	v_mfma_f32_16x16x32_bf16 v[24:27], v[216:219], v[176:179], v[24:27]
	v_mfma_f32_16x16x32_bf16 v[24:27], v[220:223], v[180:183], v[24:27]
	v_mfma_f32_16x16x32_bf16 v[16:19], v[216:219], v[184:187], v[16:19]
	v_mfma_f32_16x16x32_bf16 v[16:19], v[220:223], v[188:191], v[16:19]
	v_mfma_f32_16x16x32_bf16 v[8:11], v[216:219], v[192:195], v[8:11]
	v_mfma_f32_16x16x32_bf16 v[8:11], v[220:223], v[212:215], v[8:11]
	v_mfma_f32_16x16x32_bf16 v[28:31], v[224:227], v[168:171], v[28:31]
	v_mfma_f32_16x16x32_bf16 v[28:31], v[228:231], v[172:175], v[28:31]
	v_mfma_f32_16x16x32_bf16 v[20:23], v[224:227], v[176:179], v[20:23]
	v_mfma_f32_16x16x32_bf16 v[20:23], v[228:231], v[180:183], v[20:23]
	v_mfma_f32_16x16x32_bf16 v[12:15], v[224:227], v[184:187], v[12:15]
	v_mfma_f32_16x16x32_bf16 v[12:15], v[228:231], v[188:191], v[12:15]
	v_mfma_f32_16x16x32_bf16 v[4:7], v[224:227], v[192:195], v[4:7]
	v_mfma_f32_16x16x32_bf16 v[4:7], v[228:231], v[212:215], v[4:7]
	s_add_i32 s38, s38, 2
	s_add_u32 s36, s36, 0x100
	s_addc_u32 s37, s37, 0
	s_add_u32 s14, s14, 0x100
	s_addc_u32 s15, s15, 0
	s_cmp_gt_u32 s38, 29
	s_barrier
;   __device__ __forceinline__ void operator()(EPI_ARGS) const {
;     const size_t row0 = (size_t)u.pm * 256 + wr * 64 + fr;
;     const int col0 = u.pn * 256 + wc * 32 + 8 * fq;
; #pragma unroll
;     for (int ai = 0; ai < 2; ++ai)
; #pragma unroll
;       for (int bj = 0; bj < 2; ++bj) {
;         f32x4 x0[4], x1[4];
; #pragma unroll
;         for (int m = 0; m < 4; ++m) {
;           const size_t o = (row0 + ai * HALF + m * 16) * DM + col0 + bj * HALF;
;           x0[m] = *(const f32x4*)(xres + o);
;           x1[m] = *(const f32x4*)(xres + o + 4);
;         }
;         __builtin_amdgcn_sched_barrier(0);
; #pragma unroll
;         for (int m = 0; m < 4; ++m) {
;           const size_t o = (row0 + ai * HALF + m * 16) * DM + col0 + bj * HALF;
;           *(f32x4*)(hbuf + o) = acc[ai][bj][m][0] + x0[m] * ALPHA;
;           *(f32x4*)(hbuf + o + 4) = acc[ai][bj][m][1] + x1[m] * ALPHA;
;         }
;       }
	s_setprio 0
	s_cbranch_scc0 .LBB0_619
	s_ashr_i32 s13, s12, 31
	v_lshl_or_b32 v142, s34, 8, v145
	v_ashrrev_i32_e32 v143, 31, v142
	s_lshl_b64 s[12:13], s[12:13], 21
	v_lshlrev_b64 v[184:185], 2, v[142:143]
	v_lshl_add_u64 v[188:189], s[12:13], 0, v[136:137]
	v_lshl_add_u64 v[186:187], s[0:1], 0, v[184:185]
	v_or_b32_e32 v190, 0x20000, v188
	v_mov_b32_e32 v191, v189
	v_or_b32_e32 v192, 0x40000, v188
	v_mov_b32_e32 v193, v189
	v_or_b32_e32 v194, 0x60000, v188
	v_mov_b32_e32 v195, v189
	v_lshl_add_u64 v[142:143], v[186:187], 0, v[188:189]
	v_lshl_add_u64 v[160:161], v[186:187], 0, v[190:191]
	v_lshl_add_u64 v[172:173], v[186:187], 0, v[192:193]
	v_lshl_add_u64 v[180:181], v[186:187], 0, v[194:195]
	flat_load_dwordx4 v[148:151], v[142:143]
	flat_load_dwordx4 v[152:155], v[142:143] offset:16
	flat_load_dwordx4 v[156:159], v[160:161]
	s_nop 0
	flat_load_dwordx4 v[160:163], v[160:161] offset:16
	s_nop 0
	flat_load_dwordx4 v[168:171], v[172:173]
	s_nop 0
	flat_load_dwordx4 v[172:175], v[172:173] offset:16
	s_nop 0
	flat_load_dwordx4 v[176:179], v[180:181]
	s_nop 0
	flat_load_dwordx4 v[180:183], v[180:181] offset:16
	v_lshl_add_u64 v[184:185], s[48:49], 0, v[184:185]
	s_mov_b32 s14, 0x3fb504f3
	s_waitcnt vmcnt(0) lgkmcnt(0)
	v_pk_fma_f32 v[148:149], v[148:149], s[14:15], v[128:129] op_sel_hi:[1,0,1]
	v_lshl_add_u64 v[128:129], v[184:185], 0, v[188:189]
	v_pk_fma_f32 v[126:127], v[154:155], s[14:15], v[126:127] op_sel_hi:[1,0,1]
	v_pk_fma_f32 v[124:125], v[152:153], s[14:15], v[124:125] op_sel_hi:[1,0,1]
	global_store_dwordx4 v[128:129], v[124:127], off offset:16
	v_pk_fma_f32 v[118:119], v[162:163], s[14:15], v[118:119] op_sel_hi:[1,0,1]
	v_pk_fma_f32 v[116:117], v[160:161], s[14:15], v[116:117] op_sel_hi:[1,0,1]
	v_lshl_add_u64 v[124:125], v[184:185], 0, v[190:191]
	v_pk_fma_f32 v[122:123], v[158:159], s[14:15], v[122:123] op_sel_hi:[1,0,1]
	v_pk_fma_f32 v[120:121], v[156:157], s[14:15], v[120:121] op_sel_hi:[1,0,1]
	global_store_dwordx4 v[124:125], v[116:119], off offset:16
	v_pk_fma_f32 v[110:111], v[174:175], s[14:15], v[110:111] op_sel_hi:[1,0,1]
	v_pk_fma_f32 v[108:109], v[172:173], s[14:15], v[108:109] op_sel_hi:[1,0,1]
	v_lshl_add_u64 v[116:117], v[184:185], 0, v[192:193]
	s_mov_b64 s[12:13], 0x200
	v_pk_fma_f32 v[150:151], v[150:151], s[14:15], v[130:131] op_sel_hi:[1,0,1]
	global_store_dwordx4 v[124:125], v[120:123], off
	v_pk_fma_f32 v[114:115], v[170:171], s[14:15], v[114:115] op_sel_hi:[1,0,1]
	v_pk_fma_f32 v[112:113], v[168:169], s[14:15], v[112:113] op_sel_hi:[1,0,1]
	global_store_dwordx4 v[116:117], v[108:111], off offset:16
	v_pk_fma_f32 v[106:107], v[178:179], s[14:15], v[106:107] op_sel_hi:[1,0,1]
	v_pk_fma_f32 v[104:105], v[176:177], s[14:15], v[104:105] op_sel_hi:[1,0,1]
	v_lshl_add_u64 v[108:109], v[184:185], 0, v[194:195]
	v_pk_fma_f32 v[102:103], v[182:183], s[14:15], v[102:103] op_sel_hi:[1,0,1]
	v_pk_fma_f32 v[100:101], v[180:181], s[14:15], v[100:101] op_sel_hi:[1,0,1]
	v_lshl_add_u64 v[124:125], v[186:187], 0, s[12:13]
	global_store_dwordx4 v[128:129], v[148:151], off
	global_store_dwordx4 v[116:117], v[112:115], off
	global_store_dwordx4 v[108:109], v[104:107], off
	global_store_dwordx4 v[108:109], v[100:103], off offset:16
	v_lshl_add_u64 v[112:113], v[124:125], 0, v[190:191]
	v_lshl_add_u64 v[120:121], v[124:125], 0, v[192:193]
	v_lshl_add_u64 v[130:131], v[124:125], 0, v[194:195]
	flat_load_dwordx4 v[100:103], v[142:143] offset:512
	flat_load_dwordx4 v[104:107], v[142:143] offset:528
	flat_load_dwordx4 v[108:111], v[112:113]
	s_nop 0
	flat_load_dwordx4 v[112:115], v[112:113] offset:16
	s_nop 0
	flat_load_dwordx4 v[116:119], v[120:121]
	s_nop 0
	flat_load_dwordx4 v[120:123], v[120:121] offset:16
	s_nop 0
	flat_load_dwordx4 v[124:127], v[130:131]
	flat_load_dwordx4 v[148:151], v[130:131] offset:16
	s_mov_b32 s3, 0x100000
	s_waitcnt vmcnt(0) lgkmcnt(0)
	v_pk_fma_f32 v[96:97], v[100:101], s[14:15], v[96:97] op_sel_hi:[1,0,1]
	v_add_co_u32_e32 v100, vcc, s3, v142
	s_mov_b32 s5, 0x120000
	s_nop 0
	v_addc_co_u32_e32 v101, vcc, 0, v143, vcc
	v_pk_fma_f32 v[98:99], v[102:103], s[14:15], v[98:99] op_sel_hi:[1,0,1]
	v_add_co_u32_e32 v102, vcc, s5, v142
	v_lshl_add_u64 v[130:131], v[184:185], 0, s[12:13]
	v_pk_fma_f32 v[94:95], v[106:107], s[14:15], v[94:95] op_sel_hi:[1,0,1]
	v_pk_fma_f32 v[92:93], v[104:105], s[14:15], v[92:93] op_sel_hi:[1,0,1]
	v_addc_co_u32_e32 v103, vcc, 0, v143, vcc
	s_mov_b32 s12, 0x140000
	global_store_dwordx4 v[128:129], v[92:95], off offset:528
	v_pk_fma_f32 v[86:87], v[114:115], s[14:15], v[86:87] op_sel_hi:[1,0,1]
	v_pk_fma_f32 v[84:85], v[112:113], s[14:15], v[84:85] op_sel_hi:[1,0,1]
	v_lshl_add_u64 v[92:93], v[130:131], 0, v[190:191]
	v_add_co_u32_e32 v104, vcc, s12, v142
	global_store_dwordx4 v[92:93], v[84:87], off offset:16
	v_pk_fma_f32 v[78:79], v[122:123], s[14:15], v[78:79] op_sel_hi:[1,0,1]
	v_pk_fma_f32 v[76:77], v[120:121], s[14:15], v[76:77] op_sel_hi:[1,0,1]
	v_lshl_add_u64 v[84:85], v[130:131], 0, v[192:193]
	v_addc_co_u32_e32 v105, vcc, 0, v143, vcc
	s_mov_b32 s13, 0x160000
	v_pk_fma_f32 v[90:91], v[110:111], s[14:15], v[90:91] op_sel_hi:[1,0,1]
	v_pk_fma_f32 v[88:89], v[108:109], s[14:15], v[88:89] op_sel_hi:[1,0,1]
	v_pk_fma_f32 v[82:83], v[118:119], s[14:15], v[82:83] op_sel_hi:[1,0,1]
	v_pk_fma_f32 v[80:81], v[116:117], s[14:15], v[80:81] op_sel_hi:[1,0,1]
	global_store_dwordx4 v[84:85], v[76:79], off offset:16
	v_pk_fma_f32 v[74:75], v[126:127], s[14:15], v[74:75] op_sel_hi:[1,0,1]
	v_pk_fma_f32 v[72:73], v[124:125], s[14:15], v[72:73] op_sel_hi:[1,0,1]
	v_lshl_add_u64 v[76:77], v[130:131], 0, v[194:195]
	v_pk_fma_f32 v[70:71], v[150:151], s[14:15], v[70:71] op_sel_hi:[1,0,1]
	v_pk_fma_f32 v[68:69], v[148:149], s[14:15], v[68:69] op_sel_hi:[1,0,1]
	s_mov_b64 s[16:17], 0x100000
	s_mov_b64 s[18:19], 0x120000
	s_mov_b64 s[34:35], 0x140000
	s_mov_b64 s[36:37], 0x160000
	v_add_co_u32_e32 v106, vcc, s13, v142
	global_store_dwordx4 v[128:129], v[96:99], off offset:512
	global_store_dwordx4 v[92:93], v[88:91], off
	global_store_dwordx4 v[84:85], v[80:83], off
	global_store_dwordx4 v[76:77], v[72:75], off
	global_store_dwordx4 v[76:77], v[68:71], off offset:16
	v_lshl_add_u64 v[80:81], v[142:143], 0, s[18:19]
	v_lshl_add_u64 v[72:73], v[142:143], 0, s[16:17]
	v_lshl_add_u64 v[88:89], v[142:143], 0, s[34:35]
	v_lshl_add_u64 v[96:97], v[142:143], 0, s[36:37]
	v_addc_co_u32_e32 v107, vcc, 0, v143, vcc
	flat_load_dwordx4 v[68:71], v[100:101]
	s_nop 0
	flat_load_dwordx4 v[72:75], v[72:73] offset:16
	s_nop 0
	flat_load_dwordx4 v[76:79], v[102:103]
	s_nop 0
	flat_load_dwordx4 v[80:83], v[80:81] offset:16
	s_nop 0
	flat_load_dwordx4 v[84:87], v[104:105]
	s_nop 0
	flat_load_dwordx4 v[88:91], v[88:89] offset:16
	s_nop 0
	flat_load_dwordx4 v[92:95], v[106:107]
	s_nop 0
	flat_load_dwordx4 v[96:99], v[96:97] offset:16
	s_waitcnt vmcnt(0) lgkmcnt(0)
; #define PG8_WAIT_V(n) asm volatile("s_waitcnt vmcnt(" #n ")" ::: "memory")
; #define PG8_BAR __builtin_amdgcn_s_barrier()
; template <class Epi, class AddrA, class AddrB>
; __device__ __forceinline__ void gemm_phase(const Sched S, const int lda, const int ldb, const int K, const AddrA addrA,
;                                            const AddrB addrB, const Epi E) {
;     ...
;     cur = nxt; cA = nA; cB = nB; ++ui;
;   }
;   PG8_WAIT_V(0);
;   if (wr == 0) PG8_BAR;
;   PG8_BAR;
;   __device__ __forceinline__ void operator()(EPI_ARGS) const {
;     ...
;     for (int ai = 0; ai < 2; ++ai)
; #pragma unroll
;       for (int bj = 0; bj < 2; ++bj) {
;         f32x4 x0[4], x1[4];
; #pragma unroll
;         for (int m = 0; m < 4; ++m) {
;           const size_t o = (row0 + ai * HALF + m * 16) * DM + col0 + bj * HALF;
;           x0[m] = *(const f32x4*)(xres + o);
;           x1[m] = *(const f32x4*)(xres + o + 4);
;         }
;         __builtin_amdgcn_sched_barrier(0);
; #pragma unroll
;         for (int m = 0; m < 4; ++m) {
;           const size_t o = (row0 + ai * HALF + m * 16) * DM + col0 + bj * HALF;
;           *(f32x4*)(hbuf + o) = acc[ai][bj][m][0] + x0[m] * ALPHA;
;           *(f32x4*)(hbuf + o + 4) = acc[ai][bj][m][1] + x1[m] * ALPHA;
;         }
;       }
	v_pk_fma_f32 v[66:67], v[70:71], s[14:15], v[66:67] op_sel_hi:[1,0,1]
	v_add_co_u32_e32 v70, vcc, s3, v128
	v_pk_fma_f32 v[64:65], v[68:69], s[14:15], v[64:65] op_sel_hi:[1,0,1]
	v_lshl_add_u64 v[68:69], v[128:129], 0, s[16:17]
	v_addc_co_u32_e32 v71, vcc, 0, v129, vcc
	v_pk_fma_f32 v[62:63], v[74:75], s[14:15], v[62:63] op_sel_hi:[1,0,1]
	v_pk_fma_f32 v[60:61], v[72:73], s[14:15], v[60:61] op_sel_hi:[1,0,1]
	global_store_dwordx4 v[68:69], v[60:63], off offset:16
	v_add_co_u32_e32 v68, vcc, s5, v128
	s_nop 0
	v_lshl_add_u64 v[60:61], v[128:129], 0, s[18:19]
	v_addc_co_u32_e32 v69, vcc, 0, v129, vcc
	v_add_co_u32_e32 v72, vcc, s12, v128
	v_pk_fma_f32 v[54:55], v[82:83], s[14:15], v[54:55] op_sel_hi:[1,0,1]
	v_pk_fma_f32 v[52:53], v[80:81], s[14:15], v[52:53] op_sel_hi:[1,0,1]
	v_addc_co_u32_e32 v73, vcc, 0, v129, vcc
	global_store_dwordx4 v[60:61], v[52:55], off offset:16
	v_pk_fma_f32 v[46:47], v[90:91], s[14:15], v[46:47] op_sel_hi:[1,0,1]
	v_pk_fma_f32 v[44:45], v[88:89], s[14:15], v[44:45] op_sel_hi:[1,0,1]
	v_lshl_add_u64 v[52:53], v[128:129], 0, s[34:35]
	v_add_co_u32_e32 v74, vcc, s13, v128
	v_pk_fma_f32 v[58:59], v[78:79], s[14:15], v[58:59] op_sel_hi:[1,0,1]
	v_pk_fma_f32 v[56:57], v[76:77], s[14:15], v[56:57] op_sel_hi:[1,0,1]
	v_pk_fma_f32 v[50:51], v[86:87], s[14:15], v[50:51] op_sel_hi:[1,0,1]
	v_pk_fma_f32 v[48:49], v[84:85], s[14:15], v[48:49] op_sel_hi:[1,0,1]
	global_store_dwordx4 v[52:53], v[44:47], off offset:16
	v_pk_fma_f32 v[42:43], v[94:95], s[14:15], v[42:43] op_sel_hi:[1,0,1]
	v_pk_fma_f32 v[40:41], v[92:93], s[14:15], v[40:41] op_sel_hi:[1,0,1]
	v_lshl_add_u64 v[44:45], v[128:129], 0, s[36:37]
	v_addc_co_u32_e32 v75, vcc, 0, v129, vcc
	v_pk_fma_f32 v[38:39], v[98:99], s[14:15], v[38:39] op_sel_hi:[1,0,1]
	v_pk_fma_f32 v[36:37], v[96:97], s[14:15], v[36:37] op_sel_hi:[1,0,1]
	s_mov_b64 s[12:13], 0x100200
	s_mov_b64 s[16:17], 0x120200
	s_mov_b64 s[18:19], 0x140200
	s_mov_b64 s[34:35], 0x160200
	global_store_dwordx4 v[70:71], v[64:67], off
	global_store_dwordx4 v[68:69], v[56:59], off
	global_store_dwordx4 v[72:73], v[48:51], off
	global_store_dwordx4 v[74:75], v[40:43], off
	global_store_dwordx4 v[44:45], v[36:39], off offset:16
	v_lshl_add_u64 v[44:45], v[142:143], 0, s[12:13]
	v_lshl_add_u64 v[48:49], v[142:143], 0, s[16:17]
	v_lshl_add_u64 v[60:61], v[142:143], 0, s[18:19]
	v_lshl_add_u64 v[64:65], v[142:143], 0, s[34:35]
	flat_load_dwordx4 v[36:39], v[100:101] offset:512
	flat_load_dwordx4 v[40:43], v[102:103] offset:512
	s_nop 0
	flat_load_dwordx4 v[44:47], v[44:45] offset:16
	s_nop 0
	flat_load_dwordx4 v[48:51], v[48:49] offset:16
	s_nop 0
	flat_load_dwordx4 v[52:55], v[104:105] offset:512
	flat_load_dwordx4 v[56:59], v[106:107] offset:512
	s_nop 0
	flat_load_dwordx4 v[60:63], v[60:61] offset:16
	s_nop 0
	flat_load_dwordx4 v[64:67], v[64:65] offset:16
	s_waitcnt vmcnt(0) lgkmcnt(0)
	v_pk_fma_f32 v[32:33], v[36:37], s[14:15], v[32:33] op_sel_hi:[1,0,1]
	v_lshl_add_u64 v[36:37], v[128:129], 0, s[12:13]
	v_pk_fma_f32 v[30:31], v[46:47], s[14:15], v[30:31] op_sel_hi:[1,0,1]
	v_pk_fma_f32 v[28:29], v[44:45], s[14:15], v[28:29] op_sel_hi:[1,0,1]
	global_store_dwordx4 v[36:37], v[28:31], off offset:16
	v_pk_fma_f32 v[22:23], v[50:51], s[14:15], v[22:23] op_sel_hi:[1,0,1]
	v_pk_fma_f32 v[20:21], v[48:49], s[14:15], v[20:21] op_sel_hi:[1,0,1]
	v_lshl_add_u64 v[28:29], v[128:129], 0, s[16:17]
	global_store_dwordx4 v[28:29], v[20:23], off offset:16
	v_pk_fma_f32 v[14:15], v[62:63], s[14:15], v[14:15] op_sel_hi:[1,0,1]
	v_pk_fma_f32 v[12:13], v[60:61], s[14:15], v[12:13] op_sel_hi:[1,0,1]
	v_lshl_add_u64 v[20:21], v[128:129], 0, s[18:19]
	v_pk_fma_f32 v[34:35], v[38:39], s[14:15], v[34:35] op_sel_hi:[1,0,1]
	v_pk_fma_f32 v[26:27], v[42:43], s[14:15], v[26:27] op_sel_hi:[1,0,1]
	v_pk_fma_f32 v[24:25], v[40:41], s[14:15], v[24:25] op_sel_hi:[1,0,1]
	v_pk_fma_f32 v[18:19], v[54:55], s[14:15], v[18:19] op_sel_hi:[1,0,1]
	v_pk_fma_f32 v[16:17], v[52:53], s[14:15], v[16:17] op_sel_hi:[1,0,1]
	global_store_dwordx4 v[20:21], v[12:15], off offset:16
	v_pk_fma_f32 v[10:11], v[58:59], s[14:15], v[10:11] op_sel_hi:[1,0,1]
	v_pk_fma_f32 v[8:9], v[56:57], s[14:15], v[8:9] op_sel_hi:[1,0,1]
	v_lshl_add_u64 v[12:13], v[128:129], 0, s[34:35]
	v_pk_fma_f32 v[6:7], v[66:67], s[14:15], v[6:7] op_sel_hi:[1,0,1]
	v_pk_fma_f32 v[4:5], v[64:65], s[14:15], v[4:5] op_sel_hi:[1,0,1]
	s_and_b64 vcc, exec, s[6:7]
	s_mov_b32 s34, s4
	s_mov_b32 s12, s2
	s_mov_b64 s[14:15], s[10:11]
	s_mov_b64 s[16:17], s[8:9]
	global_store_dwordx4 v[70:71], v[32:35], off offset:512
	global_store_dwordx4 v[68:69], v[24:27], off offset:512
	global_store_dwordx4 v[72:73], v[16:19], off offset:512
	global_store_dwordx4 v[74:75], v[8:11], off offset:512
	global_store_dwordx4 v[12:13], v[4:7], off offset:16
	s_cbranch_vccz .LBB0_616
	s_waitcnt vmcnt(0)
	s_cmpk_gt_u32 s20, 0xff
	s_cbranch_scc1 .LBB0_623
	s_barrier
